# ResLN epilogues: half of the second residual batch loaded up front into unused VGPRs, second-half counted waits re-derived
# speedup vs baseline: 1.0091x; 1.0091x over previous
;     __device__ __forceinline__ void operator()(const f32x4 (&acc)[2][2][4][2], const Unit& u, int wr, int wc, int fr, int fq, const EpiCtx& X) const {
;     ...
;         f32x2* ps = PSn + ((size_t)u.pm * BM + wr * 64 + fe) * 64 + u.pn * 4 + wc;
; #pragma unroll
;         for (int ai = 0; ai < 2; ++ai) {
;             u32x4 raw[8];
; #pragma unroll
;             for (int m = 0; m < 4; ++m) { const unsigned off = lo + (unsigned)((ai * HALF + m * 16) * 64) * 2u; raw[2 * m] = *(const u32x4*)(xb + off); raw[2 * m + 1] = *(const u32x4*)(xb + off + 128); }
; #pragma unroll
;             for (int m = 0; m < 4; ++m) {
;                 const int rl = ai * HALF + m * 16; const unsigned off = lo + (unsigned)(rl * 64) * 2u;
;                 const f32x4 o0a = acc[ai][0][m][0], o0b = acc[ai][0][m][1], o1a = acc[ai][1][m][0], o1b = acc[ai][1][m][1];
;                 const f32x4 ra_ = dpp_swap1(odd ? o0a : o1a), rb_ = dpp_swap1(odd ? o0b : o1b);
;                 const f32x4 pa[2] = {odd ? ra_ : o0a, odd ? o1a : ra_}, pb[2] = {odd ? rb_ : o0b, odd ? o1b : rb_};
; #pragma unroll
;                 for (int q = 0; q < 2; ++q) {
;                     const u32x4 w0 = raw[2 * m + q];
;                     const f32x4 r0 = (f32x4){bf_lo(w0.x), bf_hi(w0.x), bf_lo(w0.y), bf_hi(w0.y)}, r1 = (f32x4){bf_lo(w0.z), bf_hi(w0.z), bf_lo(w0.w), bf_hi(w0.w)};
;                     f32x4 y0, y1;
;                     if (RESN) { const f32x2 t = tbl[rl + q]; const float mu = t.x, ra = t.y * ALPHA; y0 = (r0 - mu) * ra * g0 + b0 + pa[q]; y1 = (r1 - mu) * ra * g1 + b1 + pb[q]; }
;                     else { y0 = r0 * ALPHA + pa[q]; y1 = r1 * ALPHA + pb[q]; }
;                     { const u32x4 w = pack8f(y0, y1); *(u32x4*)(xb + off + q * 128) = w;
;                         y0 = (f32x4){bf_lo(w.x), bf_hi(w.x), bf_lo(w.y), bf_hi(w.y)}; y1 = (f32x4){bf_lo(w.z), bf_hi(w.z), bf_lo(w.w), bf_hi(w.w)}; }
;                     float sa = ((y0[0] + y0[1]) + (y0[2] + y0[3])) + ((y1[0] + y1[1]) + (y1[2] + y1[3]));
;                     float sb = ((y0[0] * y0[0] + y0[1] * y0[1]) + (y0[2] * y0[2] + y0[3] * y0[3])) + ((y1[0] * y1[0] + y1[1] * y1[1]) + (y1[2] * y1[2] + y1[3] * y1[3]));
;                     sa += dpp_x1(sa);
;                     sb += dpp_x1(sb);
;                     sa += __shfl_xor(sa, 16); sa += __shfl_xor(sa, 32); sb += __shfl_xor(sb, 16); sb += __shfl_xor(sb, 32);
.LBB0_582:
	s_ashr_i32 s57, s56, 31
	s_lshl_b64 s[52:53], s[56:57], 21
	s_add_u32 s21, s46, s52
	s_addc_u32 s23, s47, s53
	s_lshl_b32 s58, s54, 2
	s_or_b32 s52, s58, s41
	s_ashr_i32 s53, s52, 31
	s_lshl_b64 s[52:53], s[52:53], 15
	s_add_u32 s54, s21, s52
	s_addc_u32 s55, s23, s53
	v_mov_b32_e32 v164, v183
	global_load_dwordx4 v[194:197], v164, s[54:55]
	v_add_u32_e32 v180, 0x800, v164
	v_add_u32_e32 v178, 0x1000, v164
	v_add_u32_e32 v176, 0x1800, v164
	global_load_dwordx4 v[152:155], v164, s[54:55] offset:128
	global_load_dwordx4 v[148:151], v180, s[54:55]
	global_load_dwordx4 v[144:147], v180, s[54:55] offset:128
	global_load_dwordx4 v[140:143], v178, s[54:55]
	global_load_dwordx4 v[136:139], v178, s[54:55] offset:128
	global_load_dwordx4 v[132:135], v176, s[54:55]
	global_load_dwordx4 v[120:123], v176, s[54:55] offset:128
	v_cndmask_b32_e64 v199, v129, v117, s[8:9]
	v_cndmask_b32_e64 v200, v128, v116, s[8:9]
	v_mov_b32_e32 v177, 0
	v_mov_b32_e32 v181, 0
	v_cndmask_b32_e64 v201, v127, v115, s[8:9]
	v_cndmask_b32_e64 v202, v126, v114, s[8:9]
	v_cndmask_b32_e64 v203, v125, v113, s[8:9]
	v_cndmask_b32_e64 v204, v124, v112, s[8:9]
	v_mov_b32_e32 v189, 0
	v_mov_b32_e32 v191, 0
	v_mov_b32_e32 v190, 0
	v_mov_b32_e32 v192, 0
	v_cndmask_b32_e64 v193, v131, v119, s[8:9]
	v_cndmask_b32_e64 v198, v130, v118, s[8:9]
	v_mov_b32_e32 v179, 0
	v_mov_b32_e32 v188, 0
	v_mov_b32_dpp v177, v200 quad_perm:[1,0,3,2] row_mask:0xf bank_mask:0xf
	v_mov_b32_dpp v181, v199 quad_perm:[1,0,3,2] row_mask:0xf bank_mask:0xf
	v_mov_b32_dpp v189, v204 quad_perm:[1,0,3,2] row_mask:0xf bank_mask:0xf
	v_mov_b32_dpp v191, v203 quad_perm:[1,0,3,2] row_mask:0xf bank_mask:0xf
	v_mov_b32_dpp v190, v202 quad_perm:[1,0,3,2] row_mask:0xf bank_mask:0xf
	v_mov_b32_dpp v192, v201 quad_perm:[1,0,3,2] row_mask:0xf bank_mask:0xf
	v_mov_b32_dpp v179, v198 quad_perm:[1,0,3,2] row_mask:0xf bank_mask:0xf
	v_mov_b32_dpp v188, v193 quad_perm:[1,0,3,2] row_mask:0xf bank_mask:0xf
	v_cndmask_b32_e64 v129, v181, v129, s[8:9]
	v_cndmask_b32_e64 v128, v177, v128, s[8:9]
	v_cndmask_b32_e64 v125, v191, v125, s[8:9]
	v_cndmask_b32_e64 v124, v189, v124, s[8:9]
	v_cndmask_b32_e64 v127, v192, v127, s[8:9]
	v_cndmask_b32_e64 v126, v190, v126, s[8:9]
	v_and_b32_e32 v206, 64, v187
	v_cndmask_b32_e64 v131, v188, v131, s[8:9]
	v_cndmask_b32_e64 v130, v179, v130, s[8:9]
	v_xor_b32_e32 v205, 16, v187
	v_add_u32_e32 v193, 64, v206
	v_cmp_lt_i32_e32 vcc, v205, v193
	s_lshl_b64 s[52:53], s[56:57], 17
	v_lshl_add_u64 v[198:199], v[166:167], 0, s[52:53]
	v_cndmask_b32_e32 v210, v187, v205, vcc
	s_ashr_i32 s59, s58, 31
	v_add_u32_e32 v246, 0x4000, v164
	v_add_u32_e32 v247, 0x4800, v164
	global_load_dwordx4 v[230:233], v246, s[54:55]
	global_load_dwordx4 v[234:237], v246, s[54:55] offset:128
	global_load_dwordx4 v[238:241], v247, s[54:55]
	global_load_dwordx4 v[242:245], v247, s[54:55] offset:128
	s_waitcnt vmcnt(0)
	v_lshlrev_b32_e32 v200, 16, v194
	v_and_b32_e32 v201, 0xffff0000, v194
	v_lshlrev_b32_e32 v202, 16, v196
	v_and_b32_e32 v203, 0xffff0000, v196
	v_lshlrev_b32_e32 v196, 16, v197
	v_and_b32_e32 v197, 0xffff0000, v197
	v_lshlrev_b32_e32 v194, 16, v195
	v_and_b32_e32 v195, 0xffff0000, v195
	v_pk_fma_f32 v[128:129], v[200:201], s[18:19], v[128:129] op_sel_hi:[1,0,1]
	v_pk_fma_f32 v[126:127], v[196:197], s[18:19], v[126:127] op_sel_hi:[1,0,1]
	v_pk_fma_f32 v[124:125], v[202:203], s[18:19], v[124:125] op_sel_hi:[1,0,1]
	v_pk_fma_f32 v[130:131], v[194:195], s[18:19], v[130:131] op_sel_hi:[1,0,1]
	v_cvt_pk_bf16_f32 v194, v128, v129
	s_nop 0
	v_cvt_pk_bf16_f32 v195, v130, v131
	v_cvt_pk_bf16_f32 v196, v124, v125
	v_cvt_pk_bf16_f32 v197, v126, v127
	v_lshlrev_b32_e32 v124, 16, v194
	v_and_b32_e32 v126, 0xffff0000, v194
	v_lshlrev_b32_e32 v128, 16, v195
	v_and_b32_e32 v200, 0xffff0000, v195
	v_lshlrev_b32_e32 v202, 16, v196
	v_and_b32_e32 v204, 0xffff0000, v196
	v_lshlrev_b32_e32 v206, 16, v197
	v_and_b32_e32 v208, 0xffff0000, v197
	v_mul_f32_e32 v125, v124, v124
	v_mul_f32_e32 v127, v126, v126
	v_mul_f32_e32 v129, v128, v128
	v_mul_f32_e32 v201, v200, v200
	v_mul_f32_e32 v203, v202, v202
	v_mul_f32_e32 v205, v204, v204
	v_mul_f32_e32 v207, v206, v206
	v_mul_f32_e32 v209, v208, v208
	v_pk_add_f32 v[124:125], v[124:125], v[126:127]
	v_pk_add_f32 v[126:127], v[128:129], v[200:201]
	v_pk_add_f32 v[128:129], v[206:207], v[208:209]
	v_pk_add_f32 v[124:125], v[124:125], v[126:127]
	v_pk_add_f32 v[126:127], v[202:203], v[204:205]
	v_lshlrev_b32_e32 v130, 2, v210
	v_pk_add_f32 v[126:127], v[126:127], v[128:129]
	v_xor_b32_e32 v128, 32, v187
	v_pk_add_f32 v[124:125], v[124:125], v[126:127]
	v_mov_b32_e32 v126, 0
	v_mov_b32_e32 v127, 0
	v_cmp_lt_i32_e32 vcc, v128, v193
	v_mov_b32_dpp v126, v124 quad_perm:[1,0,3,2] row_mask:0xf bank_mask:0xf
	v_mov_b32_dpp v127, v125 quad_perm:[1,0,3,2] row_mask:0xf bank_mask:0xf
	v_pk_add_f32 v[124:125], v[124:125], v[126:127]
	ds_bpermute_b32 v126, v130, v124
	ds_bpermute_b32 v127, v130, v125
	v_cndmask_b32_e32 v128, v187, v128, vcc
	v_lshlrev_b32_e32 v131, 2, v128
	global_store_dwordx4 v164, v[194:197], s[54:55]
	s_waitcnt lgkmcnt(0)
	v_pk_add_f32 v[126:127], v[124:125], v[126:127]
	ds_bpermute_b32 v128, v131, v126
	ds_bpermute_b32 v129, v131, v127
	v_lshl_add_u64 v[124:125], s[58:59], 3, v[198:199]
	v_lshl_add_u64 v[124:125], v[124:125], 0, s[14:15]
	s_and_saveexec_b64 s[52:53], s[10:11]
	s_cbranch_execz .LBB0_584
	s_waitcnt lgkmcnt(0)
	v_pk_add_f32 v[126:127], v[126:127], v[128:129]
	global_store_dwordx2 v[124:125], v[126:127], off

;     __device__ __forceinline__ void operator()(const f32x4 (&acc)[2][2][4][2], const Unit& u, int wr, int wc, int fr, int fq, const EpiCtx& X) const {
;     ...
;             for (int m = 0; m < 4; ++m) { const unsigned off = lo + (unsigned)((ai * HALF + m * 16) * 64) * 2u; raw[2 * m] = *(const u32x4*)(xb + off); raw[2 * m + 1] = *(const u32x4*)(xb + off + 128); }
; #pragma unroll
;             for (int m = 0; m < 4; ++m) {
;                 const int rl = ai * HALF + m * 16; const unsigned off = lo + (unsigned)(rl * 64) * 2u;
;                 const f32x4 o0a = acc[ai][0][m][0], o0b = acc[ai][0][m][1], o1a = acc[ai][1][m][0], o1b = acc[ai][1][m][1];
;                 const f32x4 ra_ = dpp_swap1(odd ? o0a : o1a), rb_ = dpp_swap1(odd ? o0b : o1b);
;                 const f32x4 pa[2] = {odd ? ra_ : o0a, odd ? o1a : ra_}, pb[2] = {odd ? rb_ : o0b, odd ? o1b : rb_};
; #pragma unroll
;                 for (int q = 0; q < 2; ++q) {
;                     const u32x4 w0 = raw[2 * m + q];
;                     const f32x4 r0 = (f32x4){bf_lo(w0.x), bf_hi(w0.x), bf_lo(w0.y), bf_hi(w0.y)}, r1 = (f32x4){bf_lo(w0.z), bf_hi(w0.z), bf_lo(w0.w), bf_hi(w0.w)};
;                     f32x4 y0, y1;
;                     if (RESN) { const f32x2 t = tbl[rl + q]; const float mu = t.x, ra = t.y * ALPHA; y0 = (r0 - mu) * ra * g0 + b0 + pa[q]; y1 = (r1 - mu) * ra * g1 + b1 + pb[q]; }
;                     else { y0 = r0 * ALPHA + pa[q]; y1 = r1 * ALPHA + pb[q]; }
;                     { const u32x4 w = pack8f(y0, y1); *(u32x4*)(xb + off + q * 128) = w;
;                         y0 = (f32x4){bf_lo(w.x), bf_hi(w.x), bf_lo(w.y), bf_hi(w.y)}; y1 = (f32x4){bf_lo(w.z), bf_hi(w.z), bf_lo(w.w), bf_hi(w.w)}; }
;                     float sa = ((y0[0] + y0[1]) + (y0[2] + y0[3])) + ((y1[0] + y1[1]) + (y1[2] + y1[3]));
;                     float sb = ((y0[0] * y0[0] + y0[1] * y0[1]) + (y0[2] * y0[2] + y0[3] * y0[3])) + ((y1[0] * y1[0] + y1[1] * y1[1]) + (y1[2] * y1[2] + y1[3] * y1[3]));
;                     sa += dpp_x1(sa);
;                     sb += dpp_x1(sb);
;                     sa += __shfl_xor(sa, 16); sa += __shfl_xor(sa, 32); sb += __shfl_xor(sb, 16); sb += __shfl_xor(sb, 32);
;                     if (fq == 0 && !odd) ps[(size_t)(rl + q) * 64] = (f32x2){sa, sb};
.LBB0_598:
	s_or_b64 exec, exec, s[56:57]
	v_add_u32_e32 v96, 0x4000, v164
	v_mov_b32_e32 v104, v230
	v_mov_b32_e32 v105, v231
	v_mov_b32_e32 v106, v232
	v_mov_b32_e32 v107, v233
	v_add_u32_e32 v94, 0x4800, v164
	v_add_u32_e32 v92, 0x5000, v164
	v_add_u32_e32 v164, 0x5800, v164
	v_mov_b32_e32 v88, v234
	v_mov_b32_e32 v89, v235
	v_mov_b32_e32 v90, v236
	v_mov_b32_e32 v91, v237
	v_mov_b32_e32 v84, v238
	v_mov_b32_e32 v85, v239
	v_mov_b32_e32 v86, v240
	v_mov_b32_e32 v87, v241
	v_mov_b32_e32 v80, v242
	v_mov_b32_e32 v81, v243
	v_mov_b32_e32 v82, v244
	v_mov_b32_e32 v83, v245
	global_load_dwordx4 v[76:79], v92, s[54:55]
	global_load_dwordx4 v[72:75], v92, s[54:55] offset:128
	global_load_dwordx4 v[68:71], v164, s[54:55]
	s_waitcnt lgkmcnt(0)
	global_load_dwordx4 v[64:67], v164, s[54:55] offset:128
	v_cndmask_b32_e64 v103, v63, v55, s[8:9]
	v_cndmask_b32_e64 v110, v62, v54, s[8:9]
	v_cndmask_b32_e64 v111, v61, v53, s[8:9]
	v_cndmask_b32_e64 v112, v60, v52, s[8:9]
	v_mov_b32_e32 v93, 0
	v_mov_b32_e32 v97, 0
	v_mov_b32_e32 v95, 0
	v_mov_b32_e32 v98, 0
	v_cndmask_b32_e64 v113, v59, v51, s[8:9]
	v_cndmask_b32_e64 v114, v58, v50, s[8:9]
	v_cndmask_b32_e64 v115, v57, v49, s[8:9]
	v_cndmask_b32_e64 v116, v56, v48, s[8:9]
	v_mov_b32_e32 v99, 0
	v_mov_b32_e32 v101, 0
	v_mov_b32_e32 v100, 0
	v_mov_b32_e32 v102, 0
	v_mov_b32_dpp v93, v112 quad_perm:[1,0,3,2] row_mask:0xf bank_mask:0xf
	v_mov_b32_dpp v97, v111 quad_perm:[1,0,3,2] row_mask:0xf bank_mask:0xf
	v_mov_b32_dpp v95, v110 quad_perm:[1,0,3,2] row_mask:0xf bank_mask:0xf
	v_mov_b32_dpp v98, v103 quad_perm:[1,0,3,2] row_mask:0xf bank_mask:0xf
	v_mov_b32_dpp v99, v116 quad_perm:[1,0,3,2] row_mask:0xf bank_mask:0xf
	v_mov_b32_dpp v101, v115 quad_perm:[1,0,3,2] row_mask:0xf bank_mask:0xf
	v_mov_b32_dpp v100, v114 quad_perm:[1,0,3,2] row_mask:0xf bank_mask:0xf
	v_mov_b32_dpp v102, v113 quad_perm:[1,0,3,2] row_mask:0xf bank_mask:0xf
	v_cndmask_b32_e64 v61, v97, v61, s[8:9]
	v_cndmask_b32_e64 v60, v93, v60, s[8:9]
	v_cndmask_b32_e64 v63, v98, v63, s[8:9]
	v_cndmask_b32_e64 v62, v95, v62, s[8:9]
	v_cndmask_b32_e64 v57, v101, v57, s[8:9]
	v_cndmask_b32_e64 v56, v99, v56, s[8:9]
	v_cndmask_b32_e64 v59, v102, v59, s[8:9]
	v_cndmask_b32_e64 v58, v100, v58, s[8:9]
	v_mov_b32_e32 v108, v165
	v_mov_b32_e32 v109, v165
	v_lshlrev_b32_e32 v110, 16, v104
	v_and_b32_e32 v111, 0xffff0000, v104
	v_lshlrev_b32_e32 v104, 16, v105
	v_and_b32_e32 v105, 0xffff0000, v105
	v_lshlrev_b32_e32 v112, 16, v106
	v_and_b32_e32 v113, 0xffff0000, v106
	v_lshlrev_b32_e32 v106, 16, v107
	v_and_b32_e32 v107, 0xffff0000, v107
	v_pk_fma_f32 v[62:63], v[104:105], s[18:19], v[62:63] op_sel_hi:[1,0,1]
	v_pk_fma_f32 v[60:61], v[110:111], s[18:19], v[60:61] op_sel_hi:[1,0,1]
	v_pk_fma_f32 v[58:59], v[106:107], s[18:19], v[58:59] op_sel_hi:[1,0,1]
	v_pk_fma_f32 v[56:57], v[112:113], s[18:19], v[56:57] op_sel_hi:[1,0,1]
	v_cvt_pk_bf16_f32 v60, v60, v61
	v_cvt_pk_bf16_f32 v61, v62, v63
	s_nop 0
	v_cvt_pk_bf16_f32 v62, v56, v57
	v_cvt_pk_bf16_f32 v63, v58, v59
	v_lshlrev_b32_e32 v56, 16, v60
	v_and_b32_e32 v58, 0xffff0000, v60
	v_lshlrev_b32_e32 v104, 16, v61
	v_and_b32_e32 v106, 0xffff0000, v61
	v_lshlrev_b32_e32 v110, 16, v62
	v_and_b32_e32 v112, 0xffff0000, v62
	v_lshlrev_b32_e32 v114, 16, v63
	v_and_b32_e32 v116, 0xffff0000, v63
	v_mul_f32_e32 v57, v56, v56
	v_mul_f32_e32 v59, v58, v58
	v_mul_f32_e32 v105, v104, v104
	v_mul_f32_e32 v107, v106, v106
	v_mul_f32_e32 v111, v110, v110
	v_mul_f32_e32 v113, v112, v112
	v_mul_f32_e32 v115, v114, v114
	v_mul_f32_e32 v117, v116, v116
	v_pk_add_f32 v[56:57], v[56:57], v[58:59]
	v_pk_add_f32 v[58:59], v[104:105], v[106:107]
	v_pk_add_f32 v[104:105], v[110:111], v[112:113]
	v_pk_add_f32 v[106:107], v[114:115], v[116:117]
	v_pk_add_f32 v[56:57], v[56:57], v[58:59]
	v_pk_add_f32 v[58:59], v[104:105], v[106:107]
	global_store_dwordx4 v96, v[60:63], s[54:55]
	v_pk_add_f32 v[56:57], v[56:57], v[58:59]
	s_nop 1
	v_mov_b32_dpp v108, v56 quad_perm:[1,0,3,2] row_mask:0xf bank_mask:0xf
	v_mov_b32_dpp v109, v57 quad_perm:[1,0,3,2] row_mask:0xf bank_mask:0xf
	v_pk_add_f32 v[56:57], v[56:57], v[108:109]
	ds_bpermute_b32 v58, v130, v56
	ds_bpermute_b32 v59, v130, v57
	s_waitcnt lgkmcnt(0)
	v_pk_add_f32 v[56:57], v[56:57], v[58:59]
	ds_bpermute_b32 v58, v131, v56
	ds_bpermute_b32 v59, v131, v57
	s_and_saveexec_b64 s[56:57], s[10:11]
	s_cbranch_execz .LBB0_600
	s_waitcnt lgkmcnt(0)
	v_pk_add_f32 v[56:57], v[56:57], v[58:59]
	v_add_co_u32_e32 v58, vcc, 0x10000, v124
	s_nop 1
	v_addc_co_u32_e32 v59, vcc, 0, v125, vcc
	global_store_dwordx2 v[58:59], v[56:57], off
; __device__ __forceinline__ u32x4 pack8f(f32x4 a, f32x4 b) { u32x4 w; w.x = cvt_pk_bf16(a[0], a[1]); w.y = cvt_pk_bf16(a[2], a[3]); w.z = cvt_pk_bf16(b[0], b[1]); w.w = cvt_pk_bf16(b[2], b[3]); return w; }
;     __device__ __forceinline__ void operator()(const f32x4 (&acc)[2][2][4][2], const Unit& u, int wr, int wc, int fr, int fq, const EpiCtx& X) const {
;     ...
;             for (int m = 0; m < 4; ++m) {
;                 const int rl = ai * HALF + m * 16; const unsigned off = lo + (unsigned)(rl * 64) * 2u;
;                 const f32x4 o0a = acc[ai][0][m][0], o0b = acc[ai][0][m][1], o1a = acc[ai][1][m][0], o1b = acc[ai][1][m][1];
;                 const f32x4 ra_ = dpp_swap1(odd ? o0a : o1a), rb_ = dpp_swap1(odd ? o0b : o1b);
;                 const f32x4 pa[2] = {odd ? ra_ : o0a, odd ? o1a : ra_}, pb[2] = {odd ? rb_ : o0b, odd ? o1b : rb_};
; #pragma unroll
;                 for (int q = 0; q < 2; ++q) {
;                     const u32x4 w0 = raw[2 * m + q];
;                     const f32x4 r0 = (f32x4){bf_lo(w0.x), bf_hi(w0.x), bf_lo(w0.y), bf_hi(w0.y)}, r1 = (f32x4){bf_lo(w0.z), bf_hi(w0.z), bf_lo(w0.w), bf_hi(w0.w)};
;                     f32x4 y0, y1;
;                     if (RESN) { const f32x2 t = tbl[rl + q]; const float mu = t.x, ra = t.y * ALPHA; y0 = (r0 - mu) * ra * g0 + b0 + pa[q]; y1 = (r1 - mu) * ra * g1 + b1 + pb[q]; }
;                     else { y0 = r0 * ALPHA + pa[q]; y1 = r1 * ALPHA + pb[q]; }
;                     { const u32x4 w = pack8f(y0, y1); *(u32x4*)(xb + off + q * 128) = w;
;                         y0 = (f32x4){bf_lo(w.x), bf_hi(w.x), bf_lo(w.y), bf_hi(w.y)}; y1 = (f32x4){bf_lo(w.z), bf_hi(w.z), bf_lo(w.w), bf_hi(w.w)}; }
;                     float sa = ((y0[0] + y0[1]) + (y0[2] + y0[3])) + ((y1[0] + y1[1]) + (y1[2] + y1[3]));
;                     float sb = ((y0[0] * y0[0] + y0[1] * y0[1]) + (y0[2] * y0[2] + y0[3] * y0[3])) + ((y1[0] * y1[0] + y1[1] * y1[1]) + (y1[2] * y1[2] + y1[3] * y1[3]));
;                     sa += dpp_x1(sa);
;                     sb += dpp_x1(sb);
;                     sa += __shfl_xor(sa, 16); sa += __shfl_xor(sa, 32); sb += __shfl_xor(sb, 16); sb += __shfl_xor(sb, 32);
;                     if (fq == 0 && !odd) ps[(size_t)(rl + q) * 64] = (f32x2){sa, sb};
.LBB0_600:
	s_or_b64 exec, exec, s[56:57]
	v_cndmask_b32_e64 v53, v53, v97, s[8:9]
	v_cndmask_b32_e64 v52, v52, v93, s[8:9]
	v_cndmask_b32_e64 v55, v55, v98, s[8:9]
	v_cndmask_b32_e64 v54, v54, v95, s[8:9]
	v_cndmask_b32_e64 v49, v49, v101, s[8:9]
	v_cndmask_b32_e64 v48, v48, v99, s[8:9]
	v_cndmask_b32_e64 v51, v51, v102, s[8:9]
	v_cndmask_b32_e64 v50, v50, v100, s[8:9]
	v_lshlrev_b32_e32 v56, 16, v88
	v_and_b32_e32 v57, 0xffff0000, v88
	s_waitcnt lgkmcnt(1)
	v_lshlrev_b32_e32 v58, 16, v89
	s_waitcnt lgkmcnt(0)
	v_and_b32_e32 v59, 0xffff0000, v89
	v_lshlrev_b32_e32 v60, 16, v90
	v_and_b32_e32 v61, 0xffff0000, v90
	v_lshlrev_b32_e32 v62, 16, v91
	v_and_b32_e32 v63, 0xffff0000, v91
	v_pk_fma_f32 v[54:55], v[58:59], s[18:19], v[54:55] op_sel_hi:[1,0,1]
	v_pk_fma_f32 v[52:53], v[56:57], s[18:19], v[52:53] op_sel_hi:[1,0,1]
	v_pk_fma_f32 v[50:51], v[62:63], s[18:19], v[50:51] op_sel_hi:[1,0,1]
	v_pk_fma_f32 v[48:49], v[60:61], s[18:19], v[48:49] op_sel_hi:[1,0,1]
	v_cvt_pk_bf16_f32 v52, v52, v53
	v_cvt_pk_bf16_f32 v53, v54, v55
	v_mov_b32_e32 v97, v165
	v_cvt_pk_bf16_f32 v54, v48, v49
	v_cvt_pk_bf16_f32 v55, v50, v51
	v_lshlrev_b32_e32 v48, 16, v52
	v_and_b32_e32 v50, 0xffff0000, v52
	v_lshlrev_b32_e32 v56, 16, v53
	v_and_b32_e32 v58, 0xffff0000, v53
	v_lshlrev_b32_e32 v60, 16, v54
	v_and_b32_e32 v62, 0xffff0000, v54
	v_lshlrev_b32_e32 v88, 16, v55
	v_and_b32_e32 v90, 0xffff0000, v55
	v_mul_f32_e32 v49, v48, v48
	v_mul_f32_e32 v51, v50, v50
	v_mul_f32_e32 v57, v56, v56
	v_mul_f32_e32 v59, v58, v58
	v_mul_f32_e32 v61, v60, v60
	v_mul_f32_e32 v63, v62, v62
	v_mul_f32_e32 v89, v88, v88
	v_mul_f32_e32 v91, v90, v90
	v_pk_add_f32 v[48:49], v[48:49], v[50:51]
	v_pk_add_f32 v[50:51], v[56:57], v[58:59]
	v_pk_add_f32 v[56:57], v[88:89], v[90:91]
	v_pk_add_f32 v[48:49], v[48:49], v[50:51]
	v_pk_add_f32 v[50:51], v[60:61], v[62:63]
	s_nop 0
	v_pk_add_f32 v[50:51], v[50:51], v[56:57]
	v_lshl_add_u64 v[56:57], s[54:55], 0, v[96:97]
	v_pk_add_f32 v[48:49], v[48:49], v[50:51]
	v_mov_b32_e32 v50, v165
	v_mov_b32_e32 v51, v165
	global_store_dwordx4 v[56:57], v[52:55], off offset:128
	v_mov_b32_dpp v50, v48 quad_perm:[1,0,3,2] row_mask:0xf bank_mask:0xf
	v_mov_b32_dpp v51, v49 quad_perm:[1,0,3,2] row_mask:0xf bank_mask:0xf
	v_pk_add_f32 v[48:49], v[48:49], v[50:51]
	ds_bpermute_b32 v50, v130, v48
	ds_bpermute_b32 v51, v130, v49
	s_waitcnt lgkmcnt(0)
	v_pk_add_f32 v[48:49], v[48:49], v[50:51]
	ds_bpermute_b32 v50, v131, v48
	ds_bpermute_b32 v51, v131, v49
	s_and_saveexec_b64 s[56:57], s[10:11]
	s_cbranch_execz .LBB0_602
	s_waitcnt lgkmcnt(0)
	v_pk_add_f32 v[48:49], v[48:49], v[50:51]
	v_add_co_u32_e32 v50, vcc, 0x10000, v124
	s_nop 1
	v_addc_co_u32_e32 v51, vcc, 0, v125, vcc
	global_store_dwordx2 v[50:51], v[48:49], off offset:512
.LBB0_602:
	s_or_b64 exec, exec, s[56:57]
	s_waitcnt lgkmcnt(1)
	v_cndmask_b32_e64 v50, v44, v36, s[8:9]
	v_mov_b32_e32 v48, 0
	v_cndmask_b32_e64 v49, v45, v37, s[8:9]
	s_waitcnt lgkmcnt(0)
	v_cndmask_b32_e64 v51, v46, v38, s[8:9]
	v_mov_b32_dpp v48, v50 quad_perm:[1,0,3,2] row_mask:0xf bank_mask:0xf
	v_mov_b32_e32 v50, 0
	v_cndmask_b32_e64 v52, v47, v39, s[8:9]
	v_cndmask_b32_e64 v54, v40, v32, s[8:9]
	v_mov_b32_dpp v50, v49 quad_perm:[1,0,3,2] row_mask:0xf bank_mask:0xf
	v_mov_b32_e32 v49, 0
	v_cndmask_b32_e64 v53, v41, v33, s[8:9]
	v_cndmask_b32_e64 v55, v42, v34, s[8:9]
	v_mov_b32_dpp v49, v51 quad_perm:[1,0,3,2] row_mask:0xf bank_mask:0xf
	v_mov_b32_e32 v51, 0
	v_cndmask_b32_e64 v56, v43, v35, s[8:9]
	v_cndmask_b32_e64 v45, v50, v45, s[8:9]
	v_mov_b32_dpp v51, v52 quad_perm:[1,0,3,2] row_mask:0xf bank_mask:0xf
	v_mov_b32_e32 v52, 0
	v_cndmask_b32_e64 v44, v48, v44, s[8:9]
	v_cndmask_b32_e64 v47, v51, v47, s[8:9]
	v_mov_b32_dpp v52, v54 quad_perm:[1,0,3,2] row_mask:0xf bank_mask:0xf
	v_mov_b32_e32 v54, 0
	v_cndmask_b32_e64 v46, v49, v46, s[8:9]
	v_cndmask_b32_e64 v40, v52, v40, s[8:9]
	v_mov_b32_dpp v54, v53 quad_perm:[1,0,3,2] row_mask:0xf bank_mask:0xf
	v_mov_b32_e32 v53, 0
	v_cndmask_b32_e64 v41, v54, v41, s[8:9]
	v_and_b32_e32 v57, 0xffff0000, v84
	v_mov_b32_dpp v53, v55 quad_perm:[1,0,3,2] row_mask:0xf bank_mask:0xf
	v_mov_b32_e32 v55, 0
	v_cndmask_b32_e64 v42, v53, v42, s[8:9]
	v_lshlrev_b32_e32 v58, 16, v85
	v_mov_b32_dpp v55, v56 quad_perm:[1,0,3,2] row_mask:0xf bank_mask:0xf
	v_cndmask_b32_e64 v43, v55, v43, s[8:9]
	v_lshlrev_b32_e32 v56, 16, v84
	v_and_b32_e32 v59, 0xffff0000, v85
	v_lshlrev_b32_e32 v60, 16, v86
	v_and_b32_e32 v61, 0xffff0000, v86
	v_lshlrev_b32_e32 v62, 16, v87
	v_and_b32_e32 v63, 0xffff0000, v87
	v_pk_fma_f32 v[46:47], v[58:59], s[18:19], v[46:47] op_sel_hi:[1,0,1]
	v_pk_fma_f32 v[44:45], v[56:57], s[18:19], v[44:45] op_sel_hi:[1,0,1]
	v_pk_fma_f32 v[42:43], v[62:63], s[18:19], v[42:43] op_sel_hi:[1,0,1]
	v_pk_fma_f32 v[40:41], v[60:61], s[18:19], v[40:41] op_sel_hi:[1,0,1]
	v_cvt_pk_bf16_f32 v56, v44, v45
	v_cvt_pk_bf16_f32 v57, v46, v47
	v_mov_b32_e32 v95, v165
	v_cvt_pk_bf16_f32 v58, v40, v41
	v_cvt_pk_bf16_f32 v59, v42, v43
	v_lshlrev_b32_e32 v40, 16, v56
	v_and_b32_e32 v42, 0xffff0000, v56
	v_lshlrev_b32_e32 v44, 16, v57
	v_and_b32_e32 v46, 0xffff0000, v57
	v_lshlrev_b32_e32 v60, 16, v58
	v_and_b32_e32 v62, 0xffff0000, v58
	v_lshlrev_b32_e32 v84, 16, v59
	v_and_b32_e32 v86, 0xffff0000, v59
	v_mul_f32_e32 v41, v40, v40
	v_mul_f32_e32 v43, v42, v42
	v_mul_f32_e32 v45, v44, v44
	v_mul_f32_e32 v47, v46, v46
	v_mul_f32_e32 v61, v60, v60
	v_mul_f32_e32 v63, v62, v62
	v_mul_f32_e32 v85, v84, v84
	v_mul_f32_e32 v87, v86, v86
	v_pk_add_f32 v[40:41], v[40:41], v[42:43]
	v_pk_add_f32 v[42:43], v[44:45], v[46:47]
	v_pk_add_f32 v[44:45], v[84:85], v[86:87]
	v_pk_add_f32 v[40:41], v[40:41], v[42:43]
	v_pk_add_f32 v[42:43], v[60:61], v[62:63]
	s_nop 0
	v_pk_add_f32 v[42:43], v[42:43], v[44:45]
	s_nop 0
	v_pk_add_f32 v[40:41], v[40:41], v[42:43]
	v_mov_b32_e32 v42, v165
	v_mov_b32_e32 v43, v165
	s_nop 0
	v_mov_b32_dpp v42, v40 quad_perm:[1,0,3,2] row_mask:0xf bank_mask:0xf
	v_mov_b32_dpp v43, v41 quad_perm:[1,0,3,2] row_mask:0xf bank_mask:0xf
	v_pk_add_f32 v[40:41], v[40:41], v[42:43]
	ds_bpermute_b32 v42, v130, v40
	ds_bpermute_b32 v43, v130, v41
	s_waitcnt lgkmcnt(0)
	v_pk_add_f32 v[42:43], v[40:41], v[42:43]
	ds_bpermute_b32 v44, v131, v42
	ds_bpermute_b32 v45, v131, v43
	v_lshl_add_u64 v[40:41], s[54:55], 0, v[94:95]
	global_store_dwordx4 v[40:41], v[56:59], off
	s_and_saveexec_b64 s[56:57], s[10:11]
	s_cbranch_execz .LBB0_604
	s_waitcnt lgkmcnt(0)
	v_pk_add_f32 v[42:43], v[42:43], v[44:45]
	v_add_co_u32_e32 v44, vcc, 0x12000, v124
	s_nop 1
	v_addc_co_u32_e32 v45, vcc, 0, v125, vcc
	global_store_dwordx2 v[44:45], v[42:43], off
; __device__ __forceinline__ u32x4 pack8f(f32x4 a, f32x4 b) { u32x4 w; w.x = cvt_pk_bf16(a[0], a[1]); w.y = cvt_pk_bf16(a[2], a[3]); w.z = cvt_pk_bf16(b[0], b[1]); w.w = cvt_pk_bf16(b[2], b[3]); return w; }
;     __device__ __forceinline__ void operator()(const f32x4 (&acc)[2][2][4][2], const Unit& u, int wr, int wc, int fr, int fq, const EpiCtx& X) const {
;     ...
;             for (int m = 0; m < 4; ++m) {
;                 const int rl = ai * HALF + m * 16; const unsigned off = lo + (unsigned)(rl * 64) * 2u;
;                 const f32x4 o0a = acc[ai][0][m][0], o0b = acc[ai][0][m][1], o1a = acc[ai][1][m][0], o1b = acc[ai][1][m][1];
;                 const f32x4 ra_ = dpp_swap1(odd ? o0a : o1a), rb_ = dpp_swap1(odd ? o0b : o1b);
;                 const f32x4 pa[2] = {odd ? ra_ : o0a, odd ? o1a : ra_}, pb[2] = {odd ? rb_ : o0b, odd ? o1b : rb_};
; #pragma unroll
;                 for (int q = 0; q < 2; ++q) {
;                     const u32x4 w0 = raw[2 * m + q];
;                     const f32x4 r0 = (f32x4){bf_lo(w0.x), bf_hi(w0.x), bf_lo(w0.y), bf_hi(w0.y)}, r1 = (f32x4){bf_lo(w0.z), bf_hi(w0.z), bf_lo(w0.w), bf_hi(w0.w)};
;                     f32x4 y0, y1;
;                     if (RESN) { const f32x2 t = tbl[rl + q]; const float mu = t.x, ra = t.y * ALPHA; y0 = (r0 - mu) * ra * g0 + b0 + pa[q]; y1 = (r1 - mu) * ra * g1 + b1 + pb[q]; }
;                     else { y0 = r0 * ALPHA + pa[q]; y1 = r1 * ALPHA + pb[q]; }
;                     { const u32x4 w = pack8f(y0, y1); *(u32x4*)(xb + off + q * 128) = w;
;                         y0 = (f32x4){bf_lo(w.x), bf_hi(w.x), bf_lo(w.y), bf_hi(w.y)}; y1 = (f32x4){bf_lo(w.z), bf_hi(w.z), bf_lo(w.w), bf_hi(w.w)}; }
;                     float sa = ((y0[0] + y0[1]) + (y0[2] + y0[3])) + ((y1[0] + y1[1]) + (y1[2] + y1[3]));
;                     float sb = ((y0[0] * y0[0] + y0[1] * y0[1]) + (y0[2] * y0[2] + y0[3] * y0[3])) + ((y1[0] * y1[0] + y1[1] * y1[1]) + (y1[2] * y1[2] + y1[3] * y1[3]));
;                     sa += dpp_x1(sa);
;                     sb += dpp_x1(sb);
;                     sa += __shfl_xor(sa, 16); sa += __shfl_xor(sa, 32); sb += __shfl_xor(sb, 16); sb += __shfl_xor(sb, 32);
;                     if (fq == 0 && !odd) ps[(size_t)(rl + q) * 64] = (f32x2){sa, sb};
.LBB0_604:
	s_or_b64 exec, exec, s[56:57]
	v_cndmask_b32_e64 v37, v37, v50, s[8:9]
	v_cndmask_b32_e64 v36, v36, v48, s[8:9]
	v_cndmask_b32_e64 v39, v39, v51, s[8:9]
	v_cndmask_b32_e64 v38, v38, v49, s[8:9]
	v_cndmask_b32_e64 v33, v33, v54, s[8:9]
	v_cndmask_b32_e64 v32, v32, v52, s[8:9]
	v_cndmask_b32_e64 v35, v35, v55, s[8:9]
	v_cndmask_b32_e64 v34, v34, v53, s[8:9]
	v_lshlrev_b32_e32 v42, 16, v80
	v_and_b32_e32 v43, 0xffff0000, v80
	s_waitcnt lgkmcnt(1)
	v_lshlrev_b32_e32 v44, 16, v81
	s_waitcnt lgkmcnt(0)
	v_and_b32_e32 v45, 0xffff0000, v81
	v_lshlrev_b32_e32 v46, 16, v82
	v_and_b32_e32 v47, 0xffff0000, v82
	v_lshlrev_b32_e32 v48, 16, v83
	v_and_b32_e32 v49, 0xffff0000, v83
	v_pk_fma_f32 v[38:39], v[44:45], s[18:19], v[38:39] op_sel_hi:[1,0,1]
	v_pk_fma_f32 v[36:37], v[42:43], s[18:19], v[36:37] op_sel_hi:[1,0,1]
	v_pk_fma_f32 v[34:35], v[48:49], s[18:19], v[34:35] op_sel_hi:[1,0,1]
	v_pk_fma_f32 v[32:33], v[46:47], s[18:19], v[32:33] op_sel_hi:[1,0,1]
	v_cvt_pk_bf16_f32 v36, v36, v37
	v_cvt_pk_bf16_f32 v37, v38, v39
	s_nop 0
	v_cvt_pk_bf16_f32 v38, v32, v33
	v_cvt_pk_bf16_f32 v39, v34, v35
	v_lshlrev_b32_e32 v32, 16, v36
	v_and_b32_e32 v34, 0xffff0000, v36
	v_lshlrev_b32_e32 v42, 16, v37
	v_and_b32_e32 v44, 0xffff0000, v37
	v_lshlrev_b32_e32 v46, 16, v38
	v_and_b32_e32 v48, 0xffff0000, v38
	v_lshlrev_b32_e32 v50, 16, v39
	v_and_b32_e32 v52, 0xffff0000, v39
	v_mul_f32_e32 v33, v32, v32
	v_mul_f32_e32 v35, v34, v34
	v_mul_f32_e32 v43, v42, v42
	v_mul_f32_e32 v45, v44, v44
	v_mul_f32_e32 v47, v46, v46
	v_mul_f32_e32 v49, v48, v48
	v_mul_f32_e32 v51, v50, v50
	v_mul_f32_e32 v53, v52, v52
	v_pk_add_f32 v[32:33], v[32:33], v[34:35]
	v_pk_add_f32 v[34:35], v[42:43], v[44:45]
	v_pk_add_f32 v[42:43], v[50:51], v[52:53]
	v_pk_add_f32 v[32:33], v[32:33], v[34:35]
	v_pk_add_f32 v[34:35], v[46:47], v[48:49]
	global_store_dwordx4 v[40:41], v[36:39], off offset:128
	v_pk_add_f32 v[34:35], v[34:35], v[42:43]
	s_nop 0
	v_pk_add_f32 v[32:33], v[32:33], v[34:35]
	v_mov_b32_e32 v34, v165
	v_mov_b32_e32 v35, v165
	s_nop 0
	v_mov_b32_dpp v34, v32 quad_perm:[1,0,3,2] row_mask:0xf bank_mask:0xf
	v_mov_b32_dpp v35, v33 quad_perm:[1,0,3,2] row_mask:0xf bank_mask:0xf
	v_pk_add_f32 v[32:33], v[32:33], v[34:35]
	ds_bpermute_b32 v34, v130, v32
	ds_bpermute_b32 v35, v130, v33
	s_waitcnt lgkmcnt(0)
	v_pk_add_f32 v[32:33], v[32:33], v[34:35]
	ds_bpermute_b32 v34, v131, v32
	ds_bpermute_b32 v35, v131, v33
	s_and_saveexec_b64 s[56:57], s[10:11]
	s_cbranch_execz .LBB0_606
	s_waitcnt lgkmcnt(0)
	v_pk_add_f32 v[32:33], v[32:33], v[34:35]
	v_add_co_u32_e32 v34, vcc, 0x12000, v124
	s_nop 1
	v_addc_co_u32_e32 v35, vcc, 0, v125, vcc
	global_store_dwordx2 v[34:35], v[32:33], off offset:512
.LBB0_606:
	s_or_b64 exec, exec, s[56:57]
	s_waitcnt lgkmcnt(1)
	v_cndmask_b32_e64 v34, v28, v20, s[8:9]
	v_mov_b32_e32 v32, 0
	v_cndmask_b32_e64 v33, v29, v21, s[8:9]
	s_waitcnt lgkmcnt(0)
	v_cndmask_b32_e64 v35, v30, v22, s[8:9]
	v_mov_b32_dpp v32, v34 quad_perm:[1,0,3,2] row_mask:0xf bank_mask:0xf
	v_mov_b32_e32 v34, 0
	v_cndmask_b32_e64 v36, v31, v23, s[8:9]
	v_cndmask_b32_e64 v38, v24, v16, s[8:9]
	v_mov_b32_dpp v34, v33 quad_perm:[1,0,3,2] row_mask:0xf bank_mask:0xf
	v_mov_b32_e32 v33, 0
	v_cndmask_b32_e64 v37, v25, v17, s[8:9]
	v_cndmask_b32_e64 v39, v26, v18, s[8:9]
	v_mov_b32_dpp v33, v35 quad_perm:[1,0,3,2] row_mask:0xf bank_mask:0xf
	v_mov_b32_e32 v35, 0
	v_cndmask_b32_e64 v40, v27, v19, s[8:9]
	v_cndmask_b32_e64 v29, v34, v29, s[8:9]
	v_mov_b32_dpp v35, v36 quad_perm:[1,0,3,2] row_mask:0xf bank_mask:0xf
	v_mov_b32_e32 v36, 0
	v_cndmask_b32_e64 v28, v32, v28, s[8:9]
	v_cndmask_b32_e64 v31, v35, v31, s[8:9]
	v_mov_b32_dpp v36, v38 quad_perm:[1,0,3,2] row_mask:0xf bank_mask:0xf
	v_mov_b32_e32 v38, 0
	v_cndmask_b32_e64 v30, v33, v30, s[8:9]
	v_cndmask_b32_e64 v24, v36, v24, s[8:9]
	v_mov_b32_dpp v38, v37 quad_perm:[1,0,3,2] row_mask:0xf bank_mask:0xf
	v_mov_b32_e32 v37, 0
	v_cndmask_b32_e64 v25, v38, v25, s[8:9]
	s_waitcnt vmcnt(11)
	v_and_b32_e32 v41, 0xffff0000, v76
	v_mov_b32_dpp v37, v39 quad_perm:[1,0,3,2] row_mask:0xf bank_mask:0xf
	v_mov_b32_e32 v39, 0
	v_cndmask_b32_e64 v26, v37, v26, s[8:9]
	v_lshlrev_b32_e32 v42, 16, v77
	v_mov_b32_dpp v39, v40 quad_perm:[1,0,3,2] row_mask:0xf bank_mask:0xf
	v_cndmask_b32_e64 v27, v39, v27, s[8:9]
	v_lshlrev_b32_e32 v40, 16, v76
	v_and_b32_e32 v43, 0xffff0000, v77
	v_lshlrev_b32_e32 v44, 16, v78
	v_and_b32_e32 v45, 0xffff0000, v78
	v_lshlrev_b32_e32 v46, 16, v79
	v_and_b32_e32 v47, 0xffff0000, v79
	v_pk_fma_f32 v[30:31], v[42:43], s[18:19], v[30:31] op_sel_hi:[1,0,1]
	v_pk_fma_f32 v[28:29], v[40:41], s[18:19], v[28:29] op_sel_hi:[1,0,1]
	v_pk_fma_f32 v[26:27], v[46:47], s[18:19], v[26:27] op_sel_hi:[1,0,1]
	v_pk_fma_f32 v[24:25], v[44:45], s[18:19], v[24:25] op_sel_hi:[1,0,1]
	v_cvt_pk_bf16_f32 v40, v28, v29
	v_cvt_pk_bf16_f32 v41, v30, v31
	v_mov_b32_e32 v93, v165
	v_cvt_pk_bf16_f32 v42, v24, v25
	v_cvt_pk_bf16_f32 v43, v26, v27
	v_lshlrev_b32_e32 v24, 16, v40
	v_and_b32_e32 v26, 0xffff0000, v40
	v_lshlrev_b32_e32 v28, 16, v41
	v_and_b32_e32 v30, 0xffff0000, v41
	v_lshlrev_b32_e32 v44, 16, v42
	v_and_b32_e32 v46, 0xffff0000, v42
	v_lshlrev_b32_e32 v48, 16, v43
	v_and_b32_e32 v50, 0xffff0000, v43
	v_mul_f32_e32 v25, v24, v24
	v_mul_f32_e32 v27, v26, v26
	v_mul_f32_e32 v29, v28, v28
	v_mul_f32_e32 v31, v30, v30
	v_mul_f32_e32 v45, v44, v44
	v_mul_f32_e32 v47, v46, v46
	v_mul_f32_e32 v49, v48, v48
	v_mul_f32_e32 v51, v50, v50
	v_pk_add_f32 v[24:25], v[24:25], v[26:27]
	v_pk_add_f32 v[26:27], v[28:29], v[30:31]
	v_pk_add_f32 v[28:29], v[48:49], v[50:51]
	v_pk_add_f32 v[24:25], v[24:25], v[26:27]
	v_pk_add_f32 v[26:27], v[44:45], v[46:47]
	s_nop 0
	v_pk_add_f32 v[26:27], v[26:27], v[28:29]
	s_nop 0
	v_pk_add_f32 v[24:25], v[24:25], v[26:27]
	v_mov_b32_e32 v26, v165
	v_mov_b32_e32 v27, v165
	s_nop 0
	v_mov_b32_dpp v26, v24 quad_perm:[1,0,3,2] row_mask:0xf bank_mask:0xf
	v_mov_b32_dpp v27, v25 quad_perm:[1,0,3,2] row_mask:0xf bank_mask:0xf
	v_pk_add_f32 v[24:25], v[24:25], v[26:27]
	ds_bpermute_b32 v26, v130, v24
	ds_bpermute_b32 v27, v130, v25
	s_waitcnt lgkmcnt(0)
	v_pk_add_f32 v[26:27], v[24:25], v[26:27]
	ds_bpermute_b32 v28, v131, v26
	ds_bpermute_b32 v29, v131, v27
	v_lshl_add_u64 v[24:25], s[54:55], 0, v[92:93]
	global_store_dwordx4 v[24:25], v[40:43], off
	s_and_saveexec_b64 s[56:57], s[10:11]
	s_cbranch_execz .LBB0_608
	s_waitcnt lgkmcnt(0)
	v_pk_add_f32 v[26:27], v[26:27], v[28:29]
	v_add_co_u32_e32 v28, vcc, 0x14000, v124
	s_nop 1
	v_addc_co_u32_e32 v29, vcc, 0, v125, vcc
	global_store_dwordx2 v[28:29], v[26:27], off
; __device__ __forceinline__ u32x4 pack8f(f32x4 a, f32x4 b) { u32x4 w; w.x = cvt_pk_bf16(a[0], a[1]); w.y = cvt_pk_bf16(a[2], a[3]); w.z = cvt_pk_bf16(b[0], b[1]); w.w = cvt_pk_bf16(b[2], b[3]); return w; }
; __device__ __forceinline__ float dpp_x1(float x) { return __builtin_bit_cast(float, __builtin_amdgcn_update_dpp(0, __builtin_bit_cast(int, x), 0xB1, 0xF, 0xF, false)); }
;     __device__ __forceinline__ void operator()(const f32x4 (&acc)[2][2][4][2], const Unit& u, int wr, int wc, int fr, int fq, const EpiCtx& X) const {
;     ...
;                 for (int q = 0; q < 2; ++q) {
;                     const u32x4 w0 = raw[2 * m + q];
;                     const f32x4 r0 = (f32x4){bf_lo(w0.x), bf_hi(w0.x), bf_lo(w0.y), bf_hi(w0.y)}, r1 = (f32x4){bf_lo(w0.z), bf_hi(w0.z), bf_lo(w0.w), bf_hi(w0.w)};
;                     f32x4 y0, y1;
;                     if (RESN) { const f32x2 t = tbl[rl + q]; const float mu = t.x, ra = t.y * ALPHA; y0 = (r0 - mu) * ra * g0 + b0 + pa[q]; y1 = (r1 - mu) * ra * g1 + b1 + pb[q]; }
;                     else { y0 = r0 * ALPHA + pa[q]; y1 = r1 * ALPHA + pb[q]; }
;                     { const u32x4 w = pack8f(y0, y1); *(u32x4*)(xb + off + q * 128) = w;
;                         y0 = (f32x4){bf_lo(w.x), bf_hi(w.x), bf_lo(w.y), bf_hi(w.y)}; y1 = (f32x4){bf_lo(w.z), bf_hi(w.z), bf_lo(w.w), bf_hi(w.w)}; }
;                     float sa = ((y0[0] + y0[1]) + (y0[2] + y0[3])) + ((y1[0] + y1[1]) + (y1[2] + y1[3]));
;                     float sb = ((y0[0] * y0[0] + y0[1] * y0[1]) + (y0[2] * y0[2] + y0[3] * y0[3])) + ((y1[0] * y1[0] + y1[1] * y1[1]) + (y1[2] * y1[2] + y1[3] * y1[3]));
;                     sa += dpp_x1(sa);
;                     sb += dpp_x1(sb);
;                     sa += __shfl_xor(sa, 16); sa += __shfl_xor(sa, 32); sb += __shfl_xor(sb, 16); sb += __shfl_xor(sb, 32);
;                     if (fq == 0 && !odd) ps[(size_t)(rl + q) * 64] = (f32x2){sa, sb};
.LBB0_608:
	s_or_b64 exec, exec, s[56:57]
	v_cndmask_b32_e64 v21, v21, v34, s[8:9]
	v_cndmask_b32_e64 v20, v20, v32, s[8:9]
	v_cndmask_b32_e64 v23, v23, v35, s[8:9]
	v_cndmask_b32_e64 v22, v22, v33, s[8:9]
	v_cndmask_b32_e64 v17, v17, v38, s[8:9]
	v_cndmask_b32_e64 v16, v16, v36, s[8:9]
	v_cndmask_b32_e64 v19, v19, v39, s[8:9]
	v_cndmask_b32_e64 v18, v18, v37, s[8:9]
	s_waitcnt vmcnt(12)
	v_lshlrev_b32_e32 v26, 16, v72
	v_and_b32_e32 v27, 0xffff0000, v72
	s_waitcnt lgkmcnt(1)
	v_lshlrev_b32_e32 v28, 16, v73
	s_waitcnt lgkmcnt(0)
	v_and_b32_e32 v29, 0xffff0000, v73
	v_lshlrev_b32_e32 v30, 16, v74
	v_and_b32_e32 v31, 0xffff0000, v74
	v_lshlrev_b32_e32 v32, 16, v75
	v_and_b32_e32 v33, 0xffff0000, v75
	v_pk_fma_f32 v[22:23], v[28:29], s[18:19], v[22:23] op_sel_hi:[1,0,1]
	v_pk_fma_f32 v[20:21], v[26:27], s[18:19], v[20:21] op_sel_hi:[1,0,1]
	v_pk_fma_f32 v[18:19], v[32:33], s[18:19], v[18:19] op_sel_hi:[1,0,1]
	v_pk_fma_f32 v[16:17], v[30:31], s[18:19], v[16:17] op_sel_hi:[1,0,1]
	v_cvt_pk_bf16_f32 v20, v20, v21
	v_cvt_pk_bf16_f32 v21, v22, v23
	s_nop 0
	v_cvt_pk_bf16_f32 v22, v16, v17
	v_cvt_pk_bf16_f32 v23, v18, v19
	v_lshlrev_b32_e32 v16, 16, v20
	v_and_b32_e32 v18, 0xffff0000, v20
	v_lshlrev_b32_e32 v26, 16, v21
	v_and_b32_e32 v28, 0xffff0000, v21
	v_lshlrev_b32_e32 v30, 16, v22
	v_and_b32_e32 v32, 0xffff0000, v22
	v_lshlrev_b32_e32 v34, 16, v23
	v_and_b32_e32 v36, 0xffff0000, v23
	v_mul_f32_e32 v17, v16, v16
	v_mul_f32_e32 v19, v18, v18
	v_mul_f32_e32 v27, v26, v26
	v_mul_f32_e32 v29, v28, v28
	v_mul_f32_e32 v31, v30, v30
	v_mul_f32_e32 v33, v32, v32
	v_mul_f32_e32 v35, v34, v34
	v_mul_f32_e32 v37, v36, v36
	v_pk_add_f32 v[16:17], v[16:17], v[18:19]
	v_pk_add_f32 v[18:19], v[26:27], v[28:29]
	v_pk_add_f32 v[26:27], v[34:35], v[36:37]
	v_pk_add_f32 v[16:17], v[16:17], v[18:19]
	v_pk_add_f32 v[18:19], v[30:31], v[32:33]
	global_store_dwordx4 v[24:25], v[20:23], off offset:128
	v_pk_add_f32 v[18:19], v[18:19], v[26:27]
	s_nop 0
	v_pk_add_f32 v[16:17], v[16:17], v[18:19]
	v_mov_b32_e32 v18, v165
	v_mov_b32_e32 v19, v165
	s_nop 0
	v_mov_b32_dpp v18, v16 quad_perm:[1,0,3,2] row_mask:0xf bank_mask:0xf
	v_mov_b32_dpp v19, v17 quad_perm:[1,0,3,2] row_mask:0xf bank_mask:0xf
	v_pk_add_f32 v[16:17], v[16:17], v[18:19]
	ds_bpermute_b32 v18, v130, v16
	ds_bpermute_b32 v19, v130, v17
	s_waitcnt lgkmcnt(0)
	v_pk_add_f32 v[16:17], v[16:17], v[18:19]
	ds_bpermute_b32 v18, v131, v16
	ds_bpermute_b32 v19, v131, v17
	s_and_saveexec_b64 s[56:57], s[10:11]
	s_cbranch_execz .LBB0_610
	s_waitcnt lgkmcnt(0)
	v_pk_add_f32 v[16:17], v[16:17], v[18:19]
	v_add_co_u32_e32 v18, vcc, 0x14000, v124
	s_nop 1
	v_addc_co_u32_e32 v19, vcc, 0, v125, vcc
	global_store_dwordx2 v[18:19], v[16:17], off offset:512
; __device__ __forceinline__ u32x4 pack8f(f32x4 a, f32x4 b) { u32x4 w; w.x = cvt_pk_bf16(a[0], a[1]); w.y = cvt_pk_bf16(a[2], a[3]); w.z = cvt_pk_bf16(b[0], b[1]); w.w = cvt_pk_bf16(b[2], b[3]); return w; }
;     __device__ __forceinline__ void operator()(const f32x4 (&acc)[2][2][4][2], const Unit& u, int wr, int wc, int fr, int fq, const EpiCtx& X) const {
;     ...
;             for (int m = 0; m < 4; ++m) {
;                 const int rl = ai * HALF + m * 16; const unsigned off = lo + (unsigned)(rl * 64) * 2u;
;                 const f32x4 o0a = acc[ai][0][m][0], o0b = acc[ai][0][m][1], o1a = acc[ai][1][m][0], o1b = acc[ai][1][m][1];
;                 const f32x4 ra_ = dpp_swap1(odd ? o0a : o1a), rb_ = dpp_swap1(odd ? o0b : o1b);
;                 const f32x4 pa[2] = {odd ? ra_ : o0a, odd ? o1a : ra_}, pb[2] = {odd ? rb_ : o0b, odd ? o1b : rb_};
; #pragma unroll
;                 for (int q = 0; q < 2; ++q) {
;                     const u32x4 w0 = raw[2 * m + q];
;                     const f32x4 r0 = (f32x4){bf_lo(w0.x), bf_hi(w0.x), bf_lo(w0.y), bf_hi(w0.y)}, r1 = (f32x4){bf_lo(w0.z), bf_hi(w0.z), bf_lo(w0.w), bf_hi(w0.w)};
;                     f32x4 y0, y1;
;                     if (RESN) { const f32x2 t = tbl[rl + q]; const float mu = t.x, ra = t.y * ALPHA; y0 = (r0 - mu) * ra * g0 + b0 + pa[q]; y1 = (r1 - mu) * ra * g1 + b1 + pb[q]; }
;                     else { y0 = r0 * ALPHA + pa[q]; y1 = r1 * ALPHA + pb[q]; }
;                     { const u32x4 w = pack8f(y0, y1); *(u32x4*)(xb + off + q * 128) = w;
;                         y0 = (f32x4){bf_lo(w.x), bf_hi(w.x), bf_lo(w.y), bf_hi(w.y)}; y1 = (f32x4){bf_lo(w.z), bf_hi(w.z), bf_lo(w.w), bf_hi(w.w)}; }
;                     float sa = ((y0[0] + y0[1]) + (y0[2] + y0[3])) + ((y1[0] + y1[1]) + (y1[2] + y1[3]));
;                     float sb = ((y0[0] * y0[0] + y0[1] * y0[1]) + (y0[2] * y0[2] + y0[3] * y0[3])) + ((y1[0] * y1[0] + y1[1] * y1[1]) + (y1[2] * y1[2] + y1[3] * y1[3]));
;                     sa += dpp_x1(sa);
;                     sb += dpp_x1(sb);
;                     sa += __shfl_xor(sa, 16); sa += __shfl_xor(sa, 32); sb += __shfl_xor(sb, 16); sb += __shfl_xor(sb, 32);
;                     if (fq == 0 && !odd) ps[(size_t)(rl + q) * 64] = (f32x2){sa, sb};
.LBB0_610:
	s_or_b64 exec, exec, s[56:57]
	s_waitcnt lgkmcnt(1)
	v_cndmask_b32_e64 v18, v12, v4, s[8:9]
	v_mov_b32_e32 v16, 0
	v_cndmask_b32_e64 v17, v13, v5, s[8:9]
	s_waitcnt lgkmcnt(0)
	v_cndmask_b32_e64 v19, v14, v6, s[8:9]
	v_mov_b32_dpp v16, v18 quad_perm:[1,0,3,2] row_mask:0xf bank_mask:0xf
	v_mov_b32_e32 v18, 0
	v_cndmask_b32_e64 v20, v15, v7, s[8:9]
	v_cndmask_b32_e64 v22, v8, v0, s[8:9]
	v_mov_b32_dpp v18, v17 quad_perm:[1,0,3,2] row_mask:0xf bank_mask:0xf
	v_mov_b32_e32 v17, 0
	v_cndmask_b32_e64 v21, v9, v1, s[8:9]
	v_cndmask_b32_e64 v23, v10, v2, s[8:9]
	v_mov_b32_dpp v17, v19 quad_perm:[1,0,3,2] row_mask:0xf bank_mask:0xf
	v_mov_b32_e32 v19, 0
	v_cndmask_b32_e64 v24, v11, v3, s[8:9]
	v_cndmask_b32_e64 v13, v18, v13, s[8:9]
	v_mov_b32_dpp v19, v20 quad_perm:[1,0,3,2] row_mask:0xf bank_mask:0xf
	v_mov_b32_e32 v20, 0
	v_cndmask_b32_e64 v12, v16, v12, s[8:9]
	v_cndmask_b32_e64 v15, v19, v15, s[8:9]
	v_mov_b32_dpp v20, v22 quad_perm:[1,0,3,2] row_mask:0xf bank_mask:0xf
	v_mov_b32_e32 v22, 0
	v_cndmask_b32_e64 v14, v17, v14, s[8:9]
	v_cndmask_b32_e64 v8, v20, v8, s[8:9]
	v_mov_b32_dpp v22, v21 quad_perm:[1,0,3,2] row_mask:0xf bank_mask:0xf
	v_mov_b32_e32 v21, 0
	v_cndmask_b32_e64 v9, v22, v9, s[8:9]
	s_waitcnt vmcnt(13)
	v_and_b32_e32 v25, 0xffff0000, v68
	v_mov_b32_dpp v21, v23 quad_perm:[1,0,3,2] row_mask:0xf bank_mask:0xf
	v_mov_b32_e32 v23, 0
	v_cndmask_b32_e64 v10, v21, v10, s[8:9]
	v_lshlrev_b32_e32 v26, 16, v69
	v_mov_b32_dpp v23, v24 quad_perm:[1,0,3,2] row_mask:0xf bank_mask:0xf
	v_cndmask_b32_e64 v11, v23, v11, s[8:9]
	v_lshlrev_b32_e32 v24, 16, v68
	v_and_b32_e32 v27, 0xffff0000, v69
	v_lshlrev_b32_e32 v28, 16, v70
	v_and_b32_e32 v29, 0xffff0000, v70
	v_lshlrev_b32_e32 v30, 16, v71
	v_and_b32_e32 v31, 0xffff0000, v71
	v_pk_fma_f32 v[14:15], v[26:27], s[18:19], v[14:15] op_sel_hi:[1,0,1]
	v_pk_fma_f32 v[12:13], v[24:25], s[18:19], v[12:13] op_sel_hi:[1,0,1]
	v_pk_fma_f32 v[10:11], v[30:31], s[18:19], v[10:11] op_sel_hi:[1,0,1]
	v_pk_fma_f32 v[8:9], v[28:29], s[18:19], v[8:9] op_sel_hi:[1,0,1]
	v_cvt_pk_bf16_f32 v24, v12, v13
	v_cvt_pk_bf16_f32 v25, v14, v15
	s_nop 0
	v_cvt_pk_bf16_f32 v26, v8, v9
	v_cvt_pk_bf16_f32 v27, v10, v11
	v_lshlrev_b32_e32 v8, 16, v24
	v_and_b32_e32 v10, 0xffff0000, v24
	v_lshlrev_b32_e32 v12, 16, v25
	v_and_b32_e32 v14, 0xffff0000, v25
	v_lshlrev_b32_e32 v28, 16, v26
	v_and_b32_e32 v30, 0xffff0000, v26
	v_lshlrev_b32_e32 v32, 16, v27
	v_and_b32_e32 v34, 0xffff0000, v27
	v_mul_f32_e32 v9, v8, v8
	v_mul_f32_e32 v11, v10, v10
	v_mul_f32_e32 v13, v12, v12
	v_mul_f32_e32 v15, v14, v14
	v_mul_f32_e32 v29, v28, v28
	v_mul_f32_e32 v31, v30, v30
	v_mul_f32_e32 v33, v32, v32
	v_mul_f32_e32 v35, v34, v34
	v_pk_add_f32 v[8:9], v[8:9], v[10:11]
	v_pk_add_f32 v[10:11], v[12:13], v[14:15]
	v_pk_add_f32 v[12:13], v[32:33], v[34:35]
	v_pk_add_f32 v[8:9], v[8:9], v[10:11]
	v_pk_add_f32 v[10:11], v[28:29], v[30:31]
	s_nop 0
	v_pk_add_f32 v[10:11], v[10:11], v[12:13]
	s_nop 0
	v_pk_add_f32 v[8:9], v[8:9], v[10:11]
	v_mov_b32_e32 v10, v165
	v_mov_b32_e32 v11, v165
	s_nop 0
	v_mov_b32_dpp v10, v8 quad_perm:[1,0,3,2] row_mask:0xf bank_mask:0xf
	v_mov_b32_dpp v11, v9 quad_perm:[1,0,3,2] row_mask:0xf bank_mask:0xf
	v_pk_add_f32 v[8:9], v[8:9], v[10:11]
	ds_bpermute_b32 v10, v130, v8
	ds_bpermute_b32 v11, v130, v9
	s_waitcnt lgkmcnt(0)
	v_pk_add_f32 v[10:11], v[8:9], v[10:11]
	ds_bpermute_b32 v12, v131, v10
	ds_bpermute_b32 v13, v131, v11
	v_lshl_add_u64 v[8:9], s[54:55], 0, v[164:165]
	global_store_dwordx4 v[8:9], v[24:27], off
	s_and_saveexec_b64 s[54:55], s[10:11]
	s_cbranch_execz .LBB0_612
	s_waitcnt lgkmcnt(0)
	v_pk_add_f32 v[10:11], v[10:11], v[12:13]
	v_add_co_u32_e32 v12, vcc, 0x16000, v124
	s_nop 1
	v_addc_co_u32_e32 v13, vcc, 0, v125, vcc
	global_store_dwordx2 v[12:13], v[10:11], off
.LBB0_612:
	s_or_b64 exec, exec, s[54:55]
	v_cndmask_b32_e64 v5, v5, v18, s[8:9]
	v_cndmask_b32_e64 v4, v4, v16, s[8:9]
	v_cndmask_b32_e64 v7, v7, v19, s[8:9]
	v_cndmask_b32_e64 v6, v6, v17, s[8:9]
	v_cndmask_b32_e64 v1, v1, v22, s[8:9]
	v_cndmask_b32_e64 v0, v0, v20, s[8:9]
	v_cndmask_b32_e64 v3, v3, v23, s[8:9]
	v_cndmask_b32_e64 v2, v2, v21, s[8:9]
	s_waitcnt vmcnt(14)
	v_lshlrev_b32_e32 v10, 16, v64
	v_and_b32_e32 v11, 0xffff0000, v64
	s_waitcnt lgkmcnt(1)
	v_lshlrev_b32_e32 v12, 16, v65
	s_waitcnt lgkmcnt(0)
	v_and_b32_e32 v13, 0xffff0000, v65
	v_lshlrev_b32_e32 v14, 16, v66
	v_and_b32_e32 v15, 0xffff0000, v66
	v_lshlrev_b32_e32 v16, 16, v67
	v_and_b32_e32 v17, 0xffff0000, v67
	v_pk_fma_f32 v[6:7], v[12:13], s[18:19], v[6:7] op_sel_hi:[1,0,1]
	v_pk_fma_f32 v[4:5], v[10:11], s[18:19], v[4:5] op_sel_hi:[1,0,1]
	v_pk_fma_f32 v[2:3], v[16:17], s[18:19], v[2:3] op_sel_hi:[1,0,1]
	v_pk_fma_f32 v[0:1], v[14:15], s[18:19], v[0:1] op_sel_hi:[1,0,1]
	v_cvt_pk_bf16_f32 v4, v4, v5
	v_cvt_pk_bf16_f32 v5, v6, v7
	s_nop 0
	v_cvt_pk_bf16_f32 v6, v0, v1
	v_cvt_pk_bf16_f32 v7, v2, v3
	v_lshlrev_b32_e32 v0, 16, v4
	v_and_b32_e32 v2, 0xffff0000, v4
	v_lshlrev_b32_e32 v10, 16, v5
	v_and_b32_e32 v12, 0xffff0000, v5
	v_lshlrev_b32_e32 v14, 16, v6
	v_and_b32_e32 v16, 0xffff0000, v6
	v_lshlrev_b32_e32 v18, 16, v7
	v_and_b32_e32 v20, 0xffff0000, v7
	v_mul_f32_e32 v1, v0, v0
	v_mul_f32_e32 v3, v2, v2
	v_mul_f32_e32 v11, v10, v10
	v_mul_f32_e32 v13, v12, v12
	v_mul_f32_e32 v15, v14, v14
	v_mul_f32_e32 v17, v16, v16
	v_mul_f32_e32 v19, v18, v18
	v_mul_f32_e32 v21, v20, v20
	v_pk_add_f32 v[0:1], v[0:1], v[2:3]
	v_pk_add_f32 v[2:3], v[10:11], v[12:13]
	v_pk_add_f32 v[10:11], v[18:19], v[20:21]
	v_pk_add_f32 v[0:1], v[0:1], v[2:3]
	v_pk_add_f32 v[2:3], v[14:15], v[16:17]
	global_store_dwordx4 v[8:9], v[4:7], off offset:128
	v_pk_add_f32 v[2:3], v[2:3], v[10:11]
	s_nop 0
	v_pk_add_f32 v[0:1], v[0:1], v[2:3]
	v_mov_b32_e32 v2, v165
	v_mov_b32_e32 v3, v165
	s_nop 0
	v_mov_b32_dpp v2, v0 quad_perm:[1,0,3,2] row_mask:0xf bank_mask:0xf
	v_mov_b32_dpp v3, v1 quad_perm:[1,0,3,2] row_mask:0xf bank_mask:0xf
	v_pk_add_f32 v[0:1], v[0:1], v[2:3]
	ds_bpermute_b32 v2, v130, v0
	ds_bpermute_b32 v3, v130, v1
	s_waitcnt lgkmcnt(0)
	v_pk_add_f32 v[0:1], v[0:1], v[2:3]
	ds_bpermute_b32 v2, v131, v0
	ds_bpermute_b32 v3, v131, v1
	s_and_saveexec_b64 s[54:55], s[10:11]
	s_cbranch_execz .LBB0_614
	s_waitcnt lgkmcnt(0)
	v_pk_add_f32 v[0:1], v[0:1], v[2:3]
	v_add_co_u32_e32 v2, vcc, 0x16000, v124
	s_nop 1
	v_addc_co_u32_e32 v3, vcc, 0, v125, vcc
	global_store_dwordx2 v[2:3], v[0:1], off offset:512

; #define LAS __attribute__((address_space(3)))
;     __device__ __forceinline__ void operator()(const f32x4 (&acc)[2][2][4][2], const Unit& u, int wr, int wc, int fr, int fq, const EpiCtx& X) const {
;     ...
;         char* yb = nullptr; char* xb = (char*)(XB + (size_t)u.pm * BM * DM + (size_t)(u.pn * 4 + wc) * (BM * 64));
;         unsigned lo = (unsigned)((wr * 64 + fe) * 64 + o32 + 8 * fq) * 2u; EPI_OPAQUE(lo);
;         const int col = u.pn * BM + wc * 64 + o32 + 8 * fq;
;         f32x4 g0, g1, b0, b1;
;         if (RESN) { ensure_tbl(PSp, sidp, u.pm, X);
;             g0 = *(const f32x4*)(gp + col); g1 = *(const f32x4*)(gp + col + 4); b0 = *(const f32x4*)(bp + col) * ALPHA; b1 = *(const f32x4*)(bp + col + 4) * ALPHA; }
;         const LAS f32x2* tbl = (const LAS f32x2*)(X.lds + TBL_OFF) + wr * 64 + fe;
;         f32x2* ps = PSn + ((size_t)u.pm * BM + wr * 64 + fe) * 64 + u.pn * 4 + wc;
; #pragma unroll
;         for (int ai = 0; ai < 2; ++ai) {
;             u32x4 raw[8];
; #pragma unroll
;             for (int m = 0; m < 4; ++m) { const unsigned off = lo + (unsigned)((ai * HALF + m * 16) * 64) * 2u; raw[2 * m] = *(const u32x4*)(xb + off); raw[2 * m + 1] = *(const u32x4*)(xb + off + 128); }
; #pragma unroll
;             for (int m = 0; m < 4; ++m) {
;                 const int rl = ai * HALF + m * 16; const unsigned off = lo + (unsigned)(rl * 64) * 2u;
;                 const f32x4 o0a = acc[ai][0][m][0], o0b = acc[ai][0][m][1], o1a = acc[ai][1][m][0], o1b = acc[ai][1][m][1];
;                 const f32x4 ra_ = dpp_swap1(odd ? o0a : o1a), rb_ = dpp_swap1(odd ? o0b : o1b);
;                 const f32x4 pa[2] = {odd ? ra_ : o0a, odd ? o1a : ra_}, pb[2] = {odd ? rb_ : o0b, odd ? o1b : rb_};
; #pragma unroll
;                 for (int q = 0; q < 2; ++q) {
;                     const u32x4 w0 = raw[2 * m + q];
;                     const f32x4 r0 = (f32x4){bf_lo(w0.x), bf_hi(w0.x), bf_lo(w0.y), bf_hi(w0.y)}, r1 = (f32x4){bf_lo(w0.z), bf_hi(w0.z), bf_lo(w0.w), bf_hi(w0.w)};
;                     f32x4 y0, y1;
;                     if (RESN) { const f32x2 t = tbl[rl + q]; const float mu = t.x, ra = t.y * ALPHA; y0 = (r0 - mu) * ra * g0 + b0 + pa[q]; y1 = (r1 - mu) * ra * g1 + b1 + pb[q]; }
;                     else { y0 = r0 * ALPHA + pa[q]; y1 = r1 * ALPHA + pb[q]; }
;                     { const u32x4 w = pack8f(y0, y1); *(u32x4*)(xb + off + q * 128) = w;
.LBB0_816:
	s_lshl_b64 s[4:5], s[70:71], 21
	s_add_u32 s20, s57, s4
	s_addc_u32 s21, s59, s5
	s_lshl_b32 s70, s68, 2
	s_or_b32 s4, s70, s41
	s_ashr_i32 s5, s4, 31
	v_lshl_add_u32 v72, s68, 8, v200
	v_ashrrev_i32_e32 v73, 31, v72
	s_lshl_b64 s[4:5], s[4:5], 15
	v_lshlrev_b64 v[72:73], 2, v[72:73]
	s_add_u32 s20, s20, s4
	v_lshl_add_u64 v[74:75], s[26:27], 0, v[72:73]
	s_addc_u32 s21, s21, s5
	global_load_dwordx4 v[194:197], v[74:75], off offset:16
	global_load_dwordx4 v[178:181], v[74:75], off
	global_load_dwordx4 v[214:217], v164, s[20:21]
	v_lshl_add_u64 v[72:73], s[24:25], 0, v[72:73]
	s_waitcnt lgkmcnt(0)
	global_load_dwordx4 v[76:79], v[72:73], off
	s_nop 0
	global_load_dwordx4 v[72:75], v[72:73], off offset:16
	v_cndmask_b32_e64 v136, v135, v127, s[10:11]
	v_cndmask_b32_e64 v137, v134, v126, s[10:11]
	v_cndmask_b32_e64 v138, v133, v125, s[10:11]
	v_cndmask_b32_e64 v139, v132, v124, s[10:11]
	v_mov_b32_e32 v189, 0
	v_mov_b32_e32 v193, 0
	v_mov_b32_e32 v191, 0
	v_mov_b32_e32 v209, 0
	v_cndmask_b32_e64 v140, v131, v123, s[10:11]
	v_cndmask_b32_e64 v141, v130, v122, s[10:11]
	v_cndmask_b32_e64 v142, v129, v121, s[10:11]
	v_cndmask_b32_e64 v143, v128, v120, s[10:11]
	v_mov_b32_e32 v210, 0
	v_mov_b32_e32 v212, 0
	v_mov_b32_e32 v211, 0
	v_mov_b32_e32 v213, 0
	v_mov_b32_dpp v189, v139 quad_perm:[1,0,3,2] row_mask:0xf bank_mask:0xf
	v_mov_b32_dpp v193, v138 quad_perm:[1,0,3,2] row_mask:0xf bank_mask:0xf
	v_mov_b32_dpp v191, v137 quad_perm:[1,0,3,2] row_mask:0xf bank_mask:0xf
	v_mov_b32_dpp v209, v136 quad_perm:[1,0,3,2] row_mask:0xf bank_mask:0xf
	v_mov_b32_dpp v210, v143 quad_perm:[1,0,3,2] row_mask:0xf bank_mask:0xf
	v_mov_b32_dpp v212, v142 quad_perm:[1,0,3,2] row_mask:0xf bank_mask:0xf
	v_mov_b32_dpp v211, v141 quad_perm:[1,0,3,2] row_mask:0xf bank_mask:0xf
	v_mov_b32_dpp v213, v140 quad_perm:[1,0,3,2] row_mask:0xf bank_mask:0xf
	v_add_u32_e32 v192, 0x800, v164
	v_add_u32_e32 v190, 0x1000, v164
	v_add_u32_e32 v188, 0x1800, v164
	ds_read_b64 v[218:219], v201
	v_cndmask_b32_e64 v221, v193, v133, s[10:11]
	v_cndmask_b32_e64 v220, v189, v132, s[10:11]
	v_cndmask_b32_e64 v223, v209, v135, s[10:11]
	v_cndmask_b32_e64 v222, v191, v134, s[10:11]
	v_cndmask_b32_e64 v225, v212, v129, s[10:11]
	v_cndmask_b32_e64 v224, v210, v128, s[10:11]
	v_cndmask_b32_e64 v227, v213, v131, s[10:11]
	v_cndmask_b32_e64 v226, v211, v130, s[10:11]
	global_load_dwordx4 v[152:155], v164, s[20:21] offset:128
	global_load_dwordx4 v[148:151], v192, s[20:21]
	global_load_dwordx4 v[144:147], v192, s[20:21] offset:128
	global_load_dwordx4 v[140:143], v190, s[20:21]
	global_load_dwordx4 v[136:139], v190, s[20:21] offset:128
	global_load_dwordx4 v[132:135], v188, s[20:21]
	global_load_dwordx4 v[128:131], v188, s[20:21] offset:128
	s_waitcnt lgkmcnt(0)
	v_mul_f32_e32 v208, 0x3fb504f3, v219
	v_lshl_add_u64 v[186:187], v[166:167], 0, s[72:73]
	s_ashr_i32 s71, s70, 31
	v_lshl_add_u64 v[186:187], s[70:71], 3, v[186:187]
	v_lshl_add_u64 v[186:187], v[186:187], 0, s[22:23]
	v_add_u32_e32 v246, 0x4000, v164
	v_add_u32_e32 v247, 0x4800, v164
	global_load_dwordx4 v[230:233], v246, s[20:21]
	global_load_dwordx4 v[234:237], v246, s[20:21] offset:128
	global_load_dwordx4 v[238:241], v247, s[20:21]
	global_load_dwordx4 v[242:245], v247, s[20:21] offset:128
	s_waitcnt vmcnt(0)
	v_pk_mul_f32 v[182:183], v[180:181], s[58:59] op_sel_hi:[1,0]
	v_pk_mul_f32 v[184:185], v[178:179], s[58:59] op_sel_hi:[1,0]
	v_pk_mul_f32 v[178:179], v[196:197], s[58:59] op_sel_hi:[1,0]
	v_pk_mul_f32 v[180:181], v[194:195], s[58:59] op_sel_hi:[1,0]
	v_lshlrev_b32_e32 v194, 16, v214
	v_and_b32_e32 v195, 0xffff0000, v214
	v_lshlrev_b32_e32 v196, 16, v215
	v_and_b32_e32 v197, 0xffff0000, v215
	v_lshlrev_b32_e32 v207, 16, v216
	v_and_b32_e32 v214, 0xffff0000, v216
	v_lshlrev_b32_e32 v216, 16, v217
	v_and_b32_e32 v217, 0xffff0000, v217
	v_sub_f32_e32 v195, v195, v218
	v_sub_f32_e32 v194, v194, v218
	v_sub_f32_e32 v197, v197, v218
	v_sub_f32_e32 v196, v196, v218
	v_sub_f32_e32 v215, v214, v218
	v_sub_f32_e32 v214, v207, v218
	v_sub_f32_e32 v217, v217, v218
	v_sub_f32_e32 v216, v216, v218
	v_pk_mul_f32 v[196:197], v[196:197], v[208:209] op_sel_hi:[1,0]
	v_pk_mul_f32 v[194:195], v[194:195], v[208:209] op_sel_hi:[1,0]
	v_pk_mul_f32 v[216:217], v[216:217], v[208:209] op_sel_hi:[1,0]
	v_pk_mul_f32 v[214:215], v[214:215], v[208:209] op_sel_hi:[1,0]
	v_pk_fma_f32 v[194:195], v[76:77], v[194:195], v[184:185]
	v_pk_fma_f32 v[196:197], v[78:79], v[196:197], v[182:183]
	v_pk_fma_f32 v[214:215], v[72:73], v[214:215], v[180:181]
	v_pk_fma_f32 v[216:217], v[74:75], v[216:217], v[178:179]
	v_pk_add_f32 v[196:197], v[222:223], v[196:197]
	v_pk_add_f32 v[194:195], v[220:221], v[194:195]
	v_pk_add_f32 v[218:219], v[226:227], v[216:217]
	v_pk_add_f32 v[216:217], v[224:225], v[214:215]
	v_cvt_pk_bf16_f32 v214, v194, v195
	v_cvt_pk_bf16_f32 v215, v196, v197
	v_and_b32_e32 v208, 64, v206
	v_cvt_pk_bf16_f32 v216, v216, v217
	v_cvt_pk_bf16_f32 v217, v218, v219
	v_lshlrev_b32_e32 v194, 16, v214
	v_and_b32_e32 v196, 0xffff0000, v214
	v_lshlrev_b32_e32 v218, 16, v215
	v_and_b32_e32 v220, 0xffff0000, v215
	v_lshlrev_b32_e32 v222, 16, v216
	v_and_b32_e32 v224, 0xffff0000, v216
	v_lshlrev_b32_e32 v226, 16, v217
	v_and_b32_e32 v228, 0xffff0000, v217
	v_mul_f32_e32 v195, v194, v194
	v_mul_f32_e32 v197, v196, v196
	v_mul_f32_e32 v219, v218, v218
	v_mul_f32_e32 v221, v220, v220
	v_mul_f32_e32 v223, v222, v222
	v_mul_f32_e32 v225, v224, v224
	v_mul_f32_e32 v227, v226, v226
	v_mul_f32_e32 v229, v228, v228
	v_pk_add_f32 v[194:195], v[194:195], v[196:197]
	v_pk_add_f32 v[196:197], v[218:219], v[220:221]
	v_pk_add_f32 v[218:219], v[226:227], v[228:229]
	v_pk_add_f32 v[194:195], v[194:195], v[196:197]
	v_pk_add_f32 v[196:197], v[222:223], v[224:225]
	v_xor_b32_e32 v207, 16, v206
	v_add_u32_e32 v208, 64, v208
	v_pk_add_f32 v[196:197], v[196:197], v[218:219]
	v_cmp_lt_i32_e32 vcc, v207, v208
	v_pk_add_f32 v[194:195], v[194:195], v[196:197]
	v_mov_b32_e32 v196, 0
	v_mov_b32_e32 v197, 0
	v_cndmask_b32_e32 v207, v206, v207, vcc
	v_mov_b32_dpp v196, v194 quad_perm:[1,0,3,2] row_mask:0xf bank_mask:0xf
	v_mov_b32_dpp v197, v195 quad_perm:[1,0,3,2] row_mask:0xf bank_mask:0xf
	v_lshlrev_b32_e32 v207, 2, v207
	v_pk_add_f32 v[194:195], v[194:195], v[196:197]
	ds_bpermute_b32 v196, v207, v194
	ds_bpermute_b32 v197, v207, v195
	v_xor_b32_e32 v218, 32, v206
	v_cmp_lt_i32_e32 vcc, v218, v208
	global_store_dwordx4 v164, v[214:217], s[20:21]
	s_waitcnt lgkmcnt(0)
	v_pk_add_f32 v[194:195], v[194:195], v[196:197]
	v_cndmask_b32_e32 v208, v206, v218, vcc
	v_lshlrev_b32_e32 v208, 2, v208
	ds_bpermute_b32 v196, v208, v194
	ds_bpermute_b32 v197, v208, v195
	s_and_saveexec_b64 s[52:53], s[16:17]
	s_cbranch_execz .LBB0_818
	s_waitcnt lgkmcnt(0)
	v_pk_add_f32 v[194:195], v[194:195], v[196:197]
	global_store_dwordx2 v[186:187], v[194:195], off

;     __device__ __forceinline__ void operator()(const f32x4 (&acc)[2][2][4][2], const Unit& u, int wr, int wc, int fr, int fq, const EpiCtx& X) const {
;     ...
;             for (int m = 0; m < 4; ++m) { const unsigned off = lo + (unsigned)((ai * HALF + m * 16) * 64) * 2u; raw[2 * m] = *(const u32x4*)(xb + off); raw[2 * m + 1] = *(const u32x4*)(xb + off + 128); }
; #pragma unroll
;             for (int m = 0; m < 4; ++m) {
;                 const int rl = ai * HALF + m * 16; const unsigned off = lo + (unsigned)(rl * 64) * 2u;
;                 const f32x4 o0a = acc[ai][0][m][0], o0b = acc[ai][0][m][1], o1a = acc[ai][1][m][0], o1b = acc[ai][1][m][1];
;                 const f32x4 ra_ = dpp_swap1(odd ? o0a : o1a), rb_ = dpp_swap1(odd ? o0b : o1b);
;                 const f32x4 pa[2] = {odd ? ra_ : o0a, odd ? o1a : ra_}, pb[2] = {odd ? rb_ : o0b, odd ? o1b : rb_};
; #pragma unroll
;                 for (int q = 0; q < 2; ++q) {
;                     const u32x4 w0 = raw[2 * m + q];
;                     const f32x4 r0 = (f32x4){bf_lo(w0.x), bf_hi(w0.x), bf_lo(w0.y), bf_hi(w0.y)}, r1 = (f32x4){bf_lo(w0.z), bf_hi(w0.z), bf_lo(w0.w), bf_hi(w0.w)};
;                     f32x4 y0, y1;
;                     if (RESN) { const f32x2 t = tbl[rl + q]; const float mu = t.x, ra = t.y * ALPHA; y0 = (r0 - mu) * ra * g0 + b0 + pa[q]; y1 = (r1 - mu) * ra * g1 + b1 + pb[q]; }
;                     else { y0 = r0 * ALPHA + pa[q]; y1 = r1 * ALPHA + pb[q]; }
;                     { const u32x4 w = pack8f(y0, y1); *(u32x4*)(xb + off + q * 128) = w;
;                         y0 = (f32x4){bf_lo(w.x), bf_hi(w.x), bf_lo(w.y), bf_hi(w.y)}; y1 = (f32x4){bf_lo(w.z), bf_hi(w.z), bf_lo(w.w), bf_hi(w.w)}; }
;                     float sa = ((y0[0] + y0[1]) + (y0[2] + y0[3])) + ((y1[0] + y1[1]) + (y1[2] + y1[3]));
;                     float sb = ((y0[0] * y0[0] + y0[1] * y0[1]) + (y0[2] * y0[2] + y0[3] * y0[3])) + ((y1[0] * y1[0] + y1[1] * y1[1]) + (y1[2] * y1[2] + y1[3] * y1[3]));
;                     sa += dpp_x1(sa);
;                     sb += dpp_x1(sb);
;                     sa += __shfl_xor(sa, 16); sa += __shfl_xor(sa, 32); sb += __shfl_xor(sb, 16); sb += __shfl_xor(sb, 32);
;                     if (fq == 0 && !odd) ps[(size_t)(rl + q) * 64] = (f32x2){sa, sb};
.LBB0_832:
	s_or_b64 exec, exec, s[68:69]
	v_add_u32_e32 v104, 0x4000, v164
	v_mov_b32_e32 v112, v230
	v_mov_b32_e32 v113, v231
	v_mov_b32_e32 v114, v232
	v_mov_b32_e32 v115, v233
	v_add_u32_e32 v102, 0x4800, v164
	v_add_u32_e32 v100, 0x5000, v164
	v_add_u32_e32 v164, 0x5800, v164
	v_mov_b32_e32 v96, v234
	v_mov_b32_e32 v97, v235
	v_mov_b32_e32 v98, v236
	v_mov_b32_e32 v99, v237
	v_mov_b32_e32 v92, v238
	v_mov_b32_e32 v93, v239
	v_mov_b32_e32 v94, v240
	v_mov_b32_e32 v95, v241
	v_mov_b32_e32 v88, v242
	v_mov_b32_e32 v89, v243
	v_mov_b32_e32 v90, v244
	v_mov_b32_e32 v91, v245
	global_load_dwordx4 v[84:87], v100, s[20:21]
	global_load_dwordx4 v[80:83], v100, s[20:21] offset:128
	global_load_dwordx4 v[68:71], v164, s[20:21]
	s_waitcnt lgkmcnt(0)
	global_load_dwordx4 v[64:67], v164, s[20:21] offset:128
	v_cndmask_b32_e64 v116, v62, v54, s[10:11]
	v_cndmask_b32_e64 v117, v61, v53, s[10:11]
	v_mov_b32_e32 v105, 0
	v_mov_b32_e32 v103, 0
	v_cndmask_b32_e64 v111, v63, v55, s[10:11]
	v_mov_b32_dpp v105, v117 quad_perm:[1,0,3,2] row_mask:0xf bank_mask:0xf
	v_mov_b32_dpp v103, v116 quad_perm:[1,0,3,2] row_mask:0xf bank_mask:0xf
	ds_read_b64 v[116:117], v201 offset:1024
	v_cndmask_b32_e64 v118, v60, v52, s[10:11]
	v_mov_b32_e32 v101, 0
	v_mov_b32_e32 v106, 0
	v_cndmask_b32_e64 v119, v59, v51, s[10:11]
	v_cndmask_b32_e64 v120, v58, v50, s[10:11]
	v_cndmask_b32_e64 v121, v57, v49, s[10:11]
	v_cndmask_b32_e64 v122, v56, v48, s[10:11]
	v_mov_b32_e32 v107, 0
	v_mov_b32_e32 v109, 0
	v_mov_b32_e32 v108, 0
	v_mov_b32_e32 v110, 0
	v_mov_b32_dpp v101, v118 quad_perm:[1,0,3,2] row_mask:0xf bank_mask:0xf
	v_mov_b32_dpp v106, v111 quad_perm:[1,0,3,2] row_mask:0xf bank_mask:0xf
	v_mov_b32_dpp v107, v122 quad_perm:[1,0,3,2] row_mask:0xf bank_mask:0xf
	v_mov_b32_dpp v109, v121 quad_perm:[1,0,3,2] row_mask:0xf bank_mask:0xf
	v_mov_b32_dpp v108, v120 quad_perm:[1,0,3,2] row_mask:0xf bank_mask:0xf
	v_mov_b32_dpp v110, v119 quad_perm:[1,0,3,2] row_mask:0xf bank_mask:0xf
	s_waitcnt lgkmcnt(0)
	v_mul_f32_e32 v118, 0x3fb504f3, v117
	v_cndmask_b32_e64 v61, v105, v61, s[10:11]
	v_cndmask_b32_e64 v60, v101, v60, s[10:11]
	v_cndmask_b32_e64 v63, v106, v63, s[10:11]
	v_cndmask_b32_e64 v62, v103, v62, s[10:11]
	v_cndmask_b32_e64 v57, v109, v57, s[10:11]
	v_cndmask_b32_e64 v56, v107, v56, s[10:11]
	v_cndmask_b32_e64 v59, v110, v59, s[10:11]
	v_cndmask_b32_e64 v58, v108, v58, s[10:11]
	v_lshlrev_b32_e32 v111, 16, v112
	v_and_b32_e32 v112, 0xffff0000, v112
	v_lshlrev_b32_e32 v117, 16, v113
	v_and_b32_e32 v119, 0xffff0000, v113
	v_lshlrev_b32_e32 v120, 16, v114
	v_and_b32_e32 v121, 0xffff0000, v114
	v_lshlrev_b32_e32 v122, 16, v115
	v_and_b32_e32 v123, 0xffff0000, v115
	v_sub_f32_e32 v113, v112, v116
	v_sub_f32_e32 v112, v111, v116
	v_sub_f32_e32 v115, v119, v116
	v_sub_f32_e32 v114, v117, v116
	v_sub_f32_e32 v121, v121, v116
	v_sub_f32_e32 v120, v120, v116
	v_sub_f32_e32 v117, v123, v116
	v_sub_f32_e32 v116, v122, v116
	v_pk_mul_f32 v[114:115], v[114:115], v[118:119] op_sel_hi:[1,0]
	v_pk_mul_f32 v[112:113], v[112:113], v[118:119] op_sel_hi:[1,0]
	v_pk_mul_f32 v[116:117], v[116:117], v[118:119] op_sel_hi:[1,0]
	v_pk_mul_f32 v[118:119], v[120:121], v[118:119] op_sel_hi:[1,0]
	v_pk_fma_f32 v[112:113], v[76:77], v[112:113], v[184:185]
	v_pk_fma_f32 v[114:115], v[78:79], v[114:115], v[182:183]
	v_pk_fma_f32 v[118:119], v[72:73], v[118:119], v[180:181]
	v_pk_fma_f32 v[116:117], v[74:75], v[116:117], v[178:179]
	v_pk_add_f32 v[62:63], v[62:63], v[114:115]
	v_pk_add_f32 v[60:61], v[60:61], v[112:113]
	v_pk_add_f32 v[58:59], v[58:59], v[116:117]
	v_pk_add_f32 v[56:57], v[56:57], v[118:119]
	v_cvt_pk_bf16_f32 v60, v60, v61
	v_cvt_pk_bf16_f32 v61, v62, v63
	s_nop 0
	v_cvt_pk_bf16_f32 v62, v56, v57
	v_cvt_pk_bf16_f32 v63, v58, v59
	v_lshlrev_b32_e32 v56, 16, v60
	v_and_b32_e32 v58, 0xffff0000, v60
	v_lshlrev_b32_e32 v112, 16, v61
	v_and_b32_e32 v114, 0xffff0000, v61
	v_lshlrev_b32_e32 v116, 16, v62
	v_and_b32_e32 v118, 0xffff0000, v62
	v_lshlrev_b32_e32 v120, 16, v63
	v_and_b32_e32 v122, 0xffff0000, v63
	v_mul_f32_e32 v57, v56, v56
	v_mul_f32_e32 v59, v58, v58
	v_mul_f32_e32 v113, v112, v112
	v_mul_f32_e32 v115, v114, v114
	v_mul_f32_e32 v117, v116, v116
	v_mul_f32_e32 v119, v118, v118
	v_mul_f32_e32 v121, v120, v120
	v_mul_f32_e32 v123, v122, v122
	v_pk_add_f32 v[56:57], v[56:57], v[58:59]
	v_pk_add_f32 v[58:59], v[112:113], v[114:115]
	v_pk_add_f32 v[112:113], v[120:121], v[122:123]
	v_pk_add_f32 v[56:57], v[56:57], v[58:59]
	v_pk_add_f32 v[58:59], v[116:117], v[118:119]
	global_store_dwordx4 v104, v[60:63], s[20:21]
	v_pk_add_f32 v[58:59], v[58:59], v[112:113]
	s_nop 0
	v_pk_add_f32 v[56:57], v[56:57], v[58:59]
	v_mov_b32_e32 v58, v165
	v_mov_b32_e32 v59, v165
	s_nop 0
	v_mov_b32_dpp v58, v56 quad_perm:[1,0,3,2] row_mask:0xf bank_mask:0xf
	v_mov_b32_dpp v59, v57 quad_perm:[1,0,3,2] row_mask:0xf bank_mask:0xf
	v_pk_add_f32 v[56:57], v[56:57], v[58:59]
	ds_bpermute_b32 v58, v207, v56
	ds_bpermute_b32 v59, v207, v57
	s_waitcnt lgkmcnt(0)
	v_pk_add_f32 v[56:57], v[56:57], v[58:59]
	ds_bpermute_b32 v58, v208, v56
	ds_bpermute_b32 v59, v208, v57
	s_and_saveexec_b64 s[68:69], s[16:17]
	s_cbranch_execz .LBB0_834
	s_waitcnt lgkmcnt(0)
	v_pk_add_f32 v[56:57], v[56:57], v[58:59]
	v_add_co_u32_e32 v58, vcc, 0x10000, v186
	s_nop 1
	v_addc_co_u32_e32 v59, vcc, 0, v187, vcc
	global_store_dwordx2 v[58:59], v[56:57], off
; __device__ __forceinline__ u32x4 pack8f(f32x4 a, f32x4 b) { u32x4 w; w.x = cvt_pk_bf16(a[0], a[1]); w.y = cvt_pk_bf16(a[2], a[3]); w.z = cvt_pk_bf16(b[0], b[1]); w.w = cvt_pk_bf16(b[2], b[3]); return w; }
;     __device__ __forceinline__ void operator()(const f32x4 (&acc)[2][2][4][2], const Unit& u, int wr, int wc, int fr, int fq, const EpiCtx& X) const {
;     ...
;             for (int m = 0; m < 4; ++m) {
;                 const int rl = ai * HALF + m * 16; const unsigned off = lo + (unsigned)(rl * 64) * 2u;
;                 const f32x4 o0a = acc[ai][0][m][0], o0b = acc[ai][0][m][1], o1a = acc[ai][1][m][0], o1b = acc[ai][1][m][1];
;                 const f32x4 ra_ = dpp_swap1(odd ? o0a : o1a), rb_ = dpp_swap1(odd ? o0b : o1b);
;                 const f32x4 pa[2] = {odd ? ra_ : o0a, odd ? o1a : ra_}, pb[2] = {odd ? rb_ : o0b, odd ? o1b : rb_};
; #pragma unroll
;                 for (int q = 0; q < 2; ++q) {
;                     const u32x4 w0 = raw[2 * m + q];
;                     const f32x4 r0 = (f32x4){bf_lo(w0.x), bf_hi(w0.x), bf_lo(w0.y), bf_hi(w0.y)}, r1 = (f32x4){bf_lo(w0.z), bf_hi(w0.z), bf_lo(w0.w), bf_hi(w0.w)};
;                     f32x4 y0, y1;
;                     if (RESN) { const f32x2 t = tbl[rl + q]; const float mu = t.x, ra = t.y * ALPHA; y0 = (r0 - mu) * ra * g0 + b0 + pa[q]; y1 = (r1 - mu) * ra * g1 + b1 + pb[q]; }
;                     else { y0 = r0 * ALPHA + pa[q]; y1 = r1 * ALPHA + pb[q]; }
;                     { const u32x4 w = pack8f(y0, y1); *(u32x4*)(xb + off + q * 128) = w;
;                         y0 = (f32x4){bf_lo(w.x), bf_hi(w.x), bf_lo(w.y), bf_hi(w.y)}; y1 = (f32x4){bf_lo(w.z), bf_hi(w.z), bf_lo(w.w), bf_hi(w.w)}; }
;                     float sa = ((y0[0] + y0[1]) + (y0[2] + y0[3])) + ((y1[0] + y1[1]) + (y1[2] + y1[3]));
;                     float sb = ((y0[0] * y0[0] + y0[1] * y0[1]) + (y0[2] * y0[2] + y0[3] * y0[3])) + ((y1[0] * y1[0] + y1[1] * y1[1]) + (y1[2] * y1[2] + y1[3] * y1[3]));
;                     sa += dpp_x1(sa);
;                     sb += dpp_x1(sb);
;                     sa += __shfl_xor(sa, 16); sa += __shfl_xor(sa, 32); sb += __shfl_xor(sb, 16); sb += __shfl_xor(sb, 32);
;                     if (fq == 0 && !odd) ps[(size_t)(rl + q) * 64] = (f32x2){sa, sb};
.LBB0_834:
	s_or_b64 exec, exec, s[68:69]
	ds_read_b64 v[56:57], v201 offset:1032
	s_waitcnt lgkmcnt(1)
	v_lshlrev_b32_e32 v59, 16, v96
	v_and_b32_e32 v60, 0xffff0000, v96
	v_cndmask_b32_e64 v53, v53, v105, s[10:11]
	v_cndmask_b32_e64 v52, v52, v101, s[10:11]
	s_waitcnt lgkmcnt(0)
	v_mul_f32_e32 v58, 0x3fb504f3, v57
	v_sub_f32_e32 v61, v60, v56
	v_sub_f32_e32 v60, v59, v56
	v_pk_mul_f32 v[60:61], v[60:61], v[58:59] op_sel_hi:[1,0]
	v_lshlrev_b32_e32 v62, 16, v97
	v_and_b32_e32 v63, 0xffff0000, v97
	v_lshlrev_b32_e32 v96, 16, v98
	v_and_b32_e32 v97, 0xffff0000, v98
	v_lshlrev_b32_e32 v98, 16, v99
	v_and_b32_e32 v99, 0xffff0000, v99
	v_pk_fma_f32 v[60:61], v[76:77], v[60:61], v[184:185]
	v_sub_f32_e32 v63, v63, v56
	v_sub_f32_e32 v62, v62, v56
	v_pk_add_f32 v[52:53], v[52:53], v[60:61]
	v_sub_f32_e32 v61, v97, v56
	v_sub_f32_e32 v60, v96, v56
	v_sub_f32_e32 v57, v99, v56
	v_sub_f32_e32 v56, v98, v56
	v_pk_mul_f32 v[62:63], v[62:63], v[58:59] op_sel_hi:[1,0]
	v_pk_mul_f32 v[56:57], v[56:57], v[58:59] op_sel_hi:[1,0]
	v_pk_mul_f32 v[58:59], v[60:61], v[58:59] op_sel_hi:[1,0]
	v_cndmask_b32_e64 v55, v55, v106, s[10:11]
	v_cndmask_b32_e64 v54, v54, v103, s[10:11]
	v_cndmask_b32_e64 v49, v49, v109, s[10:11]
	v_cndmask_b32_e64 v48, v48, v107, s[10:11]
	v_cndmask_b32_e64 v51, v51, v110, s[10:11]
	v_cndmask_b32_e64 v50, v50, v108, s[10:11]
	v_pk_fma_f32 v[62:63], v[78:79], v[62:63], v[182:183]
	v_pk_fma_f32 v[58:59], v[72:73], v[58:59], v[180:181]
	v_pk_fma_f32 v[56:57], v[74:75], v[56:57], v[178:179]
	v_pk_add_f32 v[54:55], v[54:55], v[62:63]
	v_pk_add_f32 v[50:51], v[50:51], v[56:57]
	v_pk_add_f32 v[48:49], v[48:49], v[58:59]
	v_cvt_pk_bf16_f32 v52, v52, v53
	v_cvt_pk_bf16_f32 v53, v54, v55
	v_mov_b32_e32 v105, v165
	v_cvt_pk_bf16_f32 v54, v48, v49
	v_cvt_pk_bf16_f32 v55, v50, v51
	v_lshlrev_b32_e32 v48, 16, v52
	v_and_b32_e32 v50, 0xffff0000, v52
	v_lshlrev_b32_e32 v56, 16, v53
	v_and_b32_e32 v58, 0xffff0000, v53
	v_lshlrev_b32_e32 v60, 16, v54
	v_and_b32_e32 v62, 0xffff0000, v54
	v_lshlrev_b32_e32 v96, 16, v55
	v_and_b32_e32 v98, 0xffff0000, v55
	v_mul_f32_e32 v49, v48, v48
	v_mul_f32_e32 v51, v50, v50
	v_mul_f32_e32 v57, v56, v56
	v_mul_f32_e32 v59, v58, v58
	v_mul_f32_e32 v61, v60, v60
	v_mul_f32_e32 v63, v62, v62
	v_mul_f32_e32 v97, v96, v96
	v_mul_f32_e32 v99, v98, v98
	v_pk_add_f32 v[48:49], v[48:49], v[50:51]
	v_pk_add_f32 v[50:51], v[56:57], v[58:59]
	v_pk_add_f32 v[56:57], v[96:97], v[98:99]
	v_pk_add_f32 v[48:49], v[48:49], v[50:51]
	v_pk_add_f32 v[50:51], v[60:61], v[62:63]
	s_nop 0
	v_pk_add_f32 v[50:51], v[50:51], v[56:57]
	v_lshl_add_u64 v[56:57], s[20:21], 0, v[104:105]
	v_pk_add_f32 v[48:49], v[48:49], v[50:51]
	v_mov_b32_e32 v50, v165
	v_mov_b32_e32 v51, v165
	global_store_dwordx4 v[56:57], v[52:55], off offset:128
	v_mov_b32_dpp v50, v48 quad_perm:[1,0,3,2] row_mask:0xf bank_mask:0xf
	v_mov_b32_dpp v51, v49 quad_perm:[1,0,3,2] row_mask:0xf bank_mask:0xf
	v_pk_add_f32 v[48:49], v[48:49], v[50:51]
	ds_bpermute_b32 v50, v207, v48
	ds_bpermute_b32 v51, v207, v49
	s_waitcnt lgkmcnt(0)
	v_pk_add_f32 v[48:49], v[48:49], v[50:51]
	ds_bpermute_b32 v50, v208, v48
	ds_bpermute_b32 v51, v208, v49
	s_and_saveexec_b64 s[68:69], s[16:17]
	s_cbranch_execz .LBB0_836
	s_waitcnt lgkmcnt(0)
	v_pk_add_f32 v[48:49], v[48:49], v[50:51]
	v_add_co_u32_e32 v50, vcc, 0x10000, v186
	s_nop 1
	v_addc_co_u32_e32 v51, vcc, 0, v187, vcc
	global_store_dwordx2 v[50:51], v[48:49], off offset:512
.LBB0_836:
	s_or_b64 exec, exec, s[68:69]
	s_waitcnt lgkmcnt(1)
	v_cndmask_b32_e64 v50, v44, v36, s[10:11]
	v_mov_b32_e32 v48, 0
	v_cndmask_b32_e64 v49, v45, v37, s[10:11]
	s_waitcnt lgkmcnt(0)
	v_cndmask_b32_e64 v51, v46, v38, s[10:11]
	v_mov_b32_dpp v48, v50 quad_perm:[1,0,3,2] row_mask:0xf bank_mask:0xf
	v_mov_b32_e32 v50, 0
	v_cndmask_b32_e64 v52, v47, v39, s[10:11]
	v_cndmask_b32_e64 v54, v40, v32, s[10:11]
	v_mov_b32_dpp v50, v49 quad_perm:[1,0,3,2] row_mask:0xf bank_mask:0xf
	v_mov_b32_e32 v49, 0
	v_cndmask_b32_e64 v53, v41, v33, s[10:11]
	v_cndmask_b32_e64 v55, v42, v34, s[10:11]
	v_mov_b32_dpp v49, v51 quad_perm:[1,0,3,2] row_mask:0xf bank_mask:0xf
	v_mov_b32_e32 v51, 0
	v_cndmask_b32_e64 v56, v43, v35, s[10:11]
	v_lshlrev_b32_e32 v59, 16, v92
	v_mov_b32_dpp v51, v52 quad_perm:[1,0,3,2] row_mask:0xf bank_mask:0xf
	v_mov_b32_e32 v52, 0
	v_and_b32_e32 v60, 0xffff0000, v92
	v_cndmask_b32_e64 v45, v50, v45, s[10:11]
	v_mov_b32_dpp v52, v54 quad_perm:[1,0,3,2] row_mask:0xf bank_mask:0xf
	v_mov_b32_e32 v54, 0
	v_cndmask_b32_e64 v44, v48, v44, s[10:11]
	v_lshlrev_b32_e32 v62, 16, v93
	v_mov_b32_dpp v54, v53 quad_perm:[1,0,3,2] row_mask:0xf bank_mask:0xf
	v_mov_b32_e32 v53, 0
	v_and_b32_e32 v63, 0xffff0000, v93
	v_lshlrev_b32_e32 v92, 16, v94
	v_mov_b32_dpp v53, v55 quad_perm:[1,0,3,2] row_mask:0xf bank_mask:0xf
	v_mov_b32_e32 v55, 0
	v_and_b32_e32 v93, 0xffff0000, v94
	v_lshlrev_b32_e32 v94, 16, v95
	v_mov_b32_dpp v55, v56 quad_perm:[1,0,3,2] row_mask:0xf bank_mask:0xf
	ds_read_b64 v[56:57], v201 offset:1152
	v_and_b32_e32 v95, 0xffff0000, v95
	v_cndmask_b32_e64 v47, v51, v47, s[10:11]
	v_cndmask_b32_e64 v46, v49, v46, s[10:11]
	v_cndmask_b32_e64 v41, v54, v41, s[10:11]
	s_waitcnt lgkmcnt(0)
; __device__ __forceinline__ u32x4 pack8f(f32x4 a, f32x4 b) { u32x4 w; w.x = cvt_pk_bf16(a[0], a[1]); w.y = cvt_pk_bf16(a[2], a[3]); w.z = cvt_pk_bf16(b[0], b[1]); w.w = cvt_pk_bf16(b[2], b[3]); return w; }
;     __device__ __forceinline__ void operator()(const f32x4 (&acc)[2][2][4][2], const Unit& u, int wr, int wc, int fr, int fq, const EpiCtx& X) const {
;     ...
;             for (int m = 0; m < 4; ++m) {
;                 const int rl = ai * HALF + m * 16; const unsigned off = lo + (unsigned)(rl * 64) * 2u;
;                 const f32x4 o0a = acc[ai][0][m][0], o0b = acc[ai][0][m][1], o1a = acc[ai][1][m][0], o1b = acc[ai][1][m][1];
;                 const f32x4 ra_ = dpp_swap1(odd ? o0a : o1a), rb_ = dpp_swap1(odd ? o0b : o1b);
;                 const f32x4 pa[2] = {odd ? ra_ : o0a, odd ? o1a : ra_}, pb[2] = {odd ? rb_ : o0b, odd ? o1b : rb_};
; #pragma unroll
;                 for (int q = 0; q < 2; ++q) {
;                     const u32x4 w0 = raw[2 * m + q];
;                     const f32x4 r0 = (f32x4){bf_lo(w0.x), bf_hi(w0.x), bf_lo(w0.y), bf_hi(w0.y)}, r1 = (f32x4){bf_lo(w0.z), bf_hi(w0.z), bf_lo(w0.w), bf_hi(w0.w)};
;                     f32x4 y0, y1;
;                     if (RESN) { const f32x2 t = tbl[rl + q]; const float mu = t.x, ra = t.y * ALPHA; y0 = (r0 - mu) * ra * g0 + b0 + pa[q]; y1 = (r1 - mu) * ra * g1 + b1 + pb[q]; }
;                     else { y0 = r0 * ALPHA + pa[q]; y1 = r1 * ALPHA + pb[q]; }
;                     { const u32x4 w = pack8f(y0, y1); *(u32x4*)(xb + off + q * 128) = w;
;                         y0 = (f32x4){bf_lo(w.x), bf_hi(w.x), bf_lo(w.y), bf_hi(w.y)}; y1 = (f32x4){bf_lo(w.z), bf_hi(w.z), bf_lo(w.w), bf_hi(w.w)}; }
;                     float sa = ((y0[0] + y0[1]) + (y0[2] + y0[3])) + ((y1[0] + y1[1]) + (y1[2] + y1[3]));
;                     float sb = ((y0[0] * y0[0] + y0[1] * y0[1]) + (y0[2] * y0[2] + y0[3] * y0[3])) + ((y1[0] * y1[0] + y1[1] * y1[1]) + (y1[2] * y1[2] + y1[3] * y1[3]));
;                     sa += dpp_x1(sa);
;                     sb += dpp_x1(sb);
;                     sa += __shfl_xor(sa, 16); sa += __shfl_xor(sa, 32); sb += __shfl_xor(sb, 16); sb += __shfl_xor(sb, 32);
;                     if (fq == 0 && !odd) ps[(size_t)(rl + q) * 64] = (f32x2){sa, sb};
	v_mul_f32_e32 v58, 0x3fb504f3, v57
	v_sub_f32_e32 v61, v60, v56
	v_sub_f32_e32 v60, v59, v56
	v_pk_mul_f32 v[60:61], v[60:61], v[58:59] op_sel_hi:[1,0]
	v_sub_f32_e32 v63, v63, v56
	v_pk_fma_f32 v[60:61], v[76:77], v[60:61], v[184:185]
	v_sub_f32_e32 v62, v62, v56
	v_pk_add_f32 v[44:45], v[44:45], v[60:61]
	v_sub_f32_e32 v61, v93, v56
	v_sub_f32_e32 v60, v92, v56
	v_sub_f32_e32 v57, v95, v56
	v_sub_f32_e32 v56, v94, v56
	v_pk_mul_f32 v[62:63], v[62:63], v[58:59] op_sel_hi:[1,0]
	v_pk_mul_f32 v[56:57], v[56:57], v[58:59] op_sel_hi:[1,0]
	v_pk_mul_f32 v[58:59], v[60:61], v[58:59] op_sel_hi:[1,0]
	v_cndmask_b32_e64 v40, v52, v40, s[10:11]
	v_cndmask_b32_e64 v43, v55, v43, s[10:11]
	v_cndmask_b32_e64 v42, v53, v42, s[10:11]
	v_pk_fma_f32 v[62:63], v[78:79], v[62:63], v[182:183]
	v_pk_fma_f32 v[58:59], v[72:73], v[58:59], v[180:181]
	v_pk_fma_f32 v[56:57], v[74:75], v[56:57], v[178:179]
	v_pk_add_f32 v[46:47], v[46:47], v[62:63]
	v_pk_add_f32 v[42:43], v[42:43], v[56:57]
	v_pk_add_f32 v[40:41], v[40:41], v[58:59]
	v_cvt_pk_bf16_f32 v56, v44, v45
	v_cvt_pk_bf16_f32 v57, v46, v47
	v_mov_b32_e32 v103, v165
	v_cvt_pk_bf16_f32 v58, v40, v41
	v_cvt_pk_bf16_f32 v59, v42, v43
	v_lshlrev_b32_e32 v40, 16, v56
	v_and_b32_e32 v42, 0xffff0000, v56
	v_lshlrev_b32_e32 v44, 16, v57
	v_and_b32_e32 v46, 0xffff0000, v57
	v_lshlrev_b32_e32 v60, 16, v58
	v_and_b32_e32 v62, 0xffff0000, v58
	v_lshlrev_b32_e32 v92, 16, v59
	v_and_b32_e32 v94, 0xffff0000, v59
	v_mul_f32_e32 v41, v40, v40
	v_mul_f32_e32 v43, v42, v42
	v_mul_f32_e32 v45, v44, v44
	v_mul_f32_e32 v47, v46, v46
	v_mul_f32_e32 v61, v60, v60
	v_mul_f32_e32 v63, v62, v62
	v_mul_f32_e32 v93, v92, v92
	v_mul_f32_e32 v95, v94, v94
	v_pk_add_f32 v[40:41], v[40:41], v[42:43]
	v_pk_add_f32 v[42:43], v[44:45], v[46:47]
	v_pk_add_f32 v[44:45], v[92:93], v[94:95]
	v_pk_add_f32 v[40:41], v[40:41], v[42:43]
	v_pk_add_f32 v[42:43], v[60:61], v[62:63]
	s_nop 0
	v_pk_add_f32 v[42:43], v[42:43], v[44:45]
	s_nop 0
	v_pk_add_f32 v[40:41], v[40:41], v[42:43]
	v_mov_b32_e32 v42, v165
	v_mov_b32_e32 v43, v165
	s_nop 0
	v_mov_b32_dpp v42, v40 quad_perm:[1,0,3,2] row_mask:0xf bank_mask:0xf
	v_mov_b32_dpp v43, v41 quad_perm:[1,0,3,2] row_mask:0xf bank_mask:0xf
	v_pk_add_f32 v[40:41], v[40:41], v[42:43]
	ds_bpermute_b32 v42, v207, v40
	ds_bpermute_b32 v43, v207, v41
	s_waitcnt lgkmcnt(0)
	v_pk_add_f32 v[42:43], v[40:41], v[42:43]
	ds_bpermute_b32 v44, v208, v42
	ds_bpermute_b32 v45, v208, v43
	v_lshl_add_u64 v[40:41], s[20:21], 0, v[102:103]
	global_store_dwordx4 v[40:41], v[56:59], off
	s_and_saveexec_b64 s[68:69], s[16:17]
	s_cbranch_execz .LBB0_838
	s_waitcnt lgkmcnt(0)
	v_pk_add_f32 v[42:43], v[42:43], v[44:45]
	v_add_co_u32_e32 v44, vcc, 0x12000, v186
	s_nop 1
	v_addc_co_u32_e32 v45, vcc, 0, v187, vcc
	global_store_dwordx2 v[44:45], v[42:43], off
.LBB0_838:
	s_or_b64 exec, exec, s[68:69]
	ds_read_b64 v[42:43], v201 offset:1160
	s_waitcnt lgkmcnt(1)
	v_lshlrev_b32_e32 v45, 16, v88
	v_and_b32_e32 v46, 0xffff0000, v88
	v_cndmask_b32_e64 v37, v37, v50, s[10:11]
	v_cndmask_b32_e64 v36, v36, v48, s[10:11]
	s_waitcnt lgkmcnt(0)
	v_mul_f32_e32 v44, 0x3fb504f3, v43
	v_sub_f32_e32 v47, v46, v42
	v_sub_f32_e32 v46, v45, v42
	v_pk_mul_f32 v[46:47], v[46:47], v[44:45] op_sel_hi:[1,0]
	v_cndmask_b32_e64 v39, v39, v51, s[10:11]
	v_cndmask_b32_e64 v38, v38, v49, s[10:11]
	v_cndmask_b32_e64 v32, v32, v52, s[10:11]
	v_cndmask_b32_e64 v34, v34, v53, s[10:11]
	v_lshlrev_b32_e32 v48, 16, v89
	v_and_b32_e32 v49, 0xffff0000, v89
	v_lshlrev_b32_e32 v50, 16, v90
	v_and_b32_e32 v51, 0xffff0000, v90
	v_lshlrev_b32_e32 v52, 16, v91
	v_and_b32_e32 v53, 0xffff0000, v91
	v_pk_fma_f32 v[46:47], v[76:77], v[46:47], v[184:185]
	v_sub_f32_e32 v49, v49, v42
	v_sub_f32_e32 v48, v48, v42
	v_pk_add_f32 v[36:37], v[36:37], v[46:47]
	v_sub_f32_e32 v47, v51, v42
	v_sub_f32_e32 v46, v50, v42
	v_sub_f32_e32 v43, v53, v42
	v_sub_f32_e32 v42, v52, v42
	v_pk_mul_f32 v[48:49], v[48:49], v[44:45] op_sel_hi:[1,0]
	v_pk_mul_f32 v[42:43], v[42:43], v[44:45] op_sel_hi:[1,0]
	v_pk_mul_f32 v[44:45], v[46:47], v[44:45] op_sel_hi:[1,0]
	v_cndmask_b32_e64 v33, v33, v54, s[10:11]
	v_cndmask_b32_e64 v35, v35, v55, s[10:11]
	v_pk_fma_f32 v[48:49], v[78:79], v[48:49], v[182:183]
	v_pk_fma_f32 v[44:45], v[72:73], v[44:45], v[180:181]
	v_pk_fma_f32 v[42:43], v[74:75], v[42:43], v[178:179]
	v_pk_add_f32 v[38:39], v[38:39], v[48:49]
	v_pk_add_f32 v[34:35], v[34:35], v[42:43]
	v_pk_add_f32 v[32:33], v[32:33], v[44:45]
	v_cvt_pk_bf16_f32 v36, v36, v37
	v_cvt_pk_bf16_f32 v37, v38, v39
	s_nop 0
	v_cvt_pk_bf16_f32 v38, v32, v33
	v_cvt_pk_bf16_f32 v39, v34, v35
	v_lshlrev_b32_e32 v32, 16, v36
	v_and_b32_e32 v34, 0xffff0000, v36
	v_lshlrev_b32_e32 v42, 16, v37
	v_and_b32_e32 v44, 0xffff0000, v37
	v_lshlrev_b32_e32 v46, 16, v38
	v_and_b32_e32 v48, 0xffff0000, v38
	v_lshlrev_b32_e32 v50, 16, v39
	v_and_b32_e32 v52, 0xffff0000, v39
	v_mul_f32_e32 v33, v32, v32
	v_mul_f32_e32 v35, v34, v34
	v_mul_f32_e32 v43, v42, v42
	v_mul_f32_e32 v45, v44, v44
	v_mul_f32_e32 v47, v46, v46
	v_mul_f32_e32 v49, v48, v48
	v_mul_f32_e32 v51, v50, v50
	v_mul_f32_e32 v53, v52, v52
	v_pk_add_f32 v[32:33], v[32:33], v[34:35]
	v_pk_add_f32 v[34:35], v[42:43], v[44:45]
	v_pk_add_f32 v[42:43], v[50:51], v[52:53]
	v_pk_add_f32 v[32:33], v[32:33], v[34:35]
	v_pk_add_f32 v[34:35], v[46:47], v[48:49]
	global_store_dwordx4 v[40:41], v[36:39], off offset:128
	v_pk_add_f32 v[34:35], v[34:35], v[42:43]
	s_nop 0
	v_pk_add_f32 v[32:33], v[32:33], v[34:35]
	v_mov_b32_e32 v34, v165
	v_mov_b32_e32 v35, v165
	s_nop 0
	v_mov_b32_dpp v34, v32 quad_perm:[1,0,3,2] row_mask:0xf bank_mask:0xf
	v_mov_b32_dpp v35, v33 quad_perm:[1,0,3,2] row_mask:0xf bank_mask:0xf
	v_pk_add_f32 v[32:33], v[32:33], v[34:35]
	ds_bpermute_b32 v34, v207, v32
	ds_bpermute_b32 v35, v207, v33
	s_waitcnt lgkmcnt(0)
	v_pk_add_f32 v[32:33], v[32:33], v[34:35]
	ds_bpermute_b32 v34, v208, v32
	ds_bpermute_b32 v35, v208, v33
	s_and_saveexec_b64 s[68:69], s[16:17]
	s_cbranch_execz .LBB0_840
	s_waitcnt lgkmcnt(0)
	v_pk_add_f32 v[32:33], v[32:33], v[34:35]
	v_add_co_u32_e32 v34, vcc, 0x12000, v186
	s_nop 1
	v_addc_co_u32_e32 v35, vcc, 0, v187, vcc
	global_store_dwordx2 v[34:35], v[32:33], off offset:512
; __device__ __forceinline__ u32x4 pack8f(f32x4 a, f32x4 b) { u32x4 w; w.x = cvt_pk_bf16(a[0], a[1]); w.y = cvt_pk_bf16(a[2], a[3]); w.z = cvt_pk_bf16(b[0], b[1]); w.w = cvt_pk_bf16(b[2], b[3]); return w; }
;     __device__ __forceinline__ void operator()(const f32x4 (&acc)[2][2][4][2], const Unit& u, int wr, int wc, int fr, int fq, const EpiCtx& X) const {
;     ...
;             for (int m = 0; m < 4; ++m) {
;                 const int rl = ai * HALF + m * 16; const unsigned off = lo + (unsigned)(rl * 64) * 2u;
;                 const f32x4 o0a = acc[ai][0][m][0], o0b = acc[ai][0][m][1], o1a = acc[ai][1][m][0], o1b = acc[ai][1][m][1];
;                 const f32x4 ra_ = dpp_swap1(odd ? o0a : o1a), rb_ = dpp_swap1(odd ? o0b : o1b);
;                 const f32x4 pa[2] = {odd ? ra_ : o0a, odd ? o1a : ra_}, pb[2] = {odd ? rb_ : o0b, odd ? o1b : rb_};
; #pragma unroll
;                 for (int q = 0; q < 2; ++q) {
;                     const u32x4 w0 = raw[2 * m + q];
;                     const f32x4 r0 = (f32x4){bf_lo(w0.x), bf_hi(w0.x), bf_lo(w0.y), bf_hi(w0.y)}, r1 = (f32x4){bf_lo(w0.z), bf_hi(w0.z), bf_lo(w0.w), bf_hi(w0.w)};
;                     f32x4 y0, y1;
;                     if (RESN) { const f32x2 t = tbl[rl + q]; const float mu = t.x, ra = t.y * ALPHA; y0 = (r0 - mu) * ra * g0 + b0 + pa[q]; y1 = (r1 - mu) * ra * g1 + b1 + pb[q]; }
;                     else { y0 = r0 * ALPHA + pa[q]; y1 = r1 * ALPHA + pb[q]; }
;                     { const u32x4 w = pack8f(y0, y1); *(u32x4*)(xb + off + q * 128) = w;
;                         y0 = (f32x4){bf_lo(w.x), bf_hi(w.x), bf_lo(w.y), bf_hi(w.y)}; y1 = (f32x4){bf_lo(w.z), bf_hi(w.z), bf_lo(w.w), bf_hi(w.w)}; }
;                     float sa = ((y0[0] + y0[1]) + (y0[2] + y0[3])) + ((y1[0] + y1[1]) + (y1[2] + y1[3]));
;                     float sb = ((y0[0] * y0[0] + y0[1] * y0[1]) + (y0[2] * y0[2] + y0[3] * y0[3])) + ((y1[0] * y1[0] + y1[1] * y1[1]) + (y1[2] * y1[2] + y1[3] * y1[3]));
;                     sa += dpp_x1(sa);
;                     sb += dpp_x1(sb);
;                     sa += __shfl_xor(sa, 16); sa += __shfl_xor(sa, 32); sb += __shfl_xor(sb, 16); sb += __shfl_xor(sb, 32);
;                     if (fq == 0 && !odd) ps[(size_t)(rl + q) * 64] = (f32x2){sa, sb};
.LBB0_840:
	s_or_b64 exec, exec, s[68:69]
	s_waitcnt lgkmcnt(1)
	v_cndmask_b32_e64 v34, v28, v20, s[10:11]
	v_mov_b32_e32 v32, 0
	v_cndmask_b32_e64 v33, v29, v21, s[10:11]
	s_waitcnt lgkmcnt(0)
	v_cndmask_b32_e64 v35, v30, v22, s[10:11]
	v_mov_b32_dpp v32, v34 quad_perm:[1,0,3,2] row_mask:0xf bank_mask:0xf
	v_mov_b32_e32 v34, 0
	v_cndmask_b32_e64 v36, v31, v23, s[10:11]
	v_cndmask_b32_e64 v38, v24, v16, s[10:11]
	v_mov_b32_dpp v34, v33 quad_perm:[1,0,3,2] row_mask:0xf bank_mask:0xf
	v_mov_b32_e32 v33, 0
	v_cndmask_b32_e64 v37, v25, v17, s[10:11]
	v_cndmask_b32_e64 v39, v26, v18, s[10:11]
	v_mov_b32_dpp v33, v35 quad_perm:[1,0,3,2] row_mask:0xf bank_mask:0xf
	v_mov_b32_e32 v35, 0
	v_cndmask_b32_e64 v40, v27, v19, s[10:11]
	s_waitcnt vmcnt(11)
	v_lshlrev_b32_e32 v43, 16, v84
	v_mov_b32_dpp v35, v36 quad_perm:[1,0,3,2] row_mask:0xf bank_mask:0xf
	v_mov_b32_e32 v36, 0
	v_and_b32_e32 v44, 0xffff0000, v84
	v_cndmask_b32_e64 v29, v34, v29, s[10:11]
	v_mov_b32_dpp v36, v38 quad_perm:[1,0,3,2] row_mask:0xf bank_mask:0xf
	v_mov_b32_e32 v38, 0
	v_cndmask_b32_e64 v28, v32, v28, s[10:11]
	v_lshlrev_b32_e32 v46, 16, v85
	v_mov_b32_dpp v38, v37 quad_perm:[1,0,3,2] row_mask:0xf bank_mask:0xf
	v_mov_b32_e32 v37, 0
	v_and_b32_e32 v47, 0xffff0000, v85
	v_lshlrev_b32_e32 v48, 16, v86
	v_mov_b32_dpp v37, v39 quad_perm:[1,0,3,2] row_mask:0xf bank_mask:0xf
	v_mov_b32_e32 v39, 0
	v_and_b32_e32 v49, 0xffff0000, v86
	v_lshlrev_b32_e32 v50, 16, v87
	v_mov_b32_dpp v39, v40 quad_perm:[1,0,3,2] row_mask:0xf bank_mask:0xf
	ds_read_b64 v[40:41], v201 offset:1280
	v_and_b32_e32 v51, 0xffff0000, v87
	v_cndmask_b32_e64 v31, v35, v31, s[10:11]
	v_cndmask_b32_e64 v30, v33, v30, s[10:11]
	v_cndmask_b32_e64 v25, v38, v25, s[10:11]
	s_waitcnt lgkmcnt(0)
	v_mul_f32_e32 v42, 0x3fb504f3, v41
	v_sub_f32_e32 v45, v44, v40
	v_sub_f32_e32 v44, v43, v40
	v_pk_mul_f32 v[44:45], v[44:45], v[42:43] op_sel_hi:[1,0]
	v_sub_f32_e32 v47, v47, v40
	v_pk_fma_f32 v[44:45], v[76:77], v[44:45], v[184:185]
	v_sub_f32_e32 v46, v46, v40
	v_pk_add_f32 v[28:29], v[28:29], v[44:45]
	v_sub_f32_e32 v45, v49, v40
	v_sub_f32_e32 v44, v48, v40
	v_sub_f32_e32 v41, v51, v40
	v_sub_f32_e32 v40, v50, v40
	v_pk_mul_f32 v[46:47], v[46:47], v[42:43] op_sel_hi:[1,0]
	v_pk_mul_f32 v[40:41], v[40:41], v[42:43] op_sel_hi:[1,0]
	v_pk_mul_f32 v[42:43], v[44:45], v[42:43] op_sel_hi:[1,0]
	v_cndmask_b32_e64 v24, v36, v24, s[10:11]
	v_cndmask_b32_e64 v27, v39, v27, s[10:11]
	v_cndmask_b32_e64 v26, v37, v26, s[10:11]
	v_pk_fma_f32 v[46:47], v[78:79], v[46:47], v[182:183]
	v_pk_fma_f32 v[42:43], v[72:73], v[42:43], v[180:181]
	v_pk_fma_f32 v[40:41], v[74:75], v[40:41], v[178:179]
	v_pk_add_f32 v[30:31], v[30:31], v[46:47]
	v_pk_add_f32 v[26:27], v[26:27], v[40:41]
	v_pk_add_f32 v[24:25], v[24:25], v[42:43]
	v_cvt_pk_bf16_f32 v40, v28, v29
	v_cvt_pk_bf16_f32 v41, v30, v31
	v_mov_b32_e32 v101, v165
	v_cvt_pk_bf16_f32 v42, v24, v25
	v_cvt_pk_bf16_f32 v43, v26, v27
	v_lshlrev_b32_e32 v24, 16, v40
	v_and_b32_e32 v26, 0xffff0000, v40
	v_lshlrev_b32_e32 v28, 16, v41
	v_and_b32_e32 v30, 0xffff0000, v41
	v_lshlrev_b32_e32 v44, 16, v42
	v_and_b32_e32 v46, 0xffff0000, v42
	v_lshlrev_b32_e32 v48, 16, v43
	v_and_b32_e32 v50, 0xffff0000, v43
	v_mul_f32_e32 v25, v24, v24
	v_mul_f32_e32 v27, v26, v26
	v_mul_f32_e32 v29, v28, v28
	v_mul_f32_e32 v31, v30, v30
	v_mul_f32_e32 v45, v44, v44
	v_mul_f32_e32 v47, v46, v46
	v_mul_f32_e32 v49, v48, v48
	v_mul_f32_e32 v51, v50, v50
	v_pk_add_f32 v[24:25], v[24:25], v[26:27]
	v_pk_add_f32 v[26:27], v[28:29], v[30:31]
	v_pk_add_f32 v[28:29], v[48:49], v[50:51]
	v_pk_add_f32 v[24:25], v[24:25], v[26:27]
	v_pk_add_f32 v[26:27], v[44:45], v[46:47]
	s_nop 0
	v_pk_add_f32 v[26:27], v[26:27], v[28:29]
	s_nop 0
	v_pk_add_f32 v[24:25], v[24:25], v[26:27]
	v_mov_b32_e32 v26, v165
	v_mov_b32_e32 v27, v165
	s_nop 0
	v_mov_b32_dpp v26, v24 quad_perm:[1,0,3,2] row_mask:0xf bank_mask:0xf
	v_mov_b32_dpp v27, v25 quad_perm:[1,0,3,2] row_mask:0xf bank_mask:0xf
	v_pk_add_f32 v[24:25], v[24:25], v[26:27]
	ds_bpermute_b32 v26, v207, v24
	ds_bpermute_b32 v27, v207, v25
	s_waitcnt lgkmcnt(0)
	v_pk_add_f32 v[26:27], v[24:25], v[26:27]
	ds_bpermute_b32 v28, v208, v26
	ds_bpermute_b32 v29, v208, v27
	v_lshl_add_u64 v[24:25], s[20:21], 0, v[100:101]
	global_store_dwordx4 v[24:25], v[40:43], off
	s_and_saveexec_b64 s[68:69], s[16:17]
	s_cbranch_execz .LBB0_842
	s_waitcnt lgkmcnt(0)
	v_pk_add_f32 v[26:27], v[26:27], v[28:29]
	v_add_co_u32_e32 v28, vcc, 0x14000, v186
	s_nop 1
	v_addc_co_u32_e32 v29, vcc, 0, v187, vcc
	global_store_dwordx2 v[28:29], v[26:27], off
; __device__ __forceinline__ u32x4 pack8f(f32x4 a, f32x4 b) { u32x4 w; w.x = cvt_pk_bf16(a[0], a[1]); w.y = cvt_pk_bf16(a[2], a[3]); w.z = cvt_pk_bf16(b[0], b[1]); w.w = cvt_pk_bf16(b[2], b[3]); return w; }
;     __device__ __forceinline__ void operator()(const f32x4 (&acc)[2][2][4][2], const Unit& u, int wr, int wc, int fr, int fq, const EpiCtx& X) const {
;     ...
;             for (int m = 0; m < 4; ++m) {
;                 const int rl = ai * HALF + m * 16; const unsigned off = lo + (unsigned)(rl * 64) * 2u;
;                 const f32x4 o0a = acc[ai][0][m][0], o0b = acc[ai][0][m][1], o1a = acc[ai][1][m][0], o1b = acc[ai][1][m][1];
;                 const f32x4 ra_ = dpp_swap1(odd ? o0a : o1a), rb_ = dpp_swap1(odd ? o0b : o1b);
;                 const f32x4 pa[2] = {odd ? ra_ : o0a, odd ? o1a : ra_}, pb[2] = {odd ? rb_ : o0b, odd ? o1b : rb_};
; #pragma unroll
;                 for (int q = 0; q < 2; ++q) {
;                     const u32x4 w0 = raw[2 * m + q];
;                     const f32x4 r0 = (f32x4){bf_lo(w0.x), bf_hi(w0.x), bf_lo(w0.y), bf_hi(w0.y)}, r1 = (f32x4){bf_lo(w0.z), bf_hi(w0.z), bf_lo(w0.w), bf_hi(w0.w)};
;                     f32x4 y0, y1;
;                     if (RESN) { const f32x2 t = tbl[rl + q]; const float mu = t.x, ra = t.y * ALPHA; y0 = (r0 - mu) * ra * g0 + b0 + pa[q]; y1 = (r1 - mu) * ra * g1 + b1 + pb[q]; }
;                     else { y0 = r0 * ALPHA + pa[q]; y1 = r1 * ALPHA + pb[q]; }
;                     { const u32x4 w = pack8f(y0, y1); *(u32x4*)(xb + off + q * 128) = w;
;                         y0 = (f32x4){bf_lo(w.x), bf_hi(w.x), bf_lo(w.y), bf_hi(w.y)}; y1 = (f32x4){bf_lo(w.z), bf_hi(w.z), bf_lo(w.w), bf_hi(w.w)}; }
;                     float sa = ((y0[0] + y0[1]) + (y0[2] + y0[3])) + ((y1[0] + y1[1]) + (y1[2] + y1[3]));
;                     float sb = ((y0[0] * y0[0] + y0[1] * y0[1]) + (y0[2] * y0[2] + y0[3] * y0[3])) + ((y1[0] * y1[0] + y1[1] * y1[1]) + (y1[2] * y1[2] + y1[3] * y1[3]));
;                     sa += dpp_x1(sa);
;                     sb += dpp_x1(sb);
;                     sa += __shfl_xor(sa, 16); sa += __shfl_xor(sa, 32); sb += __shfl_xor(sb, 16); sb += __shfl_xor(sb, 32);
;                     if (fq == 0 && !odd) ps[(size_t)(rl + q) * 64] = (f32x2){sa, sb};
.LBB0_842:
	s_or_b64 exec, exec, s[68:69]
	ds_read_b64 v[26:27], v201 offset:1288
	s_waitcnt vmcnt(12) lgkmcnt(1)
	v_lshlrev_b32_e32 v29, 16, v80
	v_and_b32_e32 v30, 0xffff0000, v80
	v_cndmask_b32_e64 v21, v21, v34, s[10:11]
	v_cndmask_b32_e64 v20, v20, v32, s[10:11]
	s_waitcnt lgkmcnt(0)
	v_mul_f32_e32 v28, 0x3fb504f3, v27
	v_sub_f32_e32 v31, v30, v26
	v_sub_f32_e32 v30, v29, v26
	v_pk_mul_f32 v[30:31], v[30:31], v[28:29] op_sel_hi:[1,0]
	v_cndmask_b32_e64 v23, v23, v35, s[10:11]
	v_cndmask_b32_e64 v22, v22, v33, s[10:11]
	v_cndmask_b32_e64 v16, v16, v36, s[10:11]
	v_cndmask_b32_e64 v18, v18, v37, s[10:11]
	v_lshlrev_b32_e32 v32, 16, v81
	v_and_b32_e32 v33, 0xffff0000, v81
	v_lshlrev_b32_e32 v34, 16, v82
	v_and_b32_e32 v35, 0xffff0000, v82
	v_lshlrev_b32_e32 v36, 16, v83
	v_and_b32_e32 v37, 0xffff0000, v83
	v_pk_fma_f32 v[30:31], v[76:77], v[30:31], v[184:185]
	v_sub_f32_e32 v33, v33, v26
	v_sub_f32_e32 v32, v32, v26
	v_pk_add_f32 v[20:21], v[20:21], v[30:31]
	v_sub_f32_e32 v31, v35, v26
	v_sub_f32_e32 v30, v34, v26
	v_sub_f32_e32 v27, v37, v26
	v_sub_f32_e32 v26, v36, v26
	v_pk_mul_f32 v[32:33], v[32:33], v[28:29] op_sel_hi:[1,0]
	v_pk_mul_f32 v[26:27], v[26:27], v[28:29] op_sel_hi:[1,0]
	v_pk_mul_f32 v[28:29], v[30:31], v[28:29] op_sel_hi:[1,0]
	v_cndmask_b32_e64 v17, v17, v38, s[10:11]
	v_cndmask_b32_e64 v19, v19, v39, s[10:11]
	v_pk_fma_f32 v[32:33], v[78:79], v[32:33], v[182:183]
	v_pk_fma_f32 v[28:29], v[72:73], v[28:29], v[180:181]
	v_pk_fma_f32 v[26:27], v[74:75], v[26:27], v[178:179]
	v_pk_add_f32 v[22:23], v[22:23], v[32:33]
	v_pk_add_f32 v[18:19], v[18:19], v[26:27]
	v_pk_add_f32 v[16:17], v[16:17], v[28:29]
	v_cvt_pk_bf16_f32 v20, v20, v21
	v_cvt_pk_bf16_f32 v21, v22, v23
	s_nop 0
	v_cvt_pk_bf16_f32 v22, v16, v17
	v_cvt_pk_bf16_f32 v23, v18, v19
	v_lshlrev_b32_e32 v16, 16, v20
	v_and_b32_e32 v18, 0xffff0000, v20
	v_lshlrev_b32_e32 v26, 16, v21
	v_and_b32_e32 v28, 0xffff0000, v21
	v_lshlrev_b32_e32 v30, 16, v22
	v_and_b32_e32 v32, 0xffff0000, v22
	v_lshlrev_b32_e32 v34, 16, v23
	v_and_b32_e32 v36, 0xffff0000, v23
	v_mul_f32_e32 v17, v16, v16
	v_mul_f32_e32 v19, v18, v18
	v_mul_f32_e32 v27, v26, v26
	v_mul_f32_e32 v29, v28, v28
	v_mul_f32_e32 v31, v30, v30
	v_mul_f32_e32 v33, v32, v32
	v_mul_f32_e32 v35, v34, v34
	v_mul_f32_e32 v37, v36, v36
	v_pk_add_f32 v[16:17], v[16:17], v[18:19]
	v_pk_add_f32 v[18:19], v[26:27], v[28:29]
	v_pk_add_f32 v[26:27], v[34:35], v[36:37]
	v_pk_add_f32 v[16:17], v[16:17], v[18:19]
	v_pk_add_f32 v[18:19], v[30:31], v[32:33]
	global_store_dwordx4 v[24:25], v[20:23], off offset:128
	v_pk_add_f32 v[18:19], v[18:19], v[26:27]
	s_nop 0
	v_pk_add_f32 v[16:17], v[16:17], v[18:19]
	v_mov_b32_e32 v18, v165
	v_mov_b32_e32 v19, v165
	s_nop 0
	v_mov_b32_dpp v18, v16 quad_perm:[1,0,3,2] row_mask:0xf bank_mask:0xf
	v_mov_b32_dpp v19, v17 quad_perm:[1,0,3,2] row_mask:0xf bank_mask:0xf
	v_pk_add_f32 v[16:17], v[16:17], v[18:19]
	ds_bpermute_b32 v18, v207, v16
	ds_bpermute_b32 v19, v207, v17
	s_waitcnt lgkmcnt(0)
	v_pk_add_f32 v[16:17], v[16:17], v[18:19]
	ds_bpermute_b32 v18, v208, v16
	ds_bpermute_b32 v19, v208, v17
	s_and_saveexec_b64 s[68:69], s[16:17]
	s_cbranch_execz .LBB0_844
	s_waitcnt lgkmcnt(0)
	v_pk_add_f32 v[16:17], v[16:17], v[18:19]
	v_add_co_u32_e32 v18, vcc, 0x14000, v186
	s_nop 1
	v_addc_co_u32_e32 v19, vcc, 0, v187, vcc
	global_store_dwordx2 v[18:19], v[16:17], off offset:512
.LBB0_844:
	s_or_b64 exec, exec, s[68:69]
	s_waitcnt lgkmcnt(1)
	v_cndmask_b32_e64 v18, v12, v4, s[10:11]
	v_mov_b32_e32 v16, 0
	v_cndmask_b32_e64 v17, v13, v5, s[10:11]
	s_waitcnt lgkmcnt(0)
	v_cndmask_b32_e64 v19, v14, v6, s[10:11]
	v_mov_b32_dpp v16, v18 quad_perm:[1,0,3,2] row_mask:0xf bank_mask:0xf
	v_mov_b32_e32 v18, 0
	v_cndmask_b32_e64 v20, v15, v7, s[10:11]
	v_cndmask_b32_e64 v22, v8, v0, s[10:11]
	v_mov_b32_dpp v18, v17 quad_perm:[1,0,3,2] row_mask:0xf bank_mask:0xf
	v_mov_b32_e32 v17, 0
	v_cndmask_b32_e64 v21, v9, v1, s[10:11]
	v_cndmask_b32_e64 v23, v10, v2, s[10:11]
	v_mov_b32_dpp v17, v19 quad_perm:[1,0,3,2] row_mask:0xf bank_mask:0xf
	v_mov_b32_e32 v19, 0
	v_cndmask_b32_e64 v24, v11, v3, s[10:11]
	s_waitcnt vmcnt(13)
	v_lshlrev_b32_e32 v27, 16, v68
	v_mov_b32_dpp v19, v20 quad_perm:[1,0,3,2] row_mask:0xf bank_mask:0xf
	v_mov_b32_e32 v20, 0
	v_and_b32_e32 v28, 0xffff0000, v68
	v_cndmask_b32_e64 v13, v18, v13, s[10:11]
	v_mov_b32_dpp v20, v22 quad_perm:[1,0,3,2] row_mask:0xf bank_mask:0xf
	v_mov_b32_e32 v22, 0
	v_cndmask_b32_e64 v12, v16, v12, s[10:11]
	v_lshlrev_b32_e32 v30, 16, v69
	v_mov_b32_dpp v22, v21 quad_perm:[1,0,3,2] row_mask:0xf bank_mask:0xf
	v_mov_b32_e32 v21, 0
	v_and_b32_e32 v31, 0xffff0000, v69
	v_lshlrev_b32_e32 v32, 16, v70
	v_mov_b32_dpp v21, v23 quad_perm:[1,0,3,2] row_mask:0xf bank_mask:0xf
	v_mov_b32_e32 v23, 0
	v_and_b32_e32 v33, 0xffff0000, v70
	v_lshlrev_b32_e32 v34, 16, v71
	v_mov_b32_dpp v23, v24 quad_perm:[1,0,3,2] row_mask:0xf bank_mask:0xf
	ds_read_b64 v[24:25], v201 offset:1408
	v_and_b32_e32 v35, 0xffff0000, v71
	v_cndmask_b32_e64 v15, v19, v15, s[10:11]
	v_cndmask_b32_e64 v14, v17, v14, s[10:11]
	v_cndmask_b32_e64 v9, v22, v9, s[10:11]
	s_waitcnt lgkmcnt(0)
; __device__ __forceinline__ u32x4 pack8f(f32x4 a, f32x4 b) { u32x4 w; w.x = cvt_pk_bf16(a[0], a[1]); w.y = cvt_pk_bf16(a[2], a[3]); w.z = cvt_pk_bf16(b[0], b[1]); w.w = cvt_pk_bf16(b[2], b[3]); return w; }
;     __device__ __forceinline__ void operator()(const f32x4 (&acc)[2][2][4][2], const Unit& u, int wr, int wc, int fr, int fq, const EpiCtx& X) const {
;     ...
;             for (int m = 0; m < 4; ++m) {
;                 const int rl = ai * HALF + m * 16; const unsigned off = lo + (unsigned)(rl * 64) * 2u;
;                 const f32x4 o0a = acc[ai][0][m][0], o0b = acc[ai][0][m][1], o1a = acc[ai][1][m][0], o1b = acc[ai][1][m][1];
;                 const f32x4 ra_ = dpp_swap1(odd ? o0a : o1a), rb_ = dpp_swap1(odd ? o0b : o1b);
;                 const f32x4 pa[2] = {odd ? ra_ : o0a, odd ? o1a : ra_}, pb[2] = {odd ? rb_ : o0b, odd ? o1b : rb_};
; #pragma unroll
;                 for (int q = 0; q < 2; ++q) {
;                     const u32x4 w0 = raw[2 * m + q];
;                     const f32x4 r0 = (f32x4){bf_lo(w0.x), bf_hi(w0.x), bf_lo(w0.y), bf_hi(w0.y)}, r1 = (f32x4){bf_lo(w0.z), bf_hi(w0.z), bf_lo(w0.w), bf_hi(w0.w)};
;                     f32x4 y0, y1;
;                     if (RESN) { const f32x2 t = tbl[rl + q]; const float mu = t.x, ra = t.y * ALPHA; y0 = (r0 - mu) * ra * g0 + b0 + pa[q]; y1 = (r1 - mu) * ra * g1 + b1 + pb[q]; }
;                     else { y0 = r0 * ALPHA + pa[q]; y1 = r1 * ALPHA + pb[q]; }
;                     { const u32x4 w = pack8f(y0, y1); *(u32x4*)(xb + off + q * 128) = w;
;                         y0 = (f32x4){bf_lo(w.x), bf_hi(w.x), bf_lo(w.y), bf_hi(w.y)}; y1 = (f32x4){bf_lo(w.z), bf_hi(w.z), bf_lo(w.w), bf_hi(w.w)}; }
;                     float sa = ((y0[0] + y0[1]) + (y0[2] + y0[3])) + ((y1[0] + y1[1]) + (y1[2] + y1[3]));
;                     float sb = ((y0[0] * y0[0] + y0[1] * y0[1]) + (y0[2] * y0[2] + y0[3] * y0[3])) + ((y1[0] * y1[0] + y1[1] * y1[1]) + (y1[2] * y1[2] + y1[3] * y1[3]));
;                     sa += dpp_x1(sa);
;                     sb += dpp_x1(sb);
;                     sa += __shfl_xor(sa, 16); sa += __shfl_xor(sa, 32); sb += __shfl_xor(sb, 16); sb += __shfl_xor(sb, 32);
;                     if (fq == 0 && !odd) ps[(size_t)(rl + q) * 64] = (f32x2){sa, sb};
	v_mul_f32_e32 v26, 0x3fb504f3, v25
	v_sub_f32_e32 v29, v28, v24
	v_sub_f32_e32 v28, v27, v24
	v_pk_mul_f32 v[28:29], v[28:29], v[26:27] op_sel_hi:[1,0]
	v_sub_f32_e32 v31, v31, v24
	v_pk_fma_f32 v[28:29], v[76:77], v[28:29], v[184:185]
	v_sub_f32_e32 v30, v30, v24
	v_pk_add_f32 v[12:13], v[12:13], v[28:29]
	v_sub_f32_e32 v29, v33, v24
	v_sub_f32_e32 v28, v32, v24
	v_sub_f32_e32 v25, v35, v24
	v_sub_f32_e32 v24, v34, v24
	v_pk_mul_f32 v[30:31], v[30:31], v[26:27] op_sel_hi:[1,0]
	v_pk_mul_f32 v[24:25], v[24:25], v[26:27] op_sel_hi:[1,0]
	v_pk_mul_f32 v[26:27], v[28:29], v[26:27] op_sel_hi:[1,0]
	v_cndmask_b32_e64 v8, v20, v8, s[10:11]
	v_cndmask_b32_e64 v11, v23, v11, s[10:11]
	v_cndmask_b32_e64 v10, v21, v10, s[10:11]
	v_pk_fma_f32 v[30:31], v[78:79], v[30:31], v[182:183]
	v_pk_fma_f32 v[26:27], v[72:73], v[26:27], v[180:181]
	v_pk_fma_f32 v[24:25], v[74:75], v[24:25], v[178:179]
	v_pk_add_f32 v[14:15], v[14:15], v[30:31]
	v_pk_add_f32 v[10:11], v[10:11], v[24:25]
	v_pk_add_f32 v[8:9], v[8:9], v[26:27]
	v_cvt_pk_bf16_f32 v24, v12, v13
	v_cvt_pk_bf16_f32 v25, v14, v15
	s_nop 0
	v_cvt_pk_bf16_f32 v26, v8, v9
	v_cvt_pk_bf16_f32 v27, v10, v11
	v_lshlrev_b32_e32 v8, 16, v24
	v_and_b32_e32 v10, 0xffff0000, v24
	v_lshlrev_b32_e32 v12, 16, v25
	v_and_b32_e32 v14, 0xffff0000, v25
	v_lshlrev_b32_e32 v28, 16, v26
	v_and_b32_e32 v30, 0xffff0000, v26
	v_lshlrev_b32_e32 v32, 16, v27
	v_and_b32_e32 v34, 0xffff0000, v27
	v_mul_f32_e32 v9, v8, v8
	v_mul_f32_e32 v11, v10, v10
	v_mul_f32_e32 v13, v12, v12
	v_mul_f32_e32 v15, v14, v14
	v_mul_f32_e32 v29, v28, v28
	v_mul_f32_e32 v31, v30, v30
	v_mul_f32_e32 v33, v32, v32
	v_mul_f32_e32 v35, v34, v34
	v_pk_add_f32 v[8:9], v[8:9], v[10:11]
	v_pk_add_f32 v[10:11], v[12:13], v[14:15]
	v_pk_add_f32 v[12:13], v[32:33], v[34:35]
	v_pk_add_f32 v[8:9], v[8:9], v[10:11]
	v_pk_add_f32 v[10:11], v[28:29], v[30:31]
	s_nop 0
	v_pk_add_f32 v[10:11], v[10:11], v[12:13]
	s_nop 0
	v_pk_add_f32 v[8:9], v[8:9], v[10:11]
	v_mov_b32_e32 v10, v165
	v_mov_b32_e32 v11, v165
	s_nop 0
	v_mov_b32_dpp v10, v8 quad_perm:[1,0,3,2] row_mask:0xf bank_mask:0xf
	v_mov_b32_dpp v11, v9 quad_perm:[1,0,3,2] row_mask:0xf bank_mask:0xf
	v_pk_add_f32 v[8:9], v[8:9], v[10:11]
	ds_bpermute_b32 v10, v207, v8
	ds_bpermute_b32 v11, v207, v9
	s_waitcnt lgkmcnt(0)
	v_pk_add_f32 v[10:11], v[8:9], v[10:11]
	ds_bpermute_b32 v12, v208, v10
	ds_bpermute_b32 v13, v208, v11
	v_lshl_add_u64 v[8:9], s[20:21], 0, v[164:165]
	global_store_dwordx4 v[8:9], v[24:27], off
	s_and_saveexec_b64 s[20:21], s[16:17]
	s_cbranch_execz .LBB0_846
	s_waitcnt lgkmcnt(0)
	v_pk_add_f32 v[10:11], v[10:11], v[12:13]
	v_add_co_u32_e32 v12, vcc, 0x16000, v186
	s_nop 1
	v_addc_co_u32_e32 v13, vcc, 0, v187, vcc
	global_store_dwordx2 v[12:13], v[10:11], off
.LBB0_846:
	s_or_b64 exec, exec, s[20:21]
	ds_read_b64 v[10:11], v201 offset:1416
	s_waitcnt vmcnt(14) lgkmcnt(1)
	v_lshlrev_b32_e32 v13, 16, v64
	v_and_b32_e32 v14, 0xffff0000, v64
	v_cndmask_b32_e64 v5, v5, v18, s[10:11]
	v_cndmask_b32_e64 v4, v4, v16, s[10:11]
	s_waitcnt lgkmcnt(0)
	v_mul_f32_e32 v12, 0x3fb504f3, v11
	v_sub_f32_e32 v15, v14, v10
	v_sub_f32_e32 v14, v13, v10
	v_pk_mul_f32 v[14:15], v[14:15], v[12:13] op_sel_hi:[1,0]
	v_cndmask_b32_e64 v7, v7, v19, s[10:11]
	v_cndmask_b32_e64 v6, v6, v17, s[10:11]
	v_cndmask_b32_e64 v0, v0, v20, s[10:11]
	v_cndmask_b32_e64 v2, v2, v21, s[10:11]
	v_lshlrev_b32_e32 v16, 16, v65
	v_and_b32_e32 v17, 0xffff0000, v65
	v_lshlrev_b32_e32 v18, 16, v66
	v_and_b32_e32 v19, 0xffff0000, v66
	v_lshlrev_b32_e32 v20, 16, v67
	v_and_b32_e32 v21, 0xffff0000, v67
	v_pk_fma_f32 v[14:15], v[76:77], v[14:15], v[184:185]
	v_sub_f32_e32 v17, v17, v10
	v_sub_f32_e32 v16, v16, v10
	v_pk_add_f32 v[4:5], v[4:5], v[14:15]
	v_sub_f32_e32 v15, v19, v10
	v_sub_f32_e32 v14, v18, v10
	v_sub_f32_e32 v11, v21, v10
	v_sub_f32_e32 v10, v20, v10
	v_pk_mul_f32 v[16:17], v[16:17], v[12:13] op_sel_hi:[1,0]
	v_pk_mul_f32 v[10:11], v[10:11], v[12:13] op_sel_hi:[1,0]
	v_pk_mul_f32 v[12:13], v[14:15], v[12:13] op_sel_hi:[1,0]
	v_cndmask_b32_e64 v1, v1, v22, s[10:11]
	v_cndmask_b32_e64 v3, v3, v23, s[10:11]
	v_pk_fma_f32 v[16:17], v[78:79], v[16:17], v[182:183]
	v_pk_fma_f32 v[12:13], v[72:73], v[12:13], v[180:181]
	v_pk_fma_f32 v[10:11], v[74:75], v[10:11], v[178:179]
	v_pk_add_f32 v[6:7], v[6:7], v[16:17]
	v_pk_add_f32 v[2:3], v[2:3], v[10:11]
	v_pk_add_f32 v[0:1], v[0:1], v[12:13]
	v_cvt_pk_bf16_f32 v4, v4, v5
	v_cvt_pk_bf16_f32 v5, v6, v7
	s_nop 0
	v_cvt_pk_bf16_f32 v6, v0, v1
	v_cvt_pk_bf16_f32 v7, v2, v3
	v_lshlrev_b32_e32 v0, 16, v4
	v_and_b32_e32 v2, 0xffff0000, v4
	v_lshlrev_b32_e32 v10, 16, v5
	v_and_b32_e32 v12, 0xffff0000, v5
	v_lshlrev_b32_e32 v14, 16, v6
	v_and_b32_e32 v16, 0xffff0000, v6
	v_lshlrev_b32_e32 v18, 16, v7
	v_and_b32_e32 v20, 0xffff0000, v7
	v_mul_f32_e32 v1, v0, v0
	v_mul_f32_e32 v3, v2, v2
	v_mul_f32_e32 v11, v10, v10
	v_mul_f32_e32 v13, v12, v12
	v_mul_f32_e32 v15, v14, v14
	v_mul_f32_e32 v17, v16, v16
	v_mul_f32_e32 v19, v18, v18
	v_mul_f32_e32 v21, v20, v20
	v_pk_add_f32 v[0:1], v[0:1], v[2:3]
	v_pk_add_f32 v[2:3], v[10:11], v[12:13]
	v_pk_add_f32 v[10:11], v[18:19], v[20:21]
	v_pk_add_f32 v[0:1], v[0:1], v[2:3]
	v_pk_add_f32 v[2:3], v[14:15], v[16:17]
	global_store_dwordx4 v[8:9], v[4:7], off offset:128
	v_pk_add_f32 v[2:3], v[2:3], v[10:11]
	s_nop 0
	v_pk_add_f32 v[0:1], v[0:1], v[2:3]
	v_mov_b32_e32 v2, v165
	v_mov_b32_e32 v3, v165
	s_nop 0
	v_mov_b32_dpp v2, v0 quad_perm:[1,0,3,2] row_mask:0xf bank_mask:0xf
	v_mov_b32_dpp v3, v1 quad_perm:[1,0,3,2] row_mask:0xf bank_mask:0xf
	v_pk_add_f32 v[0:1], v[0:1], v[2:3]
	ds_bpermute_b32 v2, v207, v0
	ds_bpermute_b32 v3, v207, v1
	s_waitcnt lgkmcnt(0)
	v_pk_add_f32 v[0:1], v[0:1], v[2:3]
	ds_bpermute_b32 v2, v208, v0
	ds_bpermute_b32 v3, v208, v1
	s_and_saveexec_b64 s[20:21], s[16:17]
	s_cbranch_execz .LBB0_848
	s_waitcnt lgkmcnt(0)
	v_pk_add_f32 v[0:1], v[0:1], v[2:3]
	v_add_co_u32_e32 v2, vcc, 0x16000, v186
	s_nop 1
	v_addc_co_u32_e32 v3, vcc, 0, v187, vcc
	global_store_dwordx2 v[2:3], v[0:1], off offset:512

; #define LAS __attribute__((address_space(3)))
;     __device__ __forceinline__ void operator()(const f32x4 (&acc)[2][2][4][2], const Unit& u, int wr, int wc, int fr, int fq, const EpiCtx& X) const {
;     ...
;         char* yb = nullptr; char* xb = (char*)(XB + (size_t)u.pm * BM * DM + (size_t)(u.pn * 4 + wc) * (BM * 64));
;         unsigned lo = (unsigned)((wr * 64 + fe) * 64 + o32 + 8 * fq) * 2u; EPI_OPAQUE(lo);
;         const int col = u.pn * BM + wc * 64 + o32 + 8 * fq;
;         f32x4 g0, g1, b0, b1;
;         if (RESN) { ensure_tbl(PSp, sidp, u.pm, X);
;             g0 = *(const f32x4*)(gp + col); g1 = *(const f32x4*)(gp + col + 4); b0 = *(const f32x4*)(bp + col) * ALPHA; b1 = *(const f32x4*)(bp + col + 4) * ALPHA; }
;         const LAS f32x2* tbl = (const LAS f32x2*)(X.lds + TBL_OFF) + wr * 64 + fe;
;         f32x2* ps = PSn + ((size_t)u.pm * BM + wr * 64 + fe) * 64 + u.pn * 4 + wc;
; #pragma unroll
;         for (int ai = 0; ai < 2; ++ai) {
;             u32x4 raw[8];
; #pragma unroll
;             for (int m = 0; m < 4; ++m) { const unsigned off = lo + (unsigned)((ai * HALF + m * 16) * 64) * 2u; raw[2 * m] = *(const u32x4*)(xb + off); raw[2 * m + 1] = *(const u32x4*)(xb + off + 128); }
; #pragma unroll
;             for (int m = 0; m < 4; ++m) {
;                 const int rl = ai * HALF + m * 16; const unsigned off = lo + (unsigned)(rl * 64) * 2u;
;                 const f32x4 o0a = acc[ai][0][m][0], o0b = acc[ai][0][m][1], o1a = acc[ai][1][m][0], o1b = acc[ai][1][m][1];
;                 const f32x4 ra_ = dpp_swap1(odd ? o0a : o1a), rb_ = dpp_swap1(odd ? o0b : o1b);
;                 const f32x4 pa[2] = {odd ? ra_ : o0a, odd ? o1a : ra_}, pb[2] = {odd ? rb_ : o0b, odd ? o1b : rb_};
; #pragma unroll
;                 for (int q = 0; q < 2; ++q) {
;                     const u32x4 w0 = raw[2 * m + q];
;                     const f32x4 r0 = (f32x4){bf_lo(w0.x), bf_hi(w0.x), bf_lo(w0.y), bf_hi(w0.y)}, r1 = (f32x4){bf_lo(w0.z), bf_hi(w0.z), bf_lo(w0.w), bf_hi(w0.w)};
;                     f32x4 y0, y1;
;                     if (RESN) { const f32x2 t = tbl[rl + q]; const float mu = t.x, ra = t.y * ALPHA; y0 = (r0 - mu) * ra * g0 + b0 + pa[q]; y1 = (r1 - mu) * ra * g1 + b1 + pb[q]; }
;                     else { y0 = r0 * ALPHA + pa[q]; y1 = r1 * ALPHA + pb[q]; }
;                     { const u32x4 w = pack8f(y0, y1); *(u32x4*)(xb + off + q * 128) = w;
.LBB0_1463:
	s_lshl_b64 s[4:5], s[66:67], 21
	s_add_u32 s20, s51, s4
	s_addc_u32 s21, s53, s5
	s_lshl_b32 s66, s64, 2
	s_or_b32 s4, s66, s41
	s_ashr_i32 s5, s4, 31
	v_lshl_add_u32 v72, s64, 8, v200
	v_ashrrev_i32_e32 v73, 31, v72
	s_lshl_b64 s[4:5], s[4:5], 15
	v_lshlrev_b64 v[72:73], 2, v[72:73]
	s_add_u32 s20, s20, s4
	v_lshl_add_u64 v[74:75], s[26:27], 0, v[72:73]
	s_addc_u32 s21, s21, s5
	global_load_dwordx4 v[194:197], v[74:75], off offset:16
	global_load_dwordx4 v[178:181], v[74:75], off
	global_load_dwordx4 v[214:217], v164, s[20:21]
	v_lshl_add_u64 v[72:73], s[24:25], 0, v[72:73]
	s_waitcnt lgkmcnt(0)
	global_load_dwordx4 v[76:79], v[72:73], off
	s_nop 0
	global_load_dwordx4 v[72:75], v[72:73], off offset:16
	v_cndmask_b32_e64 v136, v135, v127, s[10:11]
	v_cndmask_b32_e64 v137, v134, v126, s[10:11]
	v_cndmask_b32_e64 v138, v133, v125, s[10:11]
	v_cndmask_b32_e64 v139, v132, v124, s[10:11]
	v_mov_b32_e32 v189, 0
	v_mov_b32_e32 v193, 0
	v_mov_b32_e32 v191, 0
	v_mov_b32_e32 v209, 0
	v_cndmask_b32_e64 v140, v131, v123, s[10:11]
	v_cndmask_b32_e64 v141, v130, v122, s[10:11]
	v_cndmask_b32_e64 v142, v129, v121, s[10:11]
	v_cndmask_b32_e64 v143, v128, v120, s[10:11]
	v_mov_b32_e32 v210, 0
	v_mov_b32_e32 v212, 0
	v_mov_b32_e32 v211, 0
	v_mov_b32_e32 v213, 0
	v_mov_b32_dpp v189, v139 quad_perm:[1,0,3,2] row_mask:0xf bank_mask:0xf
	v_mov_b32_dpp v193, v138 quad_perm:[1,0,3,2] row_mask:0xf bank_mask:0xf
	v_mov_b32_dpp v191, v137 quad_perm:[1,0,3,2] row_mask:0xf bank_mask:0xf
	v_mov_b32_dpp v209, v136 quad_perm:[1,0,3,2] row_mask:0xf bank_mask:0xf
	v_mov_b32_dpp v210, v143 quad_perm:[1,0,3,2] row_mask:0xf bank_mask:0xf
	v_mov_b32_dpp v212, v142 quad_perm:[1,0,3,2] row_mask:0xf bank_mask:0xf
	v_mov_b32_dpp v211, v141 quad_perm:[1,0,3,2] row_mask:0xf bank_mask:0xf
	v_mov_b32_dpp v213, v140 quad_perm:[1,0,3,2] row_mask:0xf bank_mask:0xf
	v_add_u32_e32 v192, 0x800, v164
	v_add_u32_e32 v190, 0x1000, v164
	v_add_u32_e32 v188, 0x1800, v164
	ds_read_b64 v[218:219], v201
	v_cndmask_b32_e64 v221, v193, v133, s[10:11]
	v_cndmask_b32_e64 v220, v189, v132, s[10:11]
	v_cndmask_b32_e64 v223, v209, v135, s[10:11]
	v_cndmask_b32_e64 v222, v191, v134, s[10:11]
	v_cndmask_b32_e64 v225, v212, v129, s[10:11]
	v_cndmask_b32_e64 v224, v210, v128, s[10:11]
	v_cndmask_b32_e64 v227, v213, v131, s[10:11]
	v_cndmask_b32_e64 v226, v211, v130, s[10:11]
	global_load_dwordx4 v[152:155], v164, s[20:21] offset:128
	global_load_dwordx4 v[148:151], v192, s[20:21]
	global_load_dwordx4 v[144:147], v192, s[20:21] offset:128
	global_load_dwordx4 v[140:143], v190, s[20:21]
	global_load_dwordx4 v[136:139], v190, s[20:21] offset:128
	global_load_dwordx4 v[132:135], v188, s[20:21]
	global_load_dwordx4 v[128:131], v188, s[20:21] offset:128
	s_waitcnt lgkmcnt(0)
	v_mul_f32_e32 v208, 0x3fb504f3, v219
	v_lshl_add_u64 v[186:187], v[166:167], 0, s[68:69]
	s_ashr_i32 s67, s66, 31
	v_lshl_add_u64 v[186:187], s[66:67], 3, v[186:187]
	v_lshl_add_u64 v[186:187], v[186:187], 0, s[22:23]
	v_add_u32_e32 v246, 0x4000, v164
	v_add_u32_e32 v247, 0x4800, v164
	global_load_dwordx4 v[230:233], v246, s[20:21]
	global_load_dwordx4 v[234:237], v246, s[20:21] offset:128
	global_load_dwordx4 v[238:241], v247, s[20:21]
	global_load_dwordx4 v[242:245], v247, s[20:21] offset:128
	s_waitcnt vmcnt(0)
	v_pk_mul_f32 v[182:183], v[180:181], s[52:53] op_sel_hi:[1,0]
	v_pk_mul_f32 v[184:185], v[178:179], s[52:53] op_sel_hi:[1,0]
	v_pk_mul_f32 v[178:179], v[196:197], s[52:53] op_sel_hi:[1,0]
	v_pk_mul_f32 v[180:181], v[194:195], s[52:53] op_sel_hi:[1,0]
	v_lshlrev_b32_e32 v194, 16, v214
	v_and_b32_e32 v195, 0xffff0000, v214
	v_lshlrev_b32_e32 v196, 16, v215
	v_and_b32_e32 v197, 0xffff0000, v215
	v_lshlrev_b32_e32 v207, 16, v216
	v_and_b32_e32 v214, 0xffff0000, v216
	v_lshlrev_b32_e32 v216, 16, v217
	v_and_b32_e32 v217, 0xffff0000, v217
	v_sub_f32_e32 v195, v195, v218
	v_sub_f32_e32 v194, v194, v218
	v_sub_f32_e32 v197, v197, v218
	v_sub_f32_e32 v196, v196, v218
	v_sub_f32_e32 v215, v214, v218
	v_sub_f32_e32 v214, v207, v218
	v_sub_f32_e32 v217, v217, v218
	v_sub_f32_e32 v216, v216, v218
	v_pk_mul_f32 v[196:197], v[196:197], v[208:209] op_sel_hi:[1,0]
	v_pk_mul_f32 v[194:195], v[194:195], v[208:209] op_sel_hi:[1,0]
	v_pk_mul_f32 v[216:217], v[216:217], v[208:209] op_sel_hi:[1,0]
	v_pk_mul_f32 v[214:215], v[214:215], v[208:209] op_sel_hi:[1,0]
	v_pk_fma_f32 v[194:195], v[76:77], v[194:195], v[184:185]
	v_pk_fma_f32 v[196:197], v[78:79], v[196:197], v[182:183]
	v_pk_fma_f32 v[214:215], v[72:73], v[214:215], v[180:181]
	v_pk_fma_f32 v[216:217], v[74:75], v[216:217], v[178:179]
	v_pk_add_f32 v[196:197], v[222:223], v[196:197]
	v_pk_add_f32 v[194:195], v[220:221], v[194:195]
	v_pk_add_f32 v[218:219], v[226:227], v[216:217]
	v_pk_add_f32 v[216:217], v[224:225], v[214:215]
	v_cvt_pk_bf16_f32 v214, v194, v195
	v_cvt_pk_bf16_f32 v215, v196, v197
	v_and_b32_e32 v208, 64, v206
	v_cvt_pk_bf16_f32 v216, v216, v217
	v_cvt_pk_bf16_f32 v217, v218, v219
	v_lshlrev_b32_e32 v194, 16, v214
	v_and_b32_e32 v196, 0xffff0000, v214
	v_lshlrev_b32_e32 v218, 16, v215
	v_and_b32_e32 v220, 0xffff0000, v215
	v_lshlrev_b32_e32 v222, 16, v216
	v_and_b32_e32 v224, 0xffff0000, v216
	v_lshlrev_b32_e32 v226, 16, v217
	v_and_b32_e32 v228, 0xffff0000, v217
	v_mul_f32_e32 v195, v194, v194
	v_mul_f32_e32 v197, v196, v196
	v_mul_f32_e32 v219, v218, v218
	v_mul_f32_e32 v221, v220, v220
	v_mul_f32_e32 v223, v222, v222
	v_mul_f32_e32 v225, v224, v224
	v_mul_f32_e32 v227, v226, v226
	v_mul_f32_e32 v229, v228, v228
	v_pk_add_f32 v[194:195], v[194:195], v[196:197]
	v_pk_add_f32 v[196:197], v[218:219], v[220:221]
	v_pk_add_f32 v[218:219], v[226:227], v[228:229]
	v_pk_add_f32 v[194:195], v[194:195], v[196:197]
	v_pk_add_f32 v[196:197], v[222:223], v[224:225]
	v_xor_b32_e32 v207, 16, v206
	v_add_u32_e32 v208, 64, v208
	v_pk_add_f32 v[196:197], v[196:197], v[218:219]
	v_cmp_lt_i32_e32 vcc, v207, v208
	v_pk_add_f32 v[194:195], v[194:195], v[196:197]
	v_mov_b32_e32 v196, 0
	v_mov_b32_e32 v197, 0
	v_cndmask_b32_e32 v207, v206, v207, vcc
	v_mov_b32_dpp v196, v194 quad_perm:[1,0,3,2] row_mask:0xf bank_mask:0xf
	v_mov_b32_dpp v197, v195 quad_perm:[1,0,3,2] row_mask:0xf bank_mask:0xf
	v_lshlrev_b32_e32 v207, 2, v207
	v_pk_add_f32 v[194:195], v[194:195], v[196:197]
	ds_bpermute_b32 v196, v207, v194
	ds_bpermute_b32 v197, v207, v195
	v_xor_b32_e32 v218, 32, v206
	v_cmp_lt_i32_e32 vcc, v218, v208
	global_store_dwordx4 v164, v[214:217], s[20:21]
	s_waitcnt lgkmcnt(0)
	v_pk_add_f32 v[194:195], v[194:195], v[196:197]
	v_cndmask_b32_e32 v208, v206, v218, vcc
	v_lshlrev_b32_e32 v208, 2, v208
	ds_bpermute_b32 v196, v208, v194
	ds_bpermute_b32 v197, v208, v195
	s_and_saveexec_b64 s[64:65], s[16:17]
	s_cbranch_execz .LBB0_1465
	s_waitcnt lgkmcnt(0)
	v_pk_add_f32 v[194:195], v[194:195], v[196:197]
	global_store_dwordx2 v[186:187], v[194:195], off

;     __device__ __forceinline__ void operator()(const f32x4 (&acc)[2][2][4][2], const Unit& u, int wr, int wc, int fr, int fq, const EpiCtx& X) const {
;     ...
;             for (int m = 0; m < 4; ++m) { const unsigned off = lo + (unsigned)((ai * HALF + m * 16) * 64) * 2u; raw[2 * m] = *(const u32x4*)(xb + off); raw[2 * m + 1] = *(const u32x4*)(xb + off + 128); }
; #pragma unroll
;             for (int m = 0; m < 4; ++m) {
;                 const int rl = ai * HALF + m * 16; const unsigned off = lo + (unsigned)(rl * 64) * 2u;
;                 const f32x4 o0a = acc[ai][0][m][0], o0b = acc[ai][0][m][1], o1a = acc[ai][1][m][0], o1b = acc[ai][1][m][1];
;                 const f32x4 ra_ = dpp_swap1(odd ? o0a : o1a), rb_ = dpp_swap1(odd ? o0b : o1b);
;                 const f32x4 pa[2] = {odd ? ra_ : o0a, odd ? o1a : ra_}, pb[2] = {odd ? rb_ : o0b, odd ? o1b : rb_};
; #pragma unroll
;                 for (int q = 0; q < 2; ++q) {
;                     const u32x4 w0 = raw[2 * m + q];
;                     const f32x4 r0 = (f32x4){bf_lo(w0.x), bf_hi(w0.x), bf_lo(w0.y), bf_hi(w0.y)}, r1 = (f32x4){bf_lo(w0.z), bf_hi(w0.z), bf_lo(w0.w), bf_hi(w0.w)};
;                     f32x4 y0, y1;
;                     if (RESN) { const f32x2 t = tbl[rl + q]; const float mu = t.x, ra = t.y * ALPHA; y0 = (r0 - mu) * ra * g0 + b0 + pa[q]; y1 = (r1 - mu) * ra * g1 + b1 + pb[q]; }
;                     else { y0 = r0 * ALPHA + pa[q]; y1 = r1 * ALPHA + pb[q]; }
;                     { const u32x4 w = pack8f(y0, y1); *(u32x4*)(xb + off + q * 128) = w;
;                         y0 = (f32x4){bf_lo(w.x), bf_hi(w.x), bf_lo(w.y), bf_hi(w.y)}; y1 = (f32x4){bf_lo(w.z), bf_hi(w.z), bf_lo(w.w), bf_hi(w.w)}; }
;                     float sa = ((y0[0] + y0[1]) + (y0[2] + y0[3])) + ((y1[0] + y1[1]) + (y1[2] + y1[3]));
;                     float sb = ((y0[0] * y0[0] + y0[1] * y0[1]) + (y0[2] * y0[2] + y0[3] * y0[3])) + ((y1[0] * y1[0] + y1[1] * y1[1]) + (y1[2] * y1[2] + y1[3] * y1[3]));
;                     sa += dpp_x1(sa);
;                     sb += dpp_x1(sb);
;                     sa += __shfl_xor(sa, 16); sa += __shfl_xor(sa, 32); sb += __shfl_xor(sb, 16); sb += __shfl_xor(sb, 32);
;                     if (fq == 0 && !odd) ps[(size_t)(rl + q) * 64] = (f32x2){sa, sb};
.LBB0_1479:
	s_or_b64 exec, exec, s[64:65]
	v_add_u32_e32 v104, 0x4000, v164
	v_mov_b32_e32 v112, v230
	v_mov_b32_e32 v113, v231
	v_mov_b32_e32 v114, v232
	v_mov_b32_e32 v115, v233
	v_add_u32_e32 v102, 0x4800, v164
	v_add_u32_e32 v100, 0x5000, v164
	v_add_u32_e32 v164, 0x5800, v164
	v_mov_b32_e32 v96, v234
	v_mov_b32_e32 v97, v235
	v_mov_b32_e32 v98, v236
	v_mov_b32_e32 v99, v237
	v_mov_b32_e32 v92, v238
	v_mov_b32_e32 v93, v239
	v_mov_b32_e32 v94, v240
	v_mov_b32_e32 v95, v241
	v_mov_b32_e32 v88, v242
	v_mov_b32_e32 v89, v243
	v_mov_b32_e32 v90, v244
	v_mov_b32_e32 v91, v245
	global_load_dwordx4 v[84:87], v100, s[20:21]
	global_load_dwordx4 v[80:83], v100, s[20:21] offset:128
	global_load_dwordx4 v[68:71], v164, s[20:21]
	s_waitcnt lgkmcnt(0)
	global_load_dwordx4 v[64:67], v164, s[20:21] offset:128
	v_cndmask_b32_e64 v116, v62, v54, s[10:11]
	v_cndmask_b32_e64 v117, v61, v53, s[10:11]
	v_mov_b32_e32 v105, 0
	v_mov_b32_e32 v103, 0
	v_cndmask_b32_e64 v111, v63, v55, s[10:11]
	v_mov_b32_dpp v105, v117 quad_perm:[1,0,3,2] row_mask:0xf bank_mask:0xf
	v_mov_b32_dpp v103, v116 quad_perm:[1,0,3,2] row_mask:0xf bank_mask:0xf
	ds_read_b64 v[116:117], v201 offset:1024
	v_cndmask_b32_e64 v118, v60, v52, s[10:11]
	v_mov_b32_e32 v101, 0
	v_mov_b32_e32 v106, 0
	v_cndmask_b32_e64 v119, v59, v51, s[10:11]
	v_cndmask_b32_e64 v120, v58, v50, s[10:11]
	v_cndmask_b32_e64 v121, v57, v49, s[10:11]
	v_cndmask_b32_e64 v122, v56, v48, s[10:11]
	v_mov_b32_e32 v107, 0
	v_mov_b32_e32 v109, 0
	v_mov_b32_e32 v108, 0
	v_mov_b32_e32 v110, 0
	v_mov_b32_dpp v101, v118 quad_perm:[1,0,3,2] row_mask:0xf bank_mask:0xf
	v_mov_b32_dpp v106, v111 quad_perm:[1,0,3,2] row_mask:0xf bank_mask:0xf
	v_mov_b32_dpp v107, v122 quad_perm:[1,0,3,2] row_mask:0xf bank_mask:0xf
	v_mov_b32_dpp v109, v121 quad_perm:[1,0,3,2] row_mask:0xf bank_mask:0xf
	v_mov_b32_dpp v108, v120 quad_perm:[1,0,3,2] row_mask:0xf bank_mask:0xf
	v_mov_b32_dpp v110, v119 quad_perm:[1,0,3,2] row_mask:0xf bank_mask:0xf
	s_waitcnt lgkmcnt(0)
	v_mul_f32_e32 v118, 0x3fb504f3, v117
	v_cndmask_b32_e64 v61, v105, v61, s[10:11]
	v_cndmask_b32_e64 v60, v101, v60, s[10:11]
	v_cndmask_b32_e64 v63, v106, v63, s[10:11]
	v_cndmask_b32_e64 v62, v103, v62, s[10:11]
	v_cndmask_b32_e64 v57, v109, v57, s[10:11]
	v_cndmask_b32_e64 v56, v107, v56, s[10:11]
	v_cndmask_b32_e64 v59, v110, v59, s[10:11]
	v_cndmask_b32_e64 v58, v108, v58, s[10:11]
	v_lshlrev_b32_e32 v111, 16, v112
	v_and_b32_e32 v112, 0xffff0000, v112
	v_lshlrev_b32_e32 v117, 16, v113
	v_and_b32_e32 v119, 0xffff0000, v113
	v_lshlrev_b32_e32 v120, 16, v114
	v_and_b32_e32 v121, 0xffff0000, v114
	v_lshlrev_b32_e32 v122, 16, v115
	v_and_b32_e32 v123, 0xffff0000, v115
	v_sub_f32_e32 v113, v112, v116
	v_sub_f32_e32 v112, v111, v116
	v_sub_f32_e32 v115, v119, v116
	v_sub_f32_e32 v114, v117, v116
	v_sub_f32_e32 v121, v121, v116
	v_sub_f32_e32 v120, v120, v116
	v_sub_f32_e32 v117, v123, v116
	v_sub_f32_e32 v116, v122, v116
	v_pk_mul_f32 v[114:115], v[114:115], v[118:119] op_sel_hi:[1,0]
	v_pk_mul_f32 v[112:113], v[112:113], v[118:119] op_sel_hi:[1,0]
	v_pk_mul_f32 v[116:117], v[116:117], v[118:119] op_sel_hi:[1,0]
	v_pk_mul_f32 v[118:119], v[120:121], v[118:119] op_sel_hi:[1,0]
	v_pk_fma_f32 v[112:113], v[76:77], v[112:113], v[184:185]
	v_pk_fma_f32 v[114:115], v[78:79], v[114:115], v[182:183]
	v_pk_fma_f32 v[118:119], v[72:73], v[118:119], v[180:181]
	v_pk_fma_f32 v[116:117], v[74:75], v[116:117], v[178:179]
	v_pk_add_f32 v[62:63], v[62:63], v[114:115]
	v_pk_add_f32 v[60:61], v[60:61], v[112:113]
	v_pk_add_f32 v[58:59], v[58:59], v[116:117]
	v_pk_add_f32 v[56:57], v[56:57], v[118:119]
	v_cvt_pk_bf16_f32 v60, v60, v61
	v_cvt_pk_bf16_f32 v61, v62, v63
	s_nop 0
	v_cvt_pk_bf16_f32 v62, v56, v57
	v_cvt_pk_bf16_f32 v63, v58, v59
	v_lshlrev_b32_e32 v56, 16, v60
	v_and_b32_e32 v58, 0xffff0000, v60
	v_lshlrev_b32_e32 v112, 16, v61
	v_and_b32_e32 v114, 0xffff0000, v61
	v_lshlrev_b32_e32 v116, 16, v62
	v_and_b32_e32 v118, 0xffff0000, v62
	v_lshlrev_b32_e32 v120, 16, v63
	v_and_b32_e32 v122, 0xffff0000, v63
	v_mul_f32_e32 v57, v56, v56
	v_mul_f32_e32 v59, v58, v58
	v_mul_f32_e32 v113, v112, v112
	v_mul_f32_e32 v115, v114, v114
	v_mul_f32_e32 v117, v116, v116
	v_mul_f32_e32 v119, v118, v118
	v_mul_f32_e32 v121, v120, v120
	v_mul_f32_e32 v123, v122, v122
	v_pk_add_f32 v[56:57], v[56:57], v[58:59]
	v_pk_add_f32 v[58:59], v[112:113], v[114:115]
	v_pk_add_f32 v[112:113], v[120:121], v[122:123]
	v_pk_add_f32 v[56:57], v[56:57], v[58:59]
	v_pk_add_f32 v[58:59], v[116:117], v[118:119]
	global_store_dwordx4 v104, v[60:63], s[20:21]
	v_pk_add_f32 v[58:59], v[58:59], v[112:113]
	s_nop 0
	v_pk_add_f32 v[56:57], v[56:57], v[58:59]
	v_mov_b32_e32 v58, v165
	v_mov_b32_e32 v59, v165
	s_nop 0
	v_mov_b32_dpp v58, v56 quad_perm:[1,0,3,2] row_mask:0xf bank_mask:0xf
	v_mov_b32_dpp v59, v57 quad_perm:[1,0,3,2] row_mask:0xf bank_mask:0xf
	v_pk_add_f32 v[56:57], v[56:57], v[58:59]
	ds_bpermute_b32 v58, v207, v56
	ds_bpermute_b32 v59, v207, v57
	s_waitcnt lgkmcnt(0)
	v_pk_add_f32 v[56:57], v[56:57], v[58:59]
	ds_bpermute_b32 v58, v208, v56
	ds_bpermute_b32 v59, v208, v57
	s_and_saveexec_b64 s[64:65], s[16:17]
	s_cbranch_execz .LBB0_1481
	s_waitcnt lgkmcnt(0)
	v_pk_add_f32 v[56:57], v[56:57], v[58:59]
	v_add_co_u32_e32 v58, vcc, 0x10000, v186
	s_nop 1
	v_addc_co_u32_e32 v59, vcc, 0, v187, vcc
	global_store_dwordx2 v[58:59], v[56:57], off
; __device__ __forceinline__ u32x4 pack8f(f32x4 a, f32x4 b) { u32x4 w; w.x = cvt_pk_bf16(a[0], a[1]); w.y = cvt_pk_bf16(a[2], a[3]); w.z = cvt_pk_bf16(b[0], b[1]); w.w = cvt_pk_bf16(b[2], b[3]); return w; }
;     __device__ __forceinline__ void operator()(const f32x4 (&acc)[2][2][4][2], const Unit& u, int wr, int wc, int fr, int fq, const EpiCtx& X) const {
;     ...
;             for (int m = 0; m < 4; ++m) {
;                 const int rl = ai * HALF + m * 16; const unsigned off = lo + (unsigned)(rl * 64) * 2u;
;                 const f32x4 o0a = acc[ai][0][m][0], o0b = acc[ai][0][m][1], o1a = acc[ai][1][m][0], o1b = acc[ai][1][m][1];
;                 const f32x4 ra_ = dpp_swap1(odd ? o0a : o1a), rb_ = dpp_swap1(odd ? o0b : o1b);
;                 const f32x4 pa[2] = {odd ? ra_ : o0a, odd ? o1a : ra_}, pb[2] = {odd ? rb_ : o0b, odd ? o1b : rb_};
; #pragma unroll
;                 for (int q = 0; q < 2; ++q) {
;                     const u32x4 w0 = raw[2 * m + q];
;                     const f32x4 r0 = (f32x4){bf_lo(w0.x), bf_hi(w0.x), bf_lo(w0.y), bf_hi(w0.y)}, r1 = (f32x4){bf_lo(w0.z), bf_hi(w0.z), bf_lo(w0.w), bf_hi(w0.w)};
;                     f32x4 y0, y1;
;                     if (RESN) { const f32x2 t = tbl[rl + q]; const float mu = t.x, ra = t.y * ALPHA; y0 = (r0 - mu) * ra * g0 + b0 + pa[q]; y1 = (r1 - mu) * ra * g1 + b1 + pb[q]; }
;                     else { y0 = r0 * ALPHA + pa[q]; y1 = r1 * ALPHA + pb[q]; }
;                     { const u32x4 w = pack8f(y0, y1); *(u32x4*)(xb + off + q * 128) = w;
;                         y0 = (f32x4){bf_lo(w.x), bf_hi(w.x), bf_lo(w.y), bf_hi(w.y)}; y1 = (f32x4){bf_lo(w.z), bf_hi(w.z), bf_lo(w.w), bf_hi(w.w)}; }
;                     float sa = ((y0[0] + y0[1]) + (y0[2] + y0[3])) + ((y1[0] + y1[1]) + (y1[2] + y1[3]));
;                     float sb = ((y0[0] * y0[0] + y0[1] * y0[1]) + (y0[2] * y0[2] + y0[3] * y0[3])) + ((y1[0] * y1[0] + y1[1] * y1[1]) + (y1[2] * y1[2] + y1[3] * y1[3]));
;                     sa += dpp_x1(sa);
;                     sb += dpp_x1(sb);
;                     sa += __shfl_xor(sa, 16); sa += __shfl_xor(sa, 32); sb += __shfl_xor(sb, 16); sb += __shfl_xor(sb, 32);
;                     if (fq == 0 && !odd) ps[(size_t)(rl + q) * 64] = (f32x2){sa, sb};
.LBB0_1481:
	s_or_b64 exec, exec, s[64:65]
	ds_read_b64 v[56:57], v201 offset:1032
	s_waitcnt lgkmcnt(1)
	v_lshlrev_b32_e32 v59, 16, v96
	v_and_b32_e32 v60, 0xffff0000, v96
	v_cndmask_b32_e64 v53, v53, v105, s[10:11]
	v_cndmask_b32_e64 v52, v52, v101, s[10:11]
	s_waitcnt lgkmcnt(0)
	v_mul_f32_e32 v58, 0x3fb504f3, v57
	v_sub_f32_e32 v61, v60, v56
	v_sub_f32_e32 v60, v59, v56
	v_pk_mul_f32 v[60:61], v[60:61], v[58:59] op_sel_hi:[1,0]
	v_lshlrev_b32_e32 v62, 16, v97
	v_and_b32_e32 v63, 0xffff0000, v97
	v_lshlrev_b32_e32 v96, 16, v98
	v_and_b32_e32 v97, 0xffff0000, v98
	v_lshlrev_b32_e32 v98, 16, v99
	v_and_b32_e32 v99, 0xffff0000, v99
	v_pk_fma_f32 v[60:61], v[76:77], v[60:61], v[184:185]
	v_sub_f32_e32 v63, v63, v56
	v_sub_f32_e32 v62, v62, v56
	v_pk_add_f32 v[52:53], v[52:53], v[60:61]
	v_sub_f32_e32 v61, v97, v56
	v_sub_f32_e32 v60, v96, v56
	v_sub_f32_e32 v57, v99, v56
	v_sub_f32_e32 v56, v98, v56
	v_pk_mul_f32 v[62:63], v[62:63], v[58:59] op_sel_hi:[1,0]
	v_pk_mul_f32 v[56:57], v[56:57], v[58:59] op_sel_hi:[1,0]
	v_pk_mul_f32 v[58:59], v[60:61], v[58:59] op_sel_hi:[1,0]
	v_cndmask_b32_e64 v55, v55, v106, s[10:11]
	v_cndmask_b32_e64 v54, v54, v103, s[10:11]
	v_cndmask_b32_e64 v49, v49, v109, s[10:11]
	v_cndmask_b32_e64 v48, v48, v107, s[10:11]
	v_cndmask_b32_e64 v51, v51, v110, s[10:11]
	v_cndmask_b32_e64 v50, v50, v108, s[10:11]
	v_pk_fma_f32 v[62:63], v[78:79], v[62:63], v[182:183]
	v_pk_fma_f32 v[58:59], v[72:73], v[58:59], v[180:181]
	v_pk_fma_f32 v[56:57], v[74:75], v[56:57], v[178:179]
	v_pk_add_f32 v[54:55], v[54:55], v[62:63]
	v_pk_add_f32 v[50:51], v[50:51], v[56:57]
	v_pk_add_f32 v[48:49], v[48:49], v[58:59]
	v_cvt_pk_bf16_f32 v52, v52, v53
	v_cvt_pk_bf16_f32 v53, v54, v55
	v_mov_b32_e32 v105, v165
	v_cvt_pk_bf16_f32 v54, v48, v49
	v_cvt_pk_bf16_f32 v55, v50, v51
	v_lshlrev_b32_e32 v48, 16, v52
	v_and_b32_e32 v50, 0xffff0000, v52
	v_lshlrev_b32_e32 v56, 16, v53
	v_and_b32_e32 v58, 0xffff0000, v53
	v_lshlrev_b32_e32 v60, 16, v54
	v_and_b32_e32 v62, 0xffff0000, v54
	v_lshlrev_b32_e32 v96, 16, v55
	v_and_b32_e32 v98, 0xffff0000, v55
	v_mul_f32_e32 v49, v48, v48
	v_mul_f32_e32 v51, v50, v50
	v_mul_f32_e32 v57, v56, v56
	v_mul_f32_e32 v59, v58, v58
	v_mul_f32_e32 v61, v60, v60
	v_mul_f32_e32 v63, v62, v62
	v_mul_f32_e32 v97, v96, v96
	v_mul_f32_e32 v99, v98, v98
	v_pk_add_f32 v[48:49], v[48:49], v[50:51]
	v_pk_add_f32 v[50:51], v[56:57], v[58:59]
	v_pk_add_f32 v[56:57], v[96:97], v[98:99]
	v_pk_add_f32 v[48:49], v[48:49], v[50:51]
	v_pk_add_f32 v[50:51], v[60:61], v[62:63]
	s_nop 0
	v_pk_add_f32 v[50:51], v[50:51], v[56:57]
	v_lshl_add_u64 v[56:57], s[20:21], 0, v[104:105]
	v_pk_add_f32 v[48:49], v[48:49], v[50:51]
	v_mov_b32_e32 v50, v165
	v_mov_b32_e32 v51, v165
	global_store_dwordx4 v[56:57], v[52:55], off offset:128
	v_mov_b32_dpp v50, v48 quad_perm:[1,0,3,2] row_mask:0xf bank_mask:0xf
	v_mov_b32_dpp v51, v49 quad_perm:[1,0,3,2] row_mask:0xf bank_mask:0xf
	v_pk_add_f32 v[48:49], v[48:49], v[50:51]
	ds_bpermute_b32 v50, v207, v48
	ds_bpermute_b32 v51, v207, v49
	s_waitcnt lgkmcnt(0)
	v_pk_add_f32 v[48:49], v[48:49], v[50:51]
	ds_bpermute_b32 v50, v208, v48
	ds_bpermute_b32 v51, v208, v49
	s_and_saveexec_b64 s[64:65], s[16:17]
	s_cbranch_execz .LBB0_1483
	s_waitcnt lgkmcnt(0)
	v_pk_add_f32 v[48:49], v[48:49], v[50:51]
	v_add_co_u32_e32 v50, vcc, 0x10000, v186
	s_nop 1
	v_addc_co_u32_e32 v51, vcc, 0, v187, vcc
	global_store_dwordx2 v[50:51], v[48:49], off offset:512
.LBB0_1483:
	s_or_b64 exec, exec, s[64:65]
	s_waitcnt lgkmcnt(1)
	v_cndmask_b32_e64 v50, v44, v36, s[10:11]
	v_mov_b32_e32 v48, 0
	v_cndmask_b32_e64 v49, v45, v37, s[10:11]
	s_waitcnt lgkmcnt(0)
	v_cndmask_b32_e64 v51, v46, v38, s[10:11]
	v_mov_b32_dpp v48, v50 quad_perm:[1,0,3,2] row_mask:0xf bank_mask:0xf
	v_mov_b32_e32 v50, 0
	v_cndmask_b32_e64 v52, v47, v39, s[10:11]
	v_cndmask_b32_e64 v54, v40, v32, s[10:11]
	v_mov_b32_dpp v50, v49 quad_perm:[1,0,3,2] row_mask:0xf bank_mask:0xf
	v_mov_b32_e32 v49, 0
	v_cndmask_b32_e64 v53, v41, v33, s[10:11]
	v_cndmask_b32_e64 v55, v42, v34, s[10:11]
	v_mov_b32_dpp v49, v51 quad_perm:[1,0,3,2] row_mask:0xf bank_mask:0xf
	v_mov_b32_e32 v51, 0
	v_cndmask_b32_e64 v56, v43, v35, s[10:11]
	v_lshlrev_b32_e32 v59, 16, v92
	v_mov_b32_dpp v51, v52 quad_perm:[1,0,3,2] row_mask:0xf bank_mask:0xf
	v_mov_b32_e32 v52, 0
	v_and_b32_e32 v60, 0xffff0000, v92
	v_cndmask_b32_e64 v45, v50, v45, s[10:11]
	v_mov_b32_dpp v52, v54 quad_perm:[1,0,3,2] row_mask:0xf bank_mask:0xf
	v_mov_b32_e32 v54, 0
	v_cndmask_b32_e64 v44, v48, v44, s[10:11]
	v_lshlrev_b32_e32 v62, 16, v93
	v_mov_b32_dpp v54, v53 quad_perm:[1,0,3,2] row_mask:0xf bank_mask:0xf
	v_mov_b32_e32 v53, 0
	v_and_b32_e32 v63, 0xffff0000, v93
	v_lshlrev_b32_e32 v92, 16, v94
	v_mov_b32_dpp v53, v55 quad_perm:[1,0,3,2] row_mask:0xf bank_mask:0xf
	v_mov_b32_e32 v55, 0
	v_and_b32_e32 v93, 0xffff0000, v94
	v_lshlrev_b32_e32 v94, 16, v95
	v_mov_b32_dpp v55, v56 quad_perm:[1,0,3,2] row_mask:0xf bank_mask:0xf
	ds_read_b64 v[56:57], v201 offset:1152
	v_and_b32_e32 v95, 0xffff0000, v95
	v_cndmask_b32_e64 v47, v51, v47, s[10:11]
	v_cndmask_b32_e64 v46, v49, v46, s[10:11]
	v_cndmask_b32_e64 v41, v54, v41, s[10:11]
	s_waitcnt lgkmcnt(0)
; __device__ __forceinline__ u32x4 pack8f(f32x4 a, f32x4 b) { u32x4 w; w.x = cvt_pk_bf16(a[0], a[1]); w.y = cvt_pk_bf16(a[2], a[3]); w.z = cvt_pk_bf16(b[0], b[1]); w.w = cvt_pk_bf16(b[2], b[3]); return w; }
;     __device__ __forceinline__ void operator()(const f32x4 (&acc)[2][2][4][2], const Unit& u, int wr, int wc, int fr, int fq, const EpiCtx& X) const {
;     ...
;             for (int m = 0; m < 4; ++m) {
;                 const int rl = ai * HALF + m * 16; const unsigned off = lo + (unsigned)(rl * 64) * 2u;
;                 const f32x4 o0a = acc[ai][0][m][0], o0b = acc[ai][0][m][1], o1a = acc[ai][1][m][0], o1b = acc[ai][1][m][1];
;                 const f32x4 ra_ = dpp_swap1(odd ? o0a : o1a), rb_ = dpp_swap1(odd ? o0b : o1b);
;                 const f32x4 pa[2] = {odd ? ra_ : o0a, odd ? o1a : ra_}, pb[2] = {odd ? rb_ : o0b, odd ? o1b : rb_};
; #pragma unroll
;                 for (int q = 0; q < 2; ++q) {
;                     const u32x4 w0 = raw[2 * m + q];
;                     const f32x4 r0 = (f32x4){bf_lo(w0.x), bf_hi(w0.x), bf_lo(w0.y), bf_hi(w0.y)}, r1 = (f32x4){bf_lo(w0.z), bf_hi(w0.z), bf_lo(w0.w), bf_hi(w0.w)};
;                     f32x4 y0, y1;
;                     if (RESN) { const f32x2 t = tbl[rl + q]; const float mu = t.x, ra = t.y * ALPHA; y0 = (r0 - mu) * ra * g0 + b0 + pa[q]; y1 = (r1 - mu) * ra * g1 + b1 + pb[q]; }
;                     else { y0 = r0 * ALPHA + pa[q]; y1 = r1 * ALPHA + pb[q]; }
;                     { const u32x4 w = pack8f(y0, y1); *(u32x4*)(xb + off + q * 128) = w;
;                         y0 = (f32x4){bf_lo(w.x), bf_hi(w.x), bf_lo(w.y), bf_hi(w.y)}; y1 = (f32x4){bf_lo(w.z), bf_hi(w.z), bf_lo(w.w), bf_hi(w.w)}; }
;                     float sa = ((y0[0] + y0[1]) + (y0[2] + y0[3])) + ((y1[0] + y1[1]) + (y1[2] + y1[3]));
;                     float sb = ((y0[0] * y0[0] + y0[1] * y0[1]) + (y0[2] * y0[2] + y0[3] * y0[3])) + ((y1[0] * y1[0] + y1[1] * y1[1]) + (y1[2] * y1[2] + y1[3] * y1[3]));
;                     sa += dpp_x1(sa);
;                     sb += dpp_x1(sb);
;                     sa += __shfl_xor(sa, 16); sa += __shfl_xor(sa, 32); sb += __shfl_xor(sb, 16); sb += __shfl_xor(sb, 32);
;                     if (fq == 0 && !odd) ps[(size_t)(rl + q) * 64] = (f32x2){sa, sb};
	v_mul_f32_e32 v58, 0x3fb504f3, v57
	v_sub_f32_e32 v61, v60, v56
	v_sub_f32_e32 v60, v59, v56
	v_pk_mul_f32 v[60:61], v[60:61], v[58:59] op_sel_hi:[1,0]
	v_sub_f32_e32 v63, v63, v56
	v_pk_fma_f32 v[60:61], v[76:77], v[60:61], v[184:185]
	v_sub_f32_e32 v62, v62, v56
	v_pk_add_f32 v[44:45], v[44:45], v[60:61]
	v_sub_f32_e32 v61, v93, v56
	v_sub_f32_e32 v60, v92, v56
	v_sub_f32_e32 v57, v95, v56
	v_sub_f32_e32 v56, v94, v56
	v_pk_mul_f32 v[62:63], v[62:63], v[58:59] op_sel_hi:[1,0]
	v_pk_mul_f32 v[56:57], v[56:57], v[58:59] op_sel_hi:[1,0]
	v_pk_mul_f32 v[58:59], v[60:61], v[58:59] op_sel_hi:[1,0]
	v_cndmask_b32_e64 v40, v52, v40, s[10:11]
	v_cndmask_b32_e64 v43, v55, v43, s[10:11]
	v_cndmask_b32_e64 v42, v53, v42, s[10:11]
	v_pk_fma_f32 v[62:63], v[78:79], v[62:63], v[182:183]
	v_pk_fma_f32 v[58:59], v[72:73], v[58:59], v[180:181]
	v_pk_fma_f32 v[56:57], v[74:75], v[56:57], v[178:179]
	v_pk_add_f32 v[46:47], v[46:47], v[62:63]
	v_pk_add_f32 v[42:43], v[42:43], v[56:57]
	v_pk_add_f32 v[40:41], v[40:41], v[58:59]
	v_cvt_pk_bf16_f32 v56, v44, v45
	v_cvt_pk_bf16_f32 v57, v46, v47
	v_mov_b32_e32 v103, v165
	v_cvt_pk_bf16_f32 v58, v40, v41
	v_cvt_pk_bf16_f32 v59, v42, v43
	v_lshlrev_b32_e32 v40, 16, v56
	v_and_b32_e32 v42, 0xffff0000, v56
	v_lshlrev_b32_e32 v44, 16, v57
	v_and_b32_e32 v46, 0xffff0000, v57
	v_lshlrev_b32_e32 v60, 16, v58
	v_and_b32_e32 v62, 0xffff0000, v58
	v_lshlrev_b32_e32 v92, 16, v59
	v_and_b32_e32 v94, 0xffff0000, v59
	v_mul_f32_e32 v41, v40, v40
	v_mul_f32_e32 v43, v42, v42
	v_mul_f32_e32 v45, v44, v44
	v_mul_f32_e32 v47, v46, v46
	v_mul_f32_e32 v61, v60, v60
	v_mul_f32_e32 v63, v62, v62
	v_mul_f32_e32 v93, v92, v92
	v_mul_f32_e32 v95, v94, v94
	v_pk_add_f32 v[40:41], v[40:41], v[42:43]
	v_pk_add_f32 v[42:43], v[44:45], v[46:47]
	v_pk_add_f32 v[44:45], v[92:93], v[94:95]
	v_pk_add_f32 v[40:41], v[40:41], v[42:43]
	v_pk_add_f32 v[42:43], v[60:61], v[62:63]
	s_nop 0
	v_pk_add_f32 v[42:43], v[42:43], v[44:45]
	s_nop 0
	v_pk_add_f32 v[40:41], v[40:41], v[42:43]
	v_mov_b32_e32 v42, v165
	v_mov_b32_e32 v43, v165
	s_nop 0
	v_mov_b32_dpp v42, v40 quad_perm:[1,0,3,2] row_mask:0xf bank_mask:0xf
	v_mov_b32_dpp v43, v41 quad_perm:[1,0,3,2] row_mask:0xf bank_mask:0xf
	v_pk_add_f32 v[40:41], v[40:41], v[42:43]
	ds_bpermute_b32 v42, v207, v40
	ds_bpermute_b32 v43, v207, v41
	s_waitcnt lgkmcnt(0)
	v_pk_add_f32 v[42:43], v[40:41], v[42:43]
	ds_bpermute_b32 v44, v208, v42
	ds_bpermute_b32 v45, v208, v43
	v_lshl_add_u64 v[40:41], s[20:21], 0, v[102:103]
	global_store_dwordx4 v[40:41], v[56:59], off
	s_and_saveexec_b64 s[64:65], s[16:17]
	s_cbranch_execz .LBB0_1485
	s_waitcnt lgkmcnt(0)
	v_pk_add_f32 v[42:43], v[42:43], v[44:45]
	v_add_co_u32_e32 v44, vcc, 0x12000, v186
	s_nop 1
	v_addc_co_u32_e32 v45, vcc, 0, v187, vcc
	global_store_dwordx2 v[44:45], v[42:43], off
.LBB0_1485:
	s_or_b64 exec, exec, s[64:65]
	ds_read_b64 v[42:43], v201 offset:1160
	s_waitcnt lgkmcnt(1)
	v_lshlrev_b32_e32 v45, 16, v88
	v_and_b32_e32 v46, 0xffff0000, v88
	v_cndmask_b32_e64 v37, v37, v50, s[10:11]
	v_cndmask_b32_e64 v36, v36, v48, s[10:11]
	s_waitcnt lgkmcnt(0)
	v_mul_f32_e32 v44, 0x3fb504f3, v43
	v_sub_f32_e32 v47, v46, v42
	v_sub_f32_e32 v46, v45, v42
	v_pk_mul_f32 v[46:47], v[46:47], v[44:45] op_sel_hi:[1,0]
	v_cndmask_b32_e64 v39, v39, v51, s[10:11]
	v_cndmask_b32_e64 v38, v38, v49, s[10:11]
	v_cndmask_b32_e64 v32, v32, v52, s[10:11]
	v_cndmask_b32_e64 v34, v34, v53, s[10:11]
	v_lshlrev_b32_e32 v48, 16, v89
	v_and_b32_e32 v49, 0xffff0000, v89
	v_lshlrev_b32_e32 v50, 16, v90
	v_and_b32_e32 v51, 0xffff0000, v90
	v_lshlrev_b32_e32 v52, 16, v91
	v_and_b32_e32 v53, 0xffff0000, v91
	v_pk_fma_f32 v[46:47], v[76:77], v[46:47], v[184:185]
	v_sub_f32_e32 v49, v49, v42
	v_sub_f32_e32 v48, v48, v42
	v_pk_add_f32 v[36:37], v[36:37], v[46:47]
	v_sub_f32_e32 v47, v51, v42
	v_sub_f32_e32 v46, v50, v42
	v_sub_f32_e32 v43, v53, v42
	v_sub_f32_e32 v42, v52, v42
	v_pk_mul_f32 v[48:49], v[48:49], v[44:45] op_sel_hi:[1,0]
	v_pk_mul_f32 v[42:43], v[42:43], v[44:45] op_sel_hi:[1,0]
	v_pk_mul_f32 v[44:45], v[46:47], v[44:45] op_sel_hi:[1,0]
	v_cndmask_b32_e64 v33, v33, v54, s[10:11]
	v_cndmask_b32_e64 v35, v35, v55, s[10:11]
	v_pk_fma_f32 v[48:49], v[78:79], v[48:49], v[182:183]
	v_pk_fma_f32 v[44:45], v[72:73], v[44:45], v[180:181]
	v_pk_fma_f32 v[42:43], v[74:75], v[42:43], v[178:179]
	v_pk_add_f32 v[38:39], v[38:39], v[48:49]
	v_pk_add_f32 v[34:35], v[34:35], v[42:43]
	v_pk_add_f32 v[32:33], v[32:33], v[44:45]
	v_cvt_pk_bf16_f32 v36, v36, v37
	v_cvt_pk_bf16_f32 v37, v38, v39
	s_nop 0
	v_cvt_pk_bf16_f32 v38, v32, v33
	v_cvt_pk_bf16_f32 v39, v34, v35
	v_lshlrev_b32_e32 v32, 16, v36
	v_and_b32_e32 v34, 0xffff0000, v36
	v_lshlrev_b32_e32 v42, 16, v37
	v_and_b32_e32 v44, 0xffff0000, v37
	v_lshlrev_b32_e32 v46, 16, v38
	v_and_b32_e32 v48, 0xffff0000, v38
	v_lshlrev_b32_e32 v50, 16, v39
	v_and_b32_e32 v52, 0xffff0000, v39
	v_mul_f32_e32 v33, v32, v32
	v_mul_f32_e32 v35, v34, v34
	v_mul_f32_e32 v43, v42, v42
	v_mul_f32_e32 v45, v44, v44
	v_mul_f32_e32 v47, v46, v46
	v_mul_f32_e32 v49, v48, v48
	v_mul_f32_e32 v51, v50, v50
	v_mul_f32_e32 v53, v52, v52
	v_pk_add_f32 v[32:33], v[32:33], v[34:35]
	v_pk_add_f32 v[34:35], v[42:43], v[44:45]
	v_pk_add_f32 v[42:43], v[50:51], v[52:53]
	v_pk_add_f32 v[32:33], v[32:33], v[34:35]
	v_pk_add_f32 v[34:35], v[46:47], v[48:49]
	global_store_dwordx4 v[40:41], v[36:39], off offset:128
	v_pk_add_f32 v[34:35], v[34:35], v[42:43]
	s_nop 0
	v_pk_add_f32 v[32:33], v[32:33], v[34:35]
	v_mov_b32_e32 v34, v165
	v_mov_b32_e32 v35, v165
	s_nop 0
	v_mov_b32_dpp v34, v32 quad_perm:[1,0,3,2] row_mask:0xf bank_mask:0xf
	v_mov_b32_dpp v35, v33 quad_perm:[1,0,3,2] row_mask:0xf bank_mask:0xf
	v_pk_add_f32 v[32:33], v[32:33], v[34:35]
	ds_bpermute_b32 v34, v207, v32
	ds_bpermute_b32 v35, v207, v33
	s_waitcnt lgkmcnt(0)
	v_pk_add_f32 v[32:33], v[32:33], v[34:35]
	ds_bpermute_b32 v34, v208, v32
	ds_bpermute_b32 v35, v208, v33
	s_and_saveexec_b64 s[64:65], s[16:17]
	s_cbranch_execz .LBB0_1487
	s_waitcnt lgkmcnt(0)
	v_pk_add_f32 v[32:33], v[32:33], v[34:35]
	v_add_co_u32_e32 v34, vcc, 0x12000, v186
	s_nop 1
	v_addc_co_u32_e32 v35, vcc, 0, v187, vcc
	global_store_dwordx2 v[34:35], v[32:33], off offset:512
; __device__ __forceinline__ u32x4 pack8f(f32x4 a, f32x4 b) { u32x4 w; w.x = cvt_pk_bf16(a[0], a[1]); w.y = cvt_pk_bf16(a[2], a[3]); w.z = cvt_pk_bf16(b[0], b[1]); w.w = cvt_pk_bf16(b[2], b[3]); return w; }
;     __device__ __forceinline__ void operator()(const f32x4 (&acc)[2][2][4][2], const Unit& u, int wr, int wc, int fr, int fq, const EpiCtx& X) const {
;     ...
;             for (int m = 0; m < 4; ++m) {
;                 const int rl = ai * HALF + m * 16; const unsigned off = lo + (unsigned)(rl * 64) * 2u;
;                 const f32x4 o0a = acc[ai][0][m][0], o0b = acc[ai][0][m][1], o1a = acc[ai][1][m][0], o1b = acc[ai][1][m][1];
;                 const f32x4 ra_ = dpp_swap1(odd ? o0a : o1a), rb_ = dpp_swap1(odd ? o0b : o1b);
;                 const f32x4 pa[2] = {odd ? ra_ : o0a, odd ? o1a : ra_}, pb[2] = {odd ? rb_ : o0b, odd ? o1b : rb_};
; #pragma unroll
;                 for (int q = 0; q < 2; ++q) {
;                     const u32x4 w0 = raw[2 * m + q];
;                     const f32x4 r0 = (f32x4){bf_lo(w0.x), bf_hi(w0.x), bf_lo(w0.y), bf_hi(w0.y)}, r1 = (f32x4){bf_lo(w0.z), bf_hi(w0.z), bf_lo(w0.w), bf_hi(w0.w)};
;                     f32x4 y0, y1;
;                     if (RESN) { const f32x2 t = tbl[rl + q]; const float mu = t.x, ra = t.y * ALPHA; y0 = (r0 - mu) * ra * g0 + b0 + pa[q]; y1 = (r1 - mu) * ra * g1 + b1 + pb[q]; }
;                     else { y0 = r0 * ALPHA + pa[q]; y1 = r1 * ALPHA + pb[q]; }
;                     { const u32x4 w = pack8f(y0, y1); *(u32x4*)(xb + off + q * 128) = w;
;                         y0 = (f32x4){bf_lo(w.x), bf_hi(w.x), bf_lo(w.y), bf_hi(w.y)}; y1 = (f32x4){bf_lo(w.z), bf_hi(w.z), bf_lo(w.w), bf_hi(w.w)}; }
;                     float sa = ((y0[0] + y0[1]) + (y0[2] + y0[3])) + ((y1[0] + y1[1]) + (y1[2] + y1[3]));
;                     float sb = ((y0[0] * y0[0] + y0[1] * y0[1]) + (y0[2] * y0[2] + y0[3] * y0[3])) + ((y1[0] * y1[0] + y1[1] * y1[1]) + (y1[2] * y1[2] + y1[3] * y1[3]));
;                     sa += dpp_x1(sa);
;                     sb += dpp_x1(sb);
;                     sa += __shfl_xor(sa, 16); sa += __shfl_xor(sa, 32); sb += __shfl_xor(sb, 16); sb += __shfl_xor(sb, 32);
;                     if (fq == 0 && !odd) ps[(size_t)(rl + q) * 64] = (f32x2){sa, sb};
.LBB0_1487:
	s_or_b64 exec, exec, s[64:65]
	s_waitcnt lgkmcnt(1)
	v_cndmask_b32_e64 v34, v28, v20, s[10:11]
	v_mov_b32_e32 v32, 0
	v_cndmask_b32_e64 v33, v29, v21, s[10:11]
	s_waitcnt lgkmcnt(0)
	v_cndmask_b32_e64 v35, v30, v22, s[10:11]
	v_mov_b32_dpp v32, v34 quad_perm:[1,0,3,2] row_mask:0xf bank_mask:0xf
	v_mov_b32_e32 v34, 0
	v_cndmask_b32_e64 v36, v31, v23, s[10:11]
	v_cndmask_b32_e64 v38, v24, v16, s[10:11]
	v_mov_b32_dpp v34, v33 quad_perm:[1,0,3,2] row_mask:0xf bank_mask:0xf
	v_mov_b32_e32 v33, 0
	v_cndmask_b32_e64 v37, v25, v17, s[10:11]
	v_cndmask_b32_e64 v39, v26, v18, s[10:11]
	v_mov_b32_dpp v33, v35 quad_perm:[1,0,3,2] row_mask:0xf bank_mask:0xf
	v_mov_b32_e32 v35, 0
	v_cndmask_b32_e64 v40, v27, v19, s[10:11]
	s_waitcnt vmcnt(11)
	v_lshlrev_b32_e32 v43, 16, v84
	v_mov_b32_dpp v35, v36 quad_perm:[1,0,3,2] row_mask:0xf bank_mask:0xf
	v_mov_b32_e32 v36, 0
	v_and_b32_e32 v44, 0xffff0000, v84
	v_cndmask_b32_e64 v29, v34, v29, s[10:11]
	v_mov_b32_dpp v36, v38 quad_perm:[1,0,3,2] row_mask:0xf bank_mask:0xf
	v_mov_b32_e32 v38, 0
	v_cndmask_b32_e64 v28, v32, v28, s[10:11]
	v_lshlrev_b32_e32 v46, 16, v85
	v_mov_b32_dpp v38, v37 quad_perm:[1,0,3,2] row_mask:0xf bank_mask:0xf
	v_mov_b32_e32 v37, 0
	v_and_b32_e32 v47, 0xffff0000, v85
	v_lshlrev_b32_e32 v48, 16, v86
	v_mov_b32_dpp v37, v39 quad_perm:[1,0,3,2] row_mask:0xf bank_mask:0xf
	v_mov_b32_e32 v39, 0
	v_and_b32_e32 v49, 0xffff0000, v86
	v_lshlrev_b32_e32 v50, 16, v87
	v_mov_b32_dpp v39, v40 quad_perm:[1,0,3,2] row_mask:0xf bank_mask:0xf
	ds_read_b64 v[40:41], v201 offset:1280
	v_and_b32_e32 v51, 0xffff0000, v87
	v_cndmask_b32_e64 v31, v35, v31, s[10:11]
	v_cndmask_b32_e64 v30, v33, v30, s[10:11]
	v_cndmask_b32_e64 v25, v38, v25, s[10:11]
	s_waitcnt lgkmcnt(0)
	v_mul_f32_e32 v42, 0x3fb504f3, v41
	v_sub_f32_e32 v45, v44, v40
	v_sub_f32_e32 v44, v43, v40
	v_pk_mul_f32 v[44:45], v[44:45], v[42:43] op_sel_hi:[1,0]
	v_sub_f32_e32 v47, v47, v40
	v_pk_fma_f32 v[44:45], v[76:77], v[44:45], v[184:185]
	v_sub_f32_e32 v46, v46, v40
	v_pk_add_f32 v[28:29], v[28:29], v[44:45]
	v_sub_f32_e32 v45, v49, v40
	v_sub_f32_e32 v44, v48, v40
	v_sub_f32_e32 v41, v51, v40
	v_sub_f32_e32 v40, v50, v40
	v_pk_mul_f32 v[46:47], v[46:47], v[42:43] op_sel_hi:[1,0]
	v_pk_mul_f32 v[40:41], v[40:41], v[42:43] op_sel_hi:[1,0]
	v_pk_mul_f32 v[42:43], v[44:45], v[42:43] op_sel_hi:[1,0]
	v_cndmask_b32_e64 v24, v36, v24, s[10:11]
	v_cndmask_b32_e64 v27, v39, v27, s[10:11]
	v_cndmask_b32_e64 v26, v37, v26, s[10:11]
	v_pk_fma_f32 v[46:47], v[78:79], v[46:47], v[182:183]
	v_pk_fma_f32 v[42:43], v[72:73], v[42:43], v[180:181]
	v_pk_fma_f32 v[40:41], v[74:75], v[40:41], v[178:179]
	v_pk_add_f32 v[30:31], v[30:31], v[46:47]
	v_pk_add_f32 v[26:27], v[26:27], v[40:41]
	v_pk_add_f32 v[24:25], v[24:25], v[42:43]
	v_cvt_pk_bf16_f32 v40, v28, v29
	v_cvt_pk_bf16_f32 v41, v30, v31
	v_mov_b32_e32 v101, v165
	v_cvt_pk_bf16_f32 v42, v24, v25
	v_cvt_pk_bf16_f32 v43, v26, v27
	v_lshlrev_b32_e32 v24, 16, v40
	v_and_b32_e32 v26, 0xffff0000, v40
	v_lshlrev_b32_e32 v28, 16, v41
	v_and_b32_e32 v30, 0xffff0000, v41
	v_lshlrev_b32_e32 v44, 16, v42
	v_and_b32_e32 v46, 0xffff0000, v42
	v_lshlrev_b32_e32 v48, 16, v43
	v_and_b32_e32 v50, 0xffff0000, v43
	v_mul_f32_e32 v25, v24, v24
	v_mul_f32_e32 v27, v26, v26
	v_mul_f32_e32 v29, v28, v28
	v_mul_f32_e32 v31, v30, v30
	v_mul_f32_e32 v45, v44, v44
	v_mul_f32_e32 v47, v46, v46
	v_mul_f32_e32 v49, v48, v48
	v_mul_f32_e32 v51, v50, v50
	v_pk_add_f32 v[24:25], v[24:25], v[26:27]
	v_pk_add_f32 v[26:27], v[28:29], v[30:31]
	v_pk_add_f32 v[28:29], v[48:49], v[50:51]
	v_pk_add_f32 v[24:25], v[24:25], v[26:27]
	v_pk_add_f32 v[26:27], v[44:45], v[46:47]
	s_nop 0
	v_pk_add_f32 v[26:27], v[26:27], v[28:29]
	s_nop 0
	v_pk_add_f32 v[24:25], v[24:25], v[26:27]
	v_mov_b32_e32 v26, v165
	v_mov_b32_e32 v27, v165
	s_nop 0
	v_mov_b32_dpp v26, v24 quad_perm:[1,0,3,2] row_mask:0xf bank_mask:0xf
	v_mov_b32_dpp v27, v25 quad_perm:[1,0,3,2] row_mask:0xf bank_mask:0xf
	v_pk_add_f32 v[24:25], v[24:25], v[26:27]
	ds_bpermute_b32 v26, v207, v24
	ds_bpermute_b32 v27, v207, v25
	s_waitcnt lgkmcnt(0)
	v_pk_add_f32 v[26:27], v[24:25], v[26:27]
	ds_bpermute_b32 v28, v208, v26
	ds_bpermute_b32 v29, v208, v27
	v_lshl_add_u64 v[24:25], s[20:21], 0, v[100:101]
	global_store_dwordx4 v[24:25], v[40:43], off
	s_and_saveexec_b64 s[64:65], s[16:17]
	s_cbranch_execz .LBB0_1489
	s_waitcnt lgkmcnt(0)
	v_pk_add_f32 v[26:27], v[26:27], v[28:29]
	v_add_co_u32_e32 v28, vcc, 0x14000, v186
	s_nop 1
	v_addc_co_u32_e32 v29, vcc, 0, v187, vcc
	global_store_dwordx2 v[28:29], v[26:27], off
; __device__ __forceinline__ u32x4 pack8f(f32x4 a, f32x4 b) { u32x4 w; w.x = cvt_pk_bf16(a[0], a[1]); w.y = cvt_pk_bf16(a[2], a[3]); w.z = cvt_pk_bf16(b[0], b[1]); w.w = cvt_pk_bf16(b[2], b[3]); return w; }
;     __device__ __forceinline__ void operator()(const f32x4 (&acc)[2][2][4][2], const Unit& u, int wr, int wc, int fr, int fq, const EpiCtx& X) const {
;     ...
;             for (int m = 0; m < 4; ++m) {
;                 const int rl = ai * HALF + m * 16; const unsigned off = lo + (unsigned)(rl * 64) * 2u;
;                 const f32x4 o0a = acc[ai][0][m][0], o0b = acc[ai][0][m][1], o1a = acc[ai][1][m][0], o1b = acc[ai][1][m][1];
;                 const f32x4 ra_ = dpp_swap1(odd ? o0a : o1a), rb_ = dpp_swap1(odd ? o0b : o1b);
;                 const f32x4 pa[2] = {odd ? ra_ : o0a, odd ? o1a : ra_}, pb[2] = {odd ? rb_ : o0b, odd ? o1b : rb_};
; #pragma unroll
;                 for (int q = 0; q < 2; ++q) {
;                     const u32x4 w0 = raw[2 * m + q];
;                     const f32x4 r0 = (f32x4){bf_lo(w0.x), bf_hi(w0.x), bf_lo(w0.y), bf_hi(w0.y)}, r1 = (f32x4){bf_lo(w0.z), bf_hi(w0.z), bf_lo(w0.w), bf_hi(w0.w)};
;                     f32x4 y0, y1;
;                     if (RESN) { const f32x2 t = tbl[rl + q]; const float mu = t.x, ra = t.y * ALPHA; y0 = (r0 - mu) * ra * g0 + b0 + pa[q]; y1 = (r1 - mu) * ra * g1 + b1 + pb[q]; }
;                     else { y0 = r0 * ALPHA + pa[q]; y1 = r1 * ALPHA + pb[q]; }
;                     { const u32x4 w = pack8f(y0, y1); *(u32x4*)(xb + off + q * 128) = w;
;                         y0 = (f32x4){bf_lo(w.x), bf_hi(w.x), bf_lo(w.y), bf_hi(w.y)}; y1 = (f32x4){bf_lo(w.z), bf_hi(w.z), bf_lo(w.w), bf_hi(w.w)}; }
;                     float sa = ((y0[0] + y0[1]) + (y0[2] + y0[3])) + ((y1[0] + y1[1]) + (y1[2] + y1[3]));
;                     float sb = ((y0[0] * y0[0] + y0[1] * y0[1]) + (y0[2] * y0[2] + y0[3] * y0[3])) + ((y1[0] * y1[0] + y1[1] * y1[1]) + (y1[2] * y1[2] + y1[3] * y1[3]));
;                     sa += dpp_x1(sa);
;                     sb += dpp_x1(sb);
;                     sa += __shfl_xor(sa, 16); sa += __shfl_xor(sa, 32); sb += __shfl_xor(sb, 16); sb += __shfl_xor(sb, 32);
;                     if (fq == 0 && !odd) ps[(size_t)(rl + q) * 64] = (f32x2){sa, sb};
.LBB0_1489:
	s_or_b64 exec, exec, s[64:65]
	ds_read_b64 v[26:27], v201 offset:1288
	s_waitcnt vmcnt(12) lgkmcnt(1)
	v_lshlrev_b32_e32 v29, 16, v80
	v_and_b32_e32 v30, 0xffff0000, v80
	v_cndmask_b32_e64 v21, v21, v34, s[10:11]
	v_cndmask_b32_e64 v20, v20, v32, s[10:11]
	s_waitcnt lgkmcnt(0)
	v_mul_f32_e32 v28, 0x3fb504f3, v27
	v_sub_f32_e32 v31, v30, v26
	v_sub_f32_e32 v30, v29, v26
	v_pk_mul_f32 v[30:31], v[30:31], v[28:29] op_sel_hi:[1,0]
	v_cndmask_b32_e64 v23, v23, v35, s[10:11]
	v_cndmask_b32_e64 v22, v22, v33, s[10:11]
	v_cndmask_b32_e64 v16, v16, v36, s[10:11]
	v_cndmask_b32_e64 v18, v18, v37, s[10:11]
	v_lshlrev_b32_e32 v32, 16, v81
	v_and_b32_e32 v33, 0xffff0000, v81
	v_lshlrev_b32_e32 v34, 16, v82
	v_and_b32_e32 v35, 0xffff0000, v82
	v_lshlrev_b32_e32 v36, 16, v83
	v_and_b32_e32 v37, 0xffff0000, v83
	v_pk_fma_f32 v[30:31], v[76:77], v[30:31], v[184:185]
	v_sub_f32_e32 v33, v33, v26
	v_sub_f32_e32 v32, v32, v26
	v_pk_add_f32 v[20:21], v[20:21], v[30:31]
	v_sub_f32_e32 v31, v35, v26
	v_sub_f32_e32 v30, v34, v26
	v_sub_f32_e32 v27, v37, v26
	v_sub_f32_e32 v26, v36, v26
	v_pk_mul_f32 v[32:33], v[32:33], v[28:29] op_sel_hi:[1,0]
	v_pk_mul_f32 v[26:27], v[26:27], v[28:29] op_sel_hi:[1,0]
	v_pk_mul_f32 v[28:29], v[30:31], v[28:29] op_sel_hi:[1,0]
	v_cndmask_b32_e64 v17, v17, v38, s[10:11]
	v_cndmask_b32_e64 v19, v19, v39, s[10:11]
	v_pk_fma_f32 v[32:33], v[78:79], v[32:33], v[182:183]
	v_pk_fma_f32 v[28:29], v[72:73], v[28:29], v[180:181]
	v_pk_fma_f32 v[26:27], v[74:75], v[26:27], v[178:179]
	v_pk_add_f32 v[22:23], v[22:23], v[32:33]
	v_pk_add_f32 v[18:19], v[18:19], v[26:27]
	v_pk_add_f32 v[16:17], v[16:17], v[28:29]
	v_cvt_pk_bf16_f32 v20, v20, v21
	v_cvt_pk_bf16_f32 v21, v22, v23
	s_nop 0
	v_cvt_pk_bf16_f32 v22, v16, v17
	v_cvt_pk_bf16_f32 v23, v18, v19
	v_lshlrev_b32_e32 v16, 16, v20
	v_and_b32_e32 v18, 0xffff0000, v20
	v_lshlrev_b32_e32 v26, 16, v21
	v_and_b32_e32 v28, 0xffff0000, v21
	v_lshlrev_b32_e32 v30, 16, v22
	v_and_b32_e32 v32, 0xffff0000, v22
	v_lshlrev_b32_e32 v34, 16, v23
	v_and_b32_e32 v36, 0xffff0000, v23
	v_mul_f32_e32 v17, v16, v16
	v_mul_f32_e32 v19, v18, v18
	v_mul_f32_e32 v27, v26, v26
	v_mul_f32_e32 v29, v28, v28
	v_mul_f32_e32 v31, v30, v30
	v_mul_f32_e32 v33, v32, v32
	v_mul_f32_e32 v35, v34, v34
	v_mul_f32_e32 v37, v36, v36
	v_pk_add_f32 v[16:17], v[16:17], v[18:19]
	v_pk_add_f32 v[18:19], v[26:27], v[28:29]
	v_pk_add_f32 v[26:27], v[34:35], v[36:37]
	v_pk_add_f32 v[16:17], v[16:17], v[18:19]
	v_pk_add_f32 v[18:19], v[30:31], v[32:33]
	global_store_dwordx4 v[24:25], v[20:23], off offset:128
	v_pk_add_f32 v[18:19], v[18:19], v[26:27]
	s_nop 0
	v_pk_add_f32 v[16:17], v[16:17], v[18:19]
	v_mov_b32_e32 v18, v165
	v_mov_b32_e32 v19, v165
	s_nop 0
	v_mov_b32_dpp v18, v16 quad_perm:[1,0,3,2] row_mask:0xf bank_mask:0xf
	v_mov_b32_dpp v19, v17 quad_perm:[1,0,3,2] row_mask:0xf bank_mask:0xf
	v_pk_add_f32 v[16:17], v[16:17], v[18:19]
	ds_bpermute_b32 v18, v207, v16
	ds_bpermute_b32 v19, v207, v17
	s_waitcnt lgkmcnt(0)
	v_pk_add_f32 v[16:17], v[16:17], v[18:19]
	ds_bpermute_b32 v18, v208, v16
	ds_bpermute_b32 v19, v208, v17
	s_and_saveexec_b64 s[64:65], s[16:17]
	s_cbranch_execz .LBB0_1491
	s_waitcnt lgkmcnt(0)
	v_pk_add_f32 v[16:17], v[16:17], v[18:19]
	v_add_co_u32_e32 v18, vcc, 0x14000, v186
	s_nop 1
	v_addc_co_u32_e32 v19, vcc, 0, v187, vcc
	global_store_dwordx2 v[18:19], v[16:17], off offset:512
; __device__ __forceinline__ u32x4 pack8f(f32x4 a, f32x4 b) { u32x4 w; w.x = cvt_pk_bf16(a[0], a[1]); w.y = cvt_pk_bf16(a[2], a[3]); w.z = cvt_pk_bf16(b[0], b[1]); w.w = cvt_pk_bf16(b[2], b[3]); return w; }
;     __device__ __forceinline__ void operator()(const f32x4 (&acc)[2][2][4][2], const Unit& u, int wr, int wc, int fr, int fq, const EpiCtx& X) const {
;     ...
;             for (int m = 0; m < 4; ++m) {
;                 const int rl = ai * HALF + m * 16; const unsigned off = lo + (unsigned)(rl * 64) * 2u;
;                 const f32x4 o0a = acc[ai][0][m][0], o0b = acc[ai][0][m][1], o1a = acc[ai][1][m][0], o1b = acc[ai][1][m][1];
;                 const f32x4 ra_ = dpp_swap1(odd ? o0a : o1a), rb_ = dpp_swap1(odd ? o0b : o1b);
;                 const f32x4 pa[2] = {odd ? ra_ : o0a, odd ? o1a : ra_}, pb[2] = {odd ? rb_ : o0b, odd ? o1b : rb_};
; #pragma unroll
;                 for (int q = 0; q < 2; ++q) {
;                     const u32x4 w0 = raw[2 * m + q];
;                     const f32x4 r0 = (f32x4){bf_lo(w0.x), bf_hi(w0.x), bf_lo(w0.y), bf_hi(w0.y)}, r1 = (f32x4){bf_lo(w0.z), bf_hi(w0.z), bf_lo(w0.w), bf_hi(w0.w)};
;                     f32x4 y0, y1;
;                     if (RESN) { const f32x2 t = tbl[rl + q]; const float mu = t.x, ra = t.y * ALPHA; y0 = (r0 - mu) * ra * g0 + b0 + pa[q]; y1 = (r1 - mu) * ra * g1 + b1 + pb[q]; }
;                     else { y0 = r0 * ALPHA + pa[q]; y1 = r1 * ALPHA + pb[q]; }
;                     { const u32x4 w = pack8f(y0, y1); *(u32x4*)(xb + off + q * 128) = w;
;                         y0 = (f32x4){bf_lo(w.x), bf_hi(w.x), bf_lo(w.y), bf_hi(w.y)}; y1 = (f32x4){bf_lo(w.z), bf_hi(w.z), bf_lo(w.w), bf_hi(w.w)}; }
;                     float sa = ((y0[0] + y0[1]) + (y0[2] + y0[3])) + ((y1[0] + y1[1]) + (y1[2] + y1[3]));
;                     float sb = ((y0[0] * y0[0] + y0[1] * y0[1]) + (y0[2] * y0[2] + y0[3] * y0[3])) + ((y1[0] * y1[0] + y1[1] * y1[1]) + (y1[2] * y1[2] + y1[3] * y1[3]));
;                     sa += dpp_x1(sa);
;                     sb += dpp_x1(sb);
;                     sa += __shfl_xor(sa, 16); sa += __shfl_xor(sa, 32); sb += __shfl_xor(sb, 16); sb += __shfl_xor(sb, 32);
;                     if (fq == 0 && !odd) ps[(size_t)(rl + q) * 64] = (f32x2){sa, sb};
.LBB0_1491:
	s_or_b64 exec, exec, s[64:65]
	s_waitcnt lgkmcnt(1)
	v_cndmask_b32_e64 v18, v12, v4, s[10:11]
	v_mov_b32_e32 v16, 0
	v_cndmask_b32_e64 v17, v13, v5, s[10:11]
	s_waitcnt lgkmcnt(0)
	v_cndmask_b32_e64 v19, v14, v6, s[10:11]
	v_mov_b32_dpp v16, v18 quad_perm:[1,0,3,2] row_mask:0xf bank_mask:0xf
	v_mov_b32_e32 v18, 0
	v_cndmask_b32_e64 v20, v15, v7, s[10:11]
	v_cndmask_b32_e64 v22, v8, v0, s[10:11]
	v_mov_b32_dpp v18, v17 quad_perm:[1,0,3,2] row_mask:0xf bank_mask:0xf
	v_mov_b32_e32 v17, 0
	v_cndmask_b32_e64 v21, v9, v1, s[10:11]
	v_cndmask_b32_e64 v23, v10, v2, s[10:11]
	v_mov_b32_dpp v17, v19 quad_perm:[1,0,3,2] row_mask:0xf bank_mask:0xf
	v_mov_b32_e32 v19, 0
	v_cndmask_b32_e64 v24, v11, v3, s[10:11]
	s_waitcnt vmcnt(13)
	v_lshlrev_b32_e32 v27, 16, v68
	v_mov_b32_dpp v19, v20 quad_perm:[1,0,3,2] row_mask:0xf bank_mask:0xf
	v_mov_b32_e32 v20, 0
	v_and_b32_e32 v28, 0xffff0000, v68
	v_cndmask_b32_e64 v13, v18, v13, s[10:11]
	v_mov_b32_dpp v20, v22 quad_perm:[1,0,3,2] row_mask:0xf bank_mask:0xf
	v_mov_b32_e32 v22, 0
	v_cndmask_b32_e64 v12, v16, v12, s[10:11]
	v_lshlrev_b32_e32 v30, 16, v69
	v_mov_b32_dpp v22, v21 quad_perm:[1,0,3,2] row_mask:0xf bank_mask:0xf
	v_mov_b32_e32 v21, 0
	v_and_b32_e32 v31, 0xffff0000, v69
	v_lshlrev_b32_e32 v32, 16, v70
	v_mov_b32_dpp v21, v23 quad_perm:[1,0,3,2] row_mask:0xf bank_mask:0xf
	v_mov_b32_e32 v23, 0
	v_and_b32_e32 v33, 0xffff0000, v70
	v_lshlrev_b32_e32 v34, 16, v71
	v_mov_b32_dpp v23, v24 quad_perm:[1,0,3,2] row_mask:0xf bank_mask:0xf
	ds_read_b64 v[24:25], v201 offset:1408
	v_and_b32_e32 v35, 0xffff0000, v71
	v_cndmask_b32_e64 v15, v19, v15, s[10:11]
	v_cndmask_b32_e64 v14, v17, v14, s[10:11]
	v_cndmask_b32_e64 v9, v22, v9, s[10:11]
	s_waitcnt lgkmcnt(0)
	v_mul_f32_e32 v26, 0x3fb504f3, v25
	v_sub_f32_e32 v29, v28, v24
	v_sub_f32_e32 v28, v27, v24
	v_pk_mul_f32 v[28:29], v[28:29], v[26:27] op_sel_hi:[1,0]
	v_sub_f32_e32 v31, v31, v24
	v_pk_fma_f32 v[28:29], v[76:77], v[28:29], v[184:185]
	v_sub_f32_e32 v30, v30, v24
	v_pk_add_f32 v[12:13], v[12:13], v[28:29]
	v_sub_f32_e32 v29, v33, v24
	v_sub_f32_e32 v28, v32, v24
	v_sub_f32_e32 v25, v35, v24
	v_sub_f32_e32 v24, v34, v24
	v_pk_mul_f32 v[30:31], v[30:31], v[26:27] op_sel_hi:[1,0]
	v_pk_mul_f32 v[24:25], v[24:25], v[26:27] op_sel_hi:[1,0]
	v_pk_mul_f32 v[26:27], v[28:29], v[26:27] op_sel_hi:[1,0]
	v_cndmask_b32_e64 v8, v20, v8, s[10:11]
	v_cndmask_b32_e64 v11, v23, v11, s[10:11]
	v_cndmask_b32_e64 v10, v21, v10, s[10:11]
	v_pk_fma_f32 v[30:31], v[78:79], v[30:31], v[182:183]
	v_pk_fma_f32 v[26:27], v[72:73], v[26:27], v[180:181]
	v_pk_fma_f32 v[24:25], v[74:75], v[24:25], v[178:179]
	v_pk_add_f32 v[14:15], v[14:15], v[30:31]
	v_pk_add_f32 v[10:11], v[10:11], v[24:25]
	v_pk_add_f32 v[8:9], v[8:9], v[26:27]
	v_cvt_pk_bf16_f32 v24, v12, v13
	v_cvt_pk_bf16_f32 v25, v14, v15
	s_nop 0
	v_cvt_pk_bf16_f32 v26, v8, v9
	v_cvt_pk_bf16_f32 v27, v10, v11
	v_lshlrev_b32_e32 v8, 16, v24
	v_and_b32_e32 v10, 0xffff0000, v24
	v_lshlrev_b32_e32 v12, 16, v25
	v_and_b32_e32 v14, 0xffff0000, v25
	v_lshlrev_b32_e32 v28, 16, v26
	v_and_b32_e32 v30, 0xffff0000, v26
	v_lshlrev_b32_e32 v32, 16, v27
	v_and_b32_e32 v34, 0xffff0000, v27
	v_mul_f32_e32 v9, v8, v8
	v_mul_f32_e32 v11, v10, v10
	v_mul_f32_e32 v13, v12, v12
	v_mul_f32_e32 v15, v14, v14
	v_mul_f32_e32 v29, v28, v28
	v_mul_f32_e32 v31, v30, v30
	v_mul_f32_e32 v33, v32, v32
	v_mul_f32_e32 v35, v34, v34
	v_pk_add_f32 v[8:9], v[8:9], v[10:11]
	v_pk_add_f32 v[10:11], v[12:13], v[14:15]
	v_pk_add_f32 v[12:13], v[32:33], v[34:35]
	v_pk_add_f32 v[8:9], v[8:9], v[10:11]
	v_pk_add_f32 v[10:11], v[28:29], v[30:31]
	s_nop 0
	v_pk_add_f32 v[10:11], v[10:11], v[12:13]
	s_nop 0
	v_pk_add_f32 v[8:9], v[8:9], v[10:11]
	v_mov_b32_e32 v10, v165
	v_mov_b32_e32 v11, v165
	s_nop 0
	v_mov_b32_dpp v10, v8 quad_perm:[1,0,3,2] row_mask:0xf bank_mask:0xf
	v_mov_b32_dpp v11, v9 quad_perm:[1,0,3,2] row_mask:0xf bank_mask:0xf
	v_pk_add_f32 v[8:9], v[8:9], v[10:11]
	ds_bpermute_b32 v10, v207, v8
	ds_bpermute_b32 v11, v207, v9
	s_waitcnt lgkmcnt(0)
	v_pk_add_f32 v[10:11], v[8:9], v[10:11]
	ds_bpermute_b32 v12, v208, v10
	ds_bpermute_b32 v13, v208, v11
	v_lshl_add_u64 v[8:9], s[20:21], 0, v[164:165]
	global_store_dwordx4 v[8:9], v[24:27], off
	s_and_saveexec_b64 s[20:21], s[16:17]
	s_cbranch_execz .LBB0_1493
	s_waitcnt lgkmcnt(0)
	v_pk_add_f32 v[10:11], v[10:11], v[12:13]
	v_add_co_u32_e32 v12, vcc, 0x16000, v186
	s_nop 1
	v_addc_co_u32_e32 v13, vcc, 0, v187, vcc
	global_store_dwordx2 v[12:13], v[10:11], off

; #define LAS __attribute__((address_space(3)))
;     __device__ __forceinline__ void operator()(const f32x4 (&acc)[2][2][4][2], const Unit& u, int wr, int wc, int fr, int fq, const EpiCtx& X) const {
;     ...
;         char* yb = nullptr; char* xb = (char*)(XB + (size_t)u.pm * BM * DM + (size_t)(u.pn * 4 + wc) * (BM * 64));
;         unsigned lo = (unsigned)((wr * 64 + fe) * 64 + o32 + 8 * fq) * 2u; EPI_OPAQUE(lo);
;         const int col = u.pn * BM + wc * 64 + o32 + 8 * fq;
;         f32x4 g0, g1, b0, b1;
;         if (RESN) { ensure_tbl(PSp, sidp, u.pm, X);
;             g0 = *(const f32x4*)(gp + col); g1 = *(const f32x4*)(gp + col + 4); b0 = *(const f32x4*)(bp + col) * ALPHA; b1 = *(const f32x4*)(bp + col + 4) * ALPHA; }
;         const LAS f32x2* tbl = (const LAS f32x2*)(X.lds + TBL_OFF) + wr * 64 + fe;
;         f32x2* ps = PSn + ((size_t)u.pm * BM + wr * 64 + fe) * 64 + u.pn * 4 + wc;
; #pragma unroll
;         for (int ai = 0; ai < 2; ++ai) {
;             u32x4 raw[8];
; #pragma unroll
;             for (int m = 0; m < 4; ++m) { const unsigned off = lo + (unsigned)((ai * HALF + m * 16) * 64) * 2u; raw[2 * m] = *(const u32x4*)(xb + off); raw[2 * m + 1] = *(const u32x4*)(xb + off + 128); }
; #pragma unroll
;             for (int m = 0; m < 4; ++m) {
;                 const int rl = ai * HALF + m * 16; const unsigned off = lo + (unsigned)(rl * 64) * 2u;
;                 const f32x4 o0a = acc[ai][0][m][0], o0b = acc[ai][0][m][1], o1a = acc[ai][1][m][0], o1b = acc[ai][1][m][1];
;                 const f32x4 ra_ = dpp_swap1(odd ? o0a : o1a), rb_ = dpp_swap1(odd ? o0b : o1b);
;                 const f32x4 pa[2] = {odd ? ra_ : o0a, odd ? o1a : ra_}, pb[2] = {odd ? rb_ : o0b, odd ? o1b : rb_};
; #pragma unroll
;                 for (int q = 0; q < 2; ++q) {
;                     const u32x4 w0 = raw[2 * m + q];
;                     const f32x4 r0 = (f32x4){bf_lo(w0.x), bf_hi(w0.x), bf_lo(w0.y), bf_hi(w0.y)}, r1 = (f32x4){bf_lo(w0.z), bf_hi(w0.z), bf_lo(w0.w), bf_hi(w0.w)};
;                     f32x4 y0, y1;
;                     if (RESN) { const f32x2 t = tbl[rl + q]; const float mu = t.x, ra = t.y * ALPHA; y0 = (r0 - mu) * ra * g0 + b0 + pa[q]; y1 = (r1 - mu) * ra * g1 + b1 + pb[q]; }
;                     else { y0 = r0 * ALPHA + pa[q]; y1 = r1 * ALPHA + pb[q]; }
;                     { const u32x4 w = pack8f(y0, y1); *(u32x4*)(xb + off + q * 128) = w;
.LBB0_1697:
	s_lshl_b64 s[16:17], s[58:59], 21
	s_add_u32 s35, s31, s16
	s_addc_u32 s38, s68, s17
	s_lshl_b32 s58, s56, 2
	s_or_b32 s16, s58, s41
	s_ashr_i32 s17, s16, 31
	v_lshl_add_u32 v72, s56, 8, v200
	v_ashrrev_i32_e32 v73, 31, v72
	s_lshl_b64 s[16:17], s[16:17], 15
	v_lshlrev_b64 v[72:73], 2, v[72:73]
	s_add_u32 s16, s35, s16
	v_lshl_add_u64 v[74:75], s[26:27], 0, v[72:73]
	s_addc_u32 s17, s38, s17
	global_load_dwordx4 v[194:197], v[74:75], off offset:16
	global_load_dwordx4 v[178:181], v[74:75], off
	global_load_dwordx4 v[214:217], v164, s[16:17]
	v_lshl_add_u64 v[72:73], s[24:25], 0, v[72:73]
	s_waitcnt lgkmcnt(0)
	global_load_dwordx4 v[76:79], v[72:73], off
	s_nop 0
	global_load_dwordx4 v[72:75], v[72:73], off offset:16
	v_cndmask_b32_e64 v136, v135, v127, s[6:7]
	v_cndmask_b32_e64 v137, v134, v126, s[6:7]
	v_cndmask_b32_e64 v138, v133, v125, s[6:7]
	v_cndmask_b32_e64 v139, v132, v124, s[6:7]
	v_mov_b32_e32 v189, 0
	v_mov_b32_e32 v193, 0
	v_mov_b32_e32 v191, 0
	v_mov_b32_e32 v209, 0
	v_cndmask_b32_e64 v140, v131, v123, s[6:7]
	v_cndmask_b32_e64 v141, v130, v122, s[6:7]
	v_cndmask_b32_e64 v142, v129, v121, s[6:7]
	v_cndmask_b32_e64 v143, v128, v120, s[6:7]
	v_mov_b32_e32 v210, 0
	v_mov_b32_e32 v212, 0
	v_mov_b32_e32 v211, 0
	v_mov_b32_e32 v213, 0
	v_mov_b32_dpp v189, v139 quad_perm:[1,0,3,2] row_mask:0xf bank_mask:0xf
	v_mov_b32_dpp v193, v138 quad_perm:[1,0,3,2] row_mask:0xf bank_mask:0xf
	v_mov_b32_dpp v191, v137 quad_perm:[1,0,3,2] row_mask:0xf bank_mask:0xf
	v_mov_b32_dpp v209, v136 quad_perm:[1,0,3,2] row_mask:0xf bank_mask:0xf
	v_mov_b32_dpp v210, v143 quad_perm:[1,0,3,2] row_mask:0xf bank_mask:0xf
	v_mov_b32_dpp v212, v142 quad_perm:[1,0,3,2] row_mask:0xf bank_mask:0xf
	v_mov_b32_dpp v211, v141 quad_perm:[1,0,3,2] row_mask:0xf bank_mask:0xf
	v_mov_b32_dpp v213, v140 quad_perm:[1,0,3,2] row_mask:0xf bank_mask:0xf
	v_add_u32_e32 v192, 0x800, v164
	v_add_u32_e32 v190, 0x1000, v164
	v_add_u32_e32 v188, 0x1800, v164
	ds_read_b64 v[218:219], v201
	v_cndmask_b32_e64 v221, v193, v133, s[6:7]
	v_cndmask_b32_e64 v220, v189, v132, s[6:7]
	v_cndmask_b32_e64 v223, v209, v135, s[6:7]
	v_cndmask_b32_e64 v222, v191, v134, s[6:7]
	v_cndmask_b32_e64 v225, v212, v129, s[6:7]
	v_cndmask_b32_e64 v224, v210, v128, s[6:7]
	v_cndmask_b32_e64 v227, v213, v131, s[6:7]
	v_cndmask_b32_e64 v226, v211, v130, s[6:7]
	global_load_dwordx4 v[152:155], v164, s[16:17] offset:128
	global_load_dwordx4 v[148:151], v192, s[16:17]
	global_load_dwordx4 v[144:147], v192, s[16:17] offset:128
	global_load_dwordx4 v[140:143], v190, s[16:17]
	global_load_dwordx4 v[136:139], v190, s[16:17] offset:128
	global_load_dwordx4 v[132:135], v188, s[16:17]
	global_load_dwordx4 v[128:131], v188, s[16:17] offset:128
	s_waitcnt lgkmcnt(0)
	v_mul_f32_e32 v208, 0x3fb504f3, v219
	v_lshl_add_u64 v[186:187], v[166:167], 0, s[60:61]
	s_ashr_i32 s59, s58, 31
	v_lshl_add_u64 v[186:187], s[58:59], 3, v[186:187]
	v_lshl_add_u64 v[186:187], v[186:187], 0, s[20:21]
	v_add_u32_e32 v246, 0x4000, v164
	v_add_u32_e32 v247, 0x4800, v164
	global_load_dwordx4 v[230:233], v246, s[16:17]
	global_load_dwordx4 v[234:237], v246, s[16:17] offset:128
	global_load_dwordx4 v[238:241], v247, s[16:17]
	global_load_dwordx4 v[242:245], v247, s[16:17] offset:128
	s_waitcnt vmcnt(0)
	v_pk_mul_f32 v[182:183], v[180:181], s[46:47] op_sel_hi:[1,0]
	v_pk_mul_f32 v[184:185], v[178:179], s[46:47] op_sel_hi:[1,0]
	v_pk_mul_f32 v[178:179], v[196:197], s[46:47] op_sel_hi:[1,0]
	v_pk_mul_f32 v[180:181], v[194:195], s[46:47] op_sel_hi:[1,0]
	v_lshlrev_b32_e32 v194, 16, v214
	v_and_b32_e32 v195, 0xffff0000, v214
	v_lshlrev_b32_e32 v196, 16, v215
	v_and_b32_e32 v197, 0xffff0000, v215
	v_lshlrev_b32_e32 v207, 16, v216
	v_and_b32_e32 v214, 0xffff0000, v216
	v_lshlrev_b32_e32 v216, 16, v217
	v_and_b32_e32 v217, 0xffff0000, v217
	v_sub_f32_e32 v195, v195, v218
	v_sub_f32_e32 v194, v194, v218
	v_sub_f32_e32 v197, v197, v218
	v_sub_f32_e32 v196, v196, v218
	v_sub_f32_e32 v215, v214, v218
	v_sub_f32_e32 v214, v207, v218
	v_sub_f32_e32 v217, v217, v218
	v_sub_f32_e32 v216, v216, v218
	v_pk_mul_f32 v[196:197], v[196:197], v[208:209] op_sel_hi:[1,0]
	v_pk_mul_f32 v[194:195], v[194:195], v[208:209] op_sel_hi:[1,0]
	v_pk_mul_f32 v[216:217], v[216:217], v[208:209] op_sel_hi:[1,0]
	v_pk_mul_f32 v[214:215], v[214:215], v[208:209] op_sel_hi:[1,0]
	v_pk_fma_f32 v[194:195], v[76:77], v[194:195], v[184:185]
	v_pk_fma_f32 v[196:197], v[78:79], v[196:197], v[182:183]
	v_pk_fma_f32 v[214:215], v[72:73], v[214:215], v[180:181]
	v_pk_fma_f32 v[216:217], v[74:75], v[216:217], v[178:179]
	v_pk_add_f32 v[196:197], v[222:223], v[196:197]
	v_pk_add_f32 v[194:195], v[220:221], v[194:195]
	v_pk_add_f32 v[218:219], v[226:227], v[216:217]
	v_pk_add_f32 v[216:217], v[224:225], v[214:215]
	v_cvt_pk_bf16_f32 v214, v194, v195
	v_cvt_pk_bf16_f32 v215, v196, v197
	v_and_b32_e32 v208, 64, v206
	v_cvt_pk_bf16_f32 v216, v216, v217
	v_cvt_pk_bf16_f32 v217, v218, v219
	v_lshlrev_b32_e32 v194, 16, v214
	v_and_b32_e32 v196, 0xffff0000, v214
	v_lshlrev_b32_e32 v218, 16, v215
	v_and_b32_e32 v220, 0xffff0000, v215
	v_lshlrev_b32_e32 v222, 16, v216
	v_and_b32_e32 v224, 0xffff0000, v216
	v_lshlrev_b32_e32 v226, 16, v217
	v_and_b32_e32 v228, 0xffff0000, v217
	v_mul_f32_e32 v195, v194, v194
	v_mul_f32_e32 v197, v196, v196
	v_mul_f32_e32 v219, v218, v218
	v_mul_f32_e32 v221, v220, v220
	v_mul_f32_e32 v223, v222, v222
	v_mul_f32_e32 v225, v224, v224
	v_mul_f32_e32 v227, v226, v226
	v_mul_f32_e32 v229, v228, v228
	v_pk_add_f32 v[194:195], v[194:195], v[196:197]
	v_pk_add_f32 v[196:197], v[218:219], v[220:221]
	v_pk_add_f32 v[218:219], v[226:227], v[228:229]
	v_pk_add_f32 v[194:195], v[194:195], v[196:197]
	v_pk_add_f32 v[196:197], v[222:223], v[224:225]
	v_xor_b32_e32 v207, 16, v206
	v_add_u32_e32 v208, 64, v208
	v_pk_add_f32 v[196:197], v[196:197], v[218:219]
	v_cmp_lt_i32_e32 vcc, v207, v208
	v_pk_add_f32 v[194:195], v[194:195], v[196:197]
	v_mov_b32_e32 v196, 0
	v_mov_b32_e32 v197, 0
	v_cndmask_b32_e32 v207, v206, v207, vcc
	v_mov_b32_dpp v196, v194 quad_perm:[1,0,3,2] row_mask:0xf bank_mask:0xf
	v_mov_b32_dpp v197, v195 quad_perm:[1,0,3,2] row_mask:0xf bank_mask:0xf
	v_lshlrev_b32_e32 v207, 2, v207
	v_pk_add_f32 v[194:195], v[194:195], v[196:197]
	ds_bpermute_b32 v196, v207, v194
	ds_bpermute_b32 v197, v207, v195
	v_xor_b32_e32 v218, 32, v206
	v_cmp_lt_i32_e32 vcc, v218, v208
	global_store_dwordx4 v164, v[214:217], s[16:17]
	s_waitcnt lgkmcnt(0)
	v_pk_add_f32 v[194:195], v[194:195], v[196:197]
	v_cndmask_b32_e32 v208, v206, v218, vcc
	v_lshlrev_b32_e32 v208, 2, v208
	ds_bpermute_b32 v196, v208, v194
	ds_bpermute_b32 v197, v208, v195
	s_and_saveexec_b64 s[56:57], s[12:13]
	s_cbranch_execz .LBB0_1699
	s_waitcnt lgkmcnt(0)
	v_pk_add_f32 v[194:195], v[194:195], v[196:197]
	global_store_dwordx2 v[186:187], v[194:195], off

;     __device__ __forceinline__ void operator()(const f32x4 (&acc)[2][2][4][2], const Unit& u, int wr, int wc, int fr, int fq, const EpiCtx& X) const {
;     ...
;         for (int ai = 0; ai < 2; ++ai) {
;             u32x4 raw[8];
; #pragma unroll
;             for (int m = 0; m < 4; ++m) { const unsigned off = lo + (unsigned)((ai * HALF + m * 16) * 64) * 2u; raw[2 * m] = *(const u32x4*)(xb + off); raw[2 * m + 1] = *(const u32x4*)(xb + off + 128); }
; #pragma unroll
;             for (int m = 0; m < 4; ++m) {
;                 const int rl = ai * HALF + m * 16; const unsigned off = lo + (unsigned)(rl * 64) * 2u;
;                 const f32x4 o0a = acc[ai][0][m][0], o0b = acc[ai][0][m][1], o1a = acc[ai][1][m][0], o1b = acc[ai][1][m][1];
;                 const f32x4 ra_ = dpp_swap1(odd ? o0a : o1a), rb_ = dpp_swap1(odd ? o0b : o1b);
;                 const f32x4 pa[2] = {odd ? ra_ : o0a, odd ? o1a : ra_}, pb[2] = {odd ? rb_ : o0b, odd ? o1b : rb_};
; #pragma unroll
;                 for (int q = 0; q < 2; ++q) {
;                     const u32x4 w0 = raw[2 * m + q];
;                     const f32x4 r0 = (f32x4){bf_lo(w0.x), bf_hi(w0.x), bf_lo(w0.y), bf_hi(w0.y)}, r1 = (f32x4){bf_lo(w0.z), bf_hi(w0.z), bf_lo(w0.w), bf_hi(w0.w)};
;                     f32x4 y0, y1;
;                     if (RESN) { const f32x2 t = tbl[rl + q]; const float mu = t.x, ra = t.y * ALPHA; y0 = (r0 - mu) * ra * g0 + b0 + pa[q]; y1 = (r1 - mu) * ra * g1 + b1 + pb[q]; }
;                     else { y0 = r0 * ALPHA + pa[q]; y1 = r1 * ALPHA + pb[q]; }
;                     { const u32x4 w = pack8f(y0, y1); *(u32x4*)(xb + off + q * 128) = w;
;                         y0 = (f32x4){bf_lo(w.x), bf_hi(w.x), bf_lo(w.y), bf_hi(w.y)}; y1 = (f32x4){bf_lo(w.z), bf_hi(w.z), bf_lo(w.w), bf_hi(w.w)}; }
;                     float sa = ((y0[0] + y0[1]) + (y0[2] + y0[3])) + ((y1[0] + y1[1]) + (y1[2] + y1[3]));
;                     float sb = ((y0[0] * y0[0] + y0[1] * y0[1]) + (y0[2] * y0[2] + y0[3] * y0[3])) + ((y1[0] * y1[0] + y1[1] * y1[1]) + (y1[2] * y1[2] + y1[3] * y1[3]));
;                     sa += dpp_x1(sa);
;                     sb += dpp_x1(sb);
;                     sa += __shfl_xor(sa, 16); sa += __shfl_xor(sa, 32); sb += __shfl_xor(sb, 16); sb += __shfl_xor(sb, 32);
;                     if (fq == 0 && !odd) ps[(size_t)(rl + q) * 64] = (f32x2){sa, sb};
;                 }
.LBB0_1713:
	s_or_b64 exec, exec, s[56:57]
	v_add_u32_e32 v104, 0x4000, v164
	v_mov_b32_e32 v112, v230
	v_mov_b32_e32 v113, v231
	v_mov_b32_e32 v114, v232
	v_mov_b32_e32 v115, v233
	v_add_u32_e32 v102, 0x4800, v164
	v_add_u32_e32 v100, 0x5000, v164
	v_add_u32_e32 v164, 0x5800, v164
	v_mov_b32_e32 v96, v234
	v_mov_b32_e32 v97, v235
	v_mov_b32_e32 v98, v236
	v_mov_b32_e32 v99, v237
	v_mov_b32_e32 v92, v238
	v_mov_b32_e32 v93, v239
	v_mov_b32_e32 v94, v240
	v_mov_b32_e32 v95, v241
	v_mov_b32_e32 v88, v242
	v_mov_b32_e32 v89, v243
	v_mov_b32_e32 v90, v244
	v_mov_b32_e32 v91, v245
	global_load_dwordx4 v[84:87], v100, s[16:17]
	global_load_dwordx4 v[80:83], v100, s[16:17] offset:128
	global_load_dwordx4 v[68:71], v164, s[16:17]
	s_waitcnt lgkmcnt(0)
	global_load_dwordx4 v[64:67], v164, s[16:17] offset:128
	v_cndmask_b32_e64 v116, v62, v54, s[6:7]
	v_cndmask_b32_e64 v117, v61, v53, s[6:7]
	v_mov_b32_e32 v105, 0
	v_mov_b32_e32 v103, 0
	v_cndmask_b32_e64 v111, v63, v55, s[6:7]
	v_mov_b32_dpp v105, v117 quad_perm:[1,0,3,2] row_mask:0xf bank_mask:0xf
	v_mov_b32_dpp v103, v116 quad_perm:[1,0,3,2] row_mask:0xf bank_mask:0xf
	ds_read_b64 v[116:117], v201 offset:1024
	v_cndmask_b32_e64 v118, v60, v52, s[6:7]
	v_mov_b32_e32 v101, 0
	v_mov_b32_e32 v106, 0
	v_cndmask_b32_e64 v119, v59, v51, s[6:7]
	v_cndmask_b32_e64 v120, v58, v50, s[6:7]
	v_cndmask_b32_e64 v121, v57, v49, s[6:7]
	v_cndmask_b32_e64 v122, v56, v48, s[6:7]
	v_mov_b32_e32 v107, 0
	v_mov_b32_e32 v109, 0
	v_mov_b32_e32 v108, 0
	v_mov_b32_e32 v110, 0
	v_mov_b32_dpp v101, v118 quad_perm:[1,0,3,2] row_mask:0xf bank_mask:0xf
	v_mov_b32_dpp v106, v111 quad_perm:[1,0,3,2] row_mask:0xf bank_mask:0xf
	v_mov_b32_dpp v107, v122 quad_perm:[1,0,3,2] row_mask:0xf bank_mask:0xf
	v_mov_b32_dpp v109, v121 quad_perm:[1,0,3,2] row_mask:0xf bank_mask:0xf
	v_mov_b32_dpp v108, v120 quad_perm:[1,0,3,2] row_mask:0xf bank_mask:0xf
	v_mov_b32_dpp v110, v119 quad_perm:[1,0,3,2] row_mask:0xf bank_mask:0xf
	s_waitcnt lgkmcnt(0)
	v_mul_f32_e32 v118, 0x3fb504f3, v117
	v_cndmask_b32_e64 v61, v105, v61, s[6:7]
	v_cndmask_b32_e64 v60, v101, v60, s[6:7]
	v_cndmask_b32_e64 v63, v106, v63, s[6:7]
	v_cndmask_b32_e64 v62, v103, v62, s[6:7]
	v_cndmask_b32_e64 v57, v109, v57, s[6:7]
	v_cndmask_b32_e64 v56, v107, v56, s[6:7]
	v_cndmask_b32_e64 v59, v110, v59, s[6:7]
	v_cndmask_b32_e64 v58, v108, v58, s[6:7]
	v_lshlrev_b32_e32 v111, 16, v112
	v_and_b32_e32 v112, 0xffff0000, v112
	v_lshlrev_b32_e32 v117, 16, v113
	v_and_b32_e32 v119, 0xffff0000, v113
	v_lshlrev_b32_e32 v120, 16, v114
	v_and_b32_e32 v121, 0xffff0000, v114
	v_lshlrev_b32_e32 v122, 16, v115
	v_and_b32_e32 v123, 0xffff0000, v115
	v_sub_f32_e32 v113, v112, v116
	v_sub_f32_e32 v112, v111, v116
	v_sub_f32_e32 v115, v119, v116
	v_sub_f32_e32 v114, v117, v116
	v_sub_f32_e32 v121, v121, v116
	v_sub_f32_e32 v120, v120, v116
	v_sub_f32_e32 v117, v123, v116
	v_sub_f32_e32 v116, v122, v116
	v_pk_mul_f32 v[114:115], v[114:115], v[118:119] op_sel_hi:[1,0]
	v_pk_mul_f32 v[112:113], v[112:113], v[118:119] op_sel_hi:[1,0]
	v_pk_mul_f32 v[116:117], v[116:117], v[118:119] op_sel_hi:[1,0]
	v_pk_mul_f32 v[118:119], v[120:121], v[118:119] op_sel_hi:[1,0]
	v_pk_fma_f32 v[112:113], v[76:77], v[112:113], v[184:185]
	v_pk_fma_f32 v[114:115], v[78:79], v[114:115], v[182:183]
	v_pk_fma_f32 v[118:119], v[72:73], v[118:119], v[180:181]
	v_pk_fma_f32 v[116:117], v[74:75], v[116:117], v[178:179]
	v_pk_add_f32 v[62:63], v[62:63], v[114:115]
	v_pk_add_f32 v[60:61], v[60:61], v[112:113]
	v_pk_add_f32 v[58:59], v[58:59], v[116:117]
	v_pk_add_f32 v[56:57], v[56:57], v[118:119]
	v_cvt_pk_bf16_f32 v60, v60, v61
	v_cvt_pk_bf16_f32 v61, v62, v63
	s_nop 0
	v_cvt_pk_bf16_f32 v62, v56, v57
	v_cvt_pk_bf16_f32 v63, v58, v59
	v_lshlrev_b32_e32 v56, 16, v60
	v_and_b32_e32 v58, 0xffff0000, v60
	v_lshlrev_b32_e32 v112, 16, v61
	v_and_b32_e32 v114, 0xffff0000, v61
	v_lshlrev_b32_e32 v116, 16, v62
	v_and_b32_e32 v118, 0xffff0000, v62
	v_lshlrev_b32_e32 v120, 16, v63
	v_and_b32_e32 v122, 0xffff0000, v63
	v_mul_f32_e32 v57, v56, v56
	v_mul_f32_e32 v59, v58, v58
	v_mul_f32_e32 v113, v112, v112
	v_mul_f32_e32 v115, v114, v114
	v_mul_f32_e32 v117, v116, v116
	v_mul_f32_e32 v119, v118, v118
	v_mul_f32_e32 v121, v120, v120
	v_mul_f32_e32 v123, v122, v122
	v_pk_add_f32 v[56:57], v[56:57], v[58:59]
	v_pk_add_f32 v[58:59], v[112:113], v[114:115]
	v_pk_add_f32 v[112:113], v[120:121], v[122:123]
	v_pk_add_f32 v[56:57], v[56:57], v[58:59]
	v_pk_add_f32 v[58:59], v[116:117], v[118:119]
	global_store_dwordx4 v104, v[60:63], s[16:17]
	v_pk_add_f32 v[58:59], v[58:59], v[112:113]
	s_nop 0
	v_pk_add_f32 v[56:57], v[56:57], v[58:59]
	v_mov_b32_e32 v58, v165
	v_mov_b32_e32 v59, v165
	s_nop 0
	v_mov_b32_dpp v58, v56 quad_perm:[1,0,3,2] row_mask:0xf bank_mask:0xf
	v_mov_b32_dpp v59, v57 quad_perm:[1,0,3,2] row_mask:0xf bank_mask:0xf
	v_pk_add_f32 v[56:57], v[56:57], v[58:59]
	ds_bpermute_b32 v58, v207, v56
	ds_bpermute_b32 v59, v207, v57
	s_waitcnt lgkmcnt(0)
	v_pk_add_f32 v[56:57], v[56:57], v[58:59]
	ds_bpermute_b32 v58, v208, v56
	ds_bpermute_b32 v59, v208, v57
	s_and_saveexec_b64 s[56:57], s[12:13]
	s_cbranch_execz .LBB0_1715
	s_waitcnt lgkmcnt(0)
	v_pk_add_f32 v[56:57], v[56:57], v[58:59]
	v_add_co_u32_e32 v58, vcc, 0x10000, v186
	s_nop 1
	v_addc_co_u32_e32 v59, vcc, 0, v187, vcc
	global_store_dwordx2 v[58:59], v[56:57], off
; __device__ __forceinline__ u32x4 pack8f(f32x4 a, f32x4 b) { u32x4 w; w.x = cvt_pk_bf16(a[0], a[1]); w.y = cvt_pk_bf16(a[2], a[3]); w.z = cvt_pk_bf16(b[0], b[1]); w.w = cvt_pk_bf16(b[2], b[3]); return w; }
;     __device__ __forceinline__ void operator()(const f32x4 (&acc)[2][2][4][2], const Unit& u, int wr, int wc, int fr, int fq, const EpiCtx& X) const {
;     ...
;             for (int m = 0; m < 4; ++m) {
;                 const int rl = ai * HALF + m * 16; const unsigned off = lo + (unsigned)(rl * 64) * 2u;
;                 const f32x4 o0a = acc[ai][0][m][0], o0b = acc[ai][0][m][1], o1a = acc[ai][1][m][0], o1b = acc[ai][1][m][1];
;                 const f32x4 ra_ = dpp_swap1(odd ? o0a : o1a), rb_ = dpp_swap1(odd ? o0b : o1b);
;                 const f32x4 pa[2] = {odd ? ra_ : o0a, odd ? o1a : ra_}, pb[2] = {odd ? rb_ : o0b, odd ? o1b : rb_};
; #pragma unroll
;                 for (int q = 0; q < 2; ++q) {
;                     const u32x4 w0 = raw[2 * m + q];
;                     const f32x4 r0 = (f32x4){bf_lo(w0.x), bf_hi(w0.x), bf_lo(w0.y), bf_hi(w0.y)}, r1 = (f32x4){bf_lo(w0.z), bf_hi(w0.z), bf_lo(w0.w), bf_hi(w0.w)};
;                     f32x4 y0, y1;
;                     if (RESN) { const f32x2 t = tbl[rl + q]; const float mu = t.x, ra = t.y * ALPHA; y0 = (r0 - mu) * ra * g0 + b0 + pa[q]; y1 = (r1 - mu) * ra * g1 + b1 + pb[q]; }
;                     else { y0 = r0 * ALPHA + pa[q]; y1 = r1 * ALPHA + pb[q]; }
;                     { const u32x4 w = pack8f(y0, y1); *(u32x4*)(xb + off + q * 128) = w;
;                         y0 = (f32x4){bf_lo(w.x), bf_hi(w.x), bf_lo(w.y), bf_hi(w.y)}; y1 = (f32x4){bf_lo(w.z), bf_hi(w.z), bf_lo(w.w), bf_hi(w.w)}; }
;                     float sa = ((y0[0] + y0[1]) + (y0[2] + y0[3])) + ((y1[0] + y1[1]) + (y1[2] + y1[3]));
;                     float sb = ((y0[0] * y0[0] + y0[1] * y0[1]) + (y0[2] * y0[2] + y0[3] * y0[3])) + ((y1[0] * y1[0] + y1[1] * y1[1]) + (y1[2] * y1[2] + y1[3] * y1[3]));
;                     sa += dpp_x1(sa);
;                     sb += dpp_x1(sb);
;                     sa += __shfl_xor(sa, 16); sa += __shfl_xor(sa, 32); sb += __shfl_xor(sb, 16); sb += __shfl_xor(sb, 32);
;                     if (fq == 0 && !odd) ps[(size_t)(rl + q) * 64] = (f32x2){sa, sb};
;                 }
.LBB0_1715:
	s_or_b64 exec, exec, s[56:57]
	ds_read_b64 v[56:57], v201 offset:1032
	s_waitcnt lgkmcnt(1)
	v_lshlrev_b32_e32 v59, 16, v96
	v_and_b32_e32 v60, 0xffff0000, v96
	v_cndmask_b32_e64 v53, v53, v105, s[6:7]
	v_cndmask_b32_e64 v52, v52, v101, s[6:7]
	s_waitcnt lgkmcnt(0)
	v_mul_f32_e32 v58, 0x3fb504f3, v57
	v_sub_f32_e32 v61, v60, v56
	v_sub_f32_e32 v60, v59, v56
	v_pk_mul_f32 v[60:61], v[60:61], v[58:59] op_sel_hi:[1,0]
	v_lshlrev_b32_e32 v62, 16, v97
	v_and_b32_e32 v63, 0xffff0000, v97
	v_lshlrev_b32_e32 v96, 16, v98
	v_and_b32_e32 v97, 0xffff0000, v98
	v_lshlrev_b32_e32 v98, 16, v99
	v_and_b32_e32 v99, 0xffff0000, v99
	v_pk_fma_f32 v[60:61], v[76:77], v[60:61], v[184:185]
	v_sub_f32_e32 v63, v63, v56
	v_sub_f32_e32 v62, v62, v56
	v_pk_add_f32 v[52:53], v[52:53], v[60:61]
	v_sub_f32_e32 v61, v97, v56
	v_sub_f32_e32 v60, v96, v56
	v_sub_f32_e32 v57, v99, v56
	v_sub_f32_e32 v56, v98, v56
	v_pk_mul_f32 v[62:63], v[62:63], v[58:59] op_sel_hi:[1,0]
	v_pk_mul_f32 v[56:57], v[56:57], v[58:59] op_sel_hi:[1,0]
	v_pk_mul_f32 v[58:59], v[60:61], v[58:59] op_sel_hi:[1,0]
	v_cndmask_b32_e64 v55, v55, v106, s[6:7]
	v_cndmask_b32_e64 v54, v54, v103, s[6:7]
	v_cndmask_b32_e64 v49, v49, v109, s[6:7]
	v_cndmask_b32_e64 v48, v48, v107, s[6:7]
	v_cndmask_b32_e64 v51, v51, v110, s[6:7]
	v_cndmask_b32_e64 v50, v50, v108, s[6:7]
	v_pk_fma_f32 v[62:63], v[78:79], v[62:63], v[182:183]
	v_pk_fma_f32 v[58:59], v[72:73], v[58:59], v[180:181]
	v_pk_fma_f32 v[56:57], v[74:75], v[56:57], v[178:179]
	v_pk_add_f32 v[54:55], v[54:55], v[62:63]
	v_pk_add_f32 v[50:51], v[50:51], v[56:57]
	v_pk_add_f32 v[48:49], v[48:49], v[58:59]
	v_cvt_pk_bf16_f32 v52, v52, v53
	v_cvt_pk_bf16_f32 v53, v54, v55
	v_mov_b32_e32 v105, v165
	v_cvt_pk_bf16_f32 v54, v48, v49
	v_cvt_pk_bf16_f32 v55, v50, v51
	v_lshlrev_b32_e32 v48, 16, v52
	v_and_b32_e32 v50, 0xffff0000, v52
	v_lshlrev_b32_e32 v56, 16, v53
	v_and_b32_e32 v58, 0xffff0000, v53
	v_lshlrev_b32_e32 v60, 16, v54
	v_and_b32_e32 v62, 0xffff0000, v54
	v_lshlrev_b32_e32 v96, 16, v55
	v_and_b32_e32 v98, 0xffff0000, v55
	v_mul_f32_e32 v49, v48, v48
	v_mul_f32_e32 v51, v50, v50
	v_mul_f32_e32 v57, v56, v56
	v_mul_f32_e32 v59, v58, v58
	v_mul_f32_e32 v61, v60, v60
	v_mul_f32_e32 v63, v62, v62
	v_mul_f32_e32 v97, v96, v96
	v_mul_f32_e32 v99, v98, v98
	v_pk_add_f32 v[48:49], v[48:49], v[50:51]
	v_pk_add_f32 v[50:51], v[56:57], v[58:59]
	v_pk_add_f32 v[56:57], v[96:97], v[98:99]
	v_pk_add_f32 v[48:49], v[48:49], v[50:51]
	v_pk_add_f32 v[50:51], v[60:61], v[62:63]
	s_nop 0
	v_pk_add_f32 v[50:51], v[50:51], v[56:57]
	v_lshl_add_u64 v[56:57], s[16:17], 0, v[104:105]
	v_pk_add_f32 v[48:49], v[48:49], v[50:51]
	v_mov_b32_e32 v50, v165
	v_mov_b32_e32 v51, v165
	global_store_dwordx4 v[56:57], v[52:55], off offset:128
	v_mov_b32_dpp v50, v48 quad_perm:[1,0,3,2] row_mask:0xf bank_mask:0xf
	v_mov_b32_dpp v51, v49 quad_perm:[1,0,3,2] row_mask:0xf bank_mask:0xf
	v_pk_add_f32 v[48:49], v[48:49], v[50:51]
	ds_bpermute_b32 v50, v207, v48
	ds_bpermute_b32 v51, v207, v49
	s_waitcnt lgkmcnt(0)
	v_pk_add_f32 v[48:49], v[48:49], v[50:51]
	ds_bpermute_b32 v50, v208, v48
	ds_bpermute_b32 v51, v208, v49
	s_and_saveexec_b64 s[56:57], s[12:13]
	s_cbranch_execz .LBB0_1717
	s_waitcnt lgkmcnt(0)
	v_pk_add_f32 v[48:49], v[48:49], v[50:51]
	v_add_co_u32_e32 v50, vcc, 0x10000, v186
	s_nop 1
	v_addc_co_u32_e32 v51, vcc, 0, v187, vcc
	global_store_dwordx2 v[50:51], v[48:49], off offset:512
.LBB0_1717:
	s_or_b64 exec, exec, s[56:57]
	s_waitcnt lgkmcnt(1)
	v_cndmask_b32_e64 v50, v44, v36, s[6:7]
	v_mov_b32_e32 v48, 0
	v_cndmask_b32_e64 v49, v45, v37, s[6:7]
	s_waitcnt lgkmcnt(0)
	v_cndmask_b32_e64 v51, v46, v38, s[6:7]
	v_mov_b32_dpp v48, v50 quad_perm:[1,0,3,2] row_mask:0xf bank_mask:0xf
	v_mov_b32_e32 v50, 0
	v_cndmask_b32_e64 v52, v47, v39, s[6:7]
	v_cndmask_b32_e64 v54, v40, v32, s[6:7]
	v_mov_b32_dpp v50, v49 quad_perm:[1,0,3,2] row_mask:0xf bank_mask:0xf
	v_mov_b32_e32 v49, 0
	v_cndmask_b32_e64 v53, v41, v33, s[6:7]
	v_cndmask_b32_e64 v55, v42, v34, s[6:7]
	v_mov_b32_dpp v49, v51 quad_perm:[1,0,3,2] row_mask:0xf bank_mask:0xf
	v_mov_b32_e32 v51, 0
	v_cndmask_b32_e64 v56, v43, v35, s[6:7]
	v_lshlrev_b32_e32 v59, 16, v92
	v_mov_b32_dpp v51, v52 quad_perm:[1,0,3,2] row_mask:0xf bank_mask:0xf
	v_mov_b32_e32 v52, 0
	v_and_b32_e32 v60, 0xffff0000, v92
	v_cndmask_b32_e64 v45, v50, v45, s[6:7]
	v_mov_b32_dpp v52, v54 quad_perm:[1,0,3,2] row_mask:0xf bank_mask:0xf
	v_mov_b32_e32 v54, 0
	v_cndmask_b32_e64 v44, v48, v44, s[6:7]
	v_lshlrev_b32_e32 v62, 16, v93
	v_mov_b32_dpp v54, v53 quad_perm:[1,0,3,2] row_mask:0xf bank_mask:0xf
	v_mov_b32_e32 v53, 0
	v_and_b32_e32 v63, 0xffff0000, v93
	v_lshlrev_b32_e32 v92, 16, v94
	v_mov_b32_dpp v53, v55 quad_perm:[1,0,3,2] row_mask:0xf bank_mask:0xf
	v_mov_b32_e32 v55, 0
	v_and_b32_e32 v93, 0xffff0000, v94
	v_lshlrev_b32_e32 v94, 16, v95
	v_mov_b32_dpp v55, v56 quad_perm:[1,0,3,2] row_mask:0xf bank_mask:0xf
	ds_read_b64 v[56:57], v201 offset:1152
	v_and_b32_e32 v95, 0xffff0000, v95
	v_cndmask_b32_e64 v47, v51, v47, s[6:7]
	v_cndmask_b32_e64 v46, v49, v46, s[6:7]
	v_cndmask_b32_e64 v41, v54, v41, s[6:7]
	s_waitcnt lgkmcnt(0)
; __device__ __forceinline__ u32x4 pack8f(f32x4 a, f32x4 b) { u32x4 w; w.x = cvt_pk_bf16(a[0], a[1]); w.y = cvt_pk_bf16(a[2], a[3]); w.z = cvt_pk_bf16(b[0], b[1]); w.w = cvt_pk_bf16(b[2], b[3]); return w; }
;     __device__ __forceinline__ void operator()(const f32x4 (&acc)[2][2][4][2], const Unit& u, int wr, int wc, int fr, int fq, const EpiCtx& X) const {
;     ...
;             for (int m = 0; m < 4; ++m) {
;                 const int rl = ai * HALF + m * 16; const unsigned off = lo + (unsigned)(rl * 64) * 2u;
;                 const f32x4 o0a = acc[ai][0][m][0], o0b = acc[ai][0][m][1], o1a = acc[ai][1][m][0], o1b = acc[ai][1][m][1];
;                 const f32x4 ra_ = dpp_swap1(odd ? o0a : o1a), rb_ = dpp_swap1(odd ? o0b : o1b);
;                 const f32x4 pa[2] = {odd ? ra_ : o0a, odd ? o1a : ra_}, pb[2] = {odd ? rb_ : o0b, odd ? o1b : rb_};
; #pragma unroll
;                 for (int q = 0; q < 2; ++q) {
;                     const u32x4 w0 = raw[2 * m + q];
;                     const f32x4 r0 = (f32x4){bf_lo(w0.x), bf_hi(w0.x), bf_lo(w0.y), bf_hi(w0.y)}, r1 = (f32x4){bf_lo(w0.z), bf_hi(w0.z), bf_lo(w0.w), bf_hi(w0.w)};
;                     f32x4 y0, y1;
;                     if (RESN) { const f32x2 t = tbl[rl + q]; const float mu = t.x, ra = t.y * ALPHA; y0 = (r0 - mu) * ra * g0 + b0 + pa[q]; y1 = (r1 - mu) * ra * g1 + b1 + pb[q]; }
;                     else { y0 = r0 * ALPHA + pa[q]; y1 = r1 * ALPHA + pb[q]; }
;                     { const u32x4 w = pack8f(y0, y1); *(u32x4*)(xb + off + q * 128) = w;
;                         y0 = (f32x4){bf_lo(w.x), bf_hi(w.x), bf_lo(w.y), bf_hi(w.y)}; y1 = (f32x4){bf_lo(w.z), bf_hi(w.z), bf_lo(w.w), bf_hi(w.w)}; }
;                     float sa = ((y0[0] + y0[1]) + (y0[2] + y0[3])) + ((y1[0] + y1[1]) + (y1[2] + y1[3]));
;                     float sb = ((y0[0] * y0[0] + y0[1] * y0[1]) + (y0[2] * y0[2] + y0[3] * y0[3])) + ((y1[0] * y1[0] + y1[1] * y1[1]) + (y1[2] * y1[2] + y1[3] * y1[3]));
;                     sa += dpp_x1(sa);
;                     sb += dpp_x1(sb);
;                     sa += __shfl_xor(sa, 16); sa += __shfl_xor(sa, 32); sb += __shfl_xor(sb, 16); sb += __shfl_xor(sb, 32);
;                     if (fq == 0 && !odd) ps[(size_t)(rl + q) * 64] = (f32x2){sa, sb};
;                 }
	v_mul_f32_e32 v58, 0x3fb504f3, v57
	v_sub_f32_e32 v61, v60, v56
	v_sub_f32_e32 v60, v59, v56
	v_pk_mul_f32 v[60:61], v[60:61], v[58:59] op_sel_hi:[1,0]
	v_sub_f32_e32 v63, v63, v56
	v_pk_fma_f32 v[60:61], v[76:77], v[60:61], v[184:185]
	v_sub_f32_e32 v62, v62, v56
	v_pk_add_f32 v[44:45], v[44:45], v[60:61]
	v_sub_f32_e32 v61, v93, v56
	v_sub_f32_e32 v60, v92, v56
	v_sub_f32_e32 v57, v95, v56
	v_sub_f32_e32 v56, v94, v56
	v_pk_mul_f32 v[62:63], v[62:63], v[58:59] op_sel_hi:[1,0]
	v_pk_mul_f32 v[56:57], v[56:57], v[58:59] op_sel_hi:[1,0]
	v_pk_mul_f32 v[58:59], v[60:61], v[58:59] op_sel_hi:[1,0]
	v_cndmask_b32_e64 v40, v52, v40, s[6:7]
	v_cndmask_b32_e64 v43, v55, v43, s[6:7]
	v_cndmask_b32_e64 v42, v53, v42, s[6:7]
	v_pk_fma_f32 v[62:63], v[78:79], v[62:63], v[182:183]
	v_pk_fma_f32 v[58:59], v[72:73], v[58:59], v[180:181]
	v_pk_fma_f32 v[56:57], v[74:75], v[56:57], v[178:179]
	v_pk_add_f32 v[46:47], v[46:47], v[62:63]
	v_pk_add_f32 v[42:43], v[42:43], v[56:57]
	v_pk_add_f32 v[40:41], v[40:41], v[58:59]
	v_cvt_pk_bf16_f32 v56, v44, v45
	v_cvt_pk_bf16_f32 v57, v46, v47
	v_mov_b32_e32 v103, v165
	v_cvt_pk_bf16_f32 v58, v40, v41
	v_cvt_pk_bf16_f32 v59, v42, v43
	v_lshlrev_b32_e32 v40, 16, v56
	v_and_b32_e32 v42, 0xffff0000, v56
	v_lshlrev_b32_e32 v44, 16, v57
	v_and_b32_e32 v46, 0xffff0000, v57
	v_lshlrev_b32_e32 v60, 16, v58
	v_and_b32_e32 v62, 0xffff0000, v58
	v_lshlrev_b32_e32 v92, 16, v59
	v_and_b32_e32 v94, 0xffff0000, v59
	v_mul_f32_e32 v41, v40, v40
	v_mul_f32_e32 v43, v42, v42
	v_mul_f32_e32 v45, v44, v44
	v_mul_f32_e32 v47, v46, v46
	v_mul_f32_e32 v61, v60, v60
	v_mul_f32_e32 v63, v62, v62
	v_mul_f32_e32 v93, v92, v92
	v_mul_f32_e32 v95, v94, v94
	v_pk_add_f32 v[40:41], v[40:41], v[42:43]
	v_pk_add_f32 v[42:43], v[44:45], v[46:47]
	v_pk_add_f32 v[44:45], v[92:93], v[94:95]
	v_pk_add_f32 v[40:41], v[40:41], v[42:43]
	v_pk_add_f32 v[42:43], v[60:61], v[62:63]
	s_nop 0
	v_pk_add_f32 v[42:43], v[42:43], v[44:45]
	s_nop 0
	v_pk_add_f32 v[40:41], v[40:41], v[42:43]
	v_mov_b32_e32 v42, v165
	v_mov_b32_e32 v43, v165
	s_nop 0
	v_mov_b32_dpp v42, v40 quad_perm:[1,0,3,2] row_mask:0xf bank_mask:0xf
	v_mov_b32_dpp v43, v41 quad_perm:[1,0,3,2] row_mask:0xf bank_mask:0xf
	v_pk_add_f32 v[40:41], v[40:41], v[42:43]
	ds_bpermute_b32 v42, v207, v40
	ds_bpermute_b32 v43, v207, v41
	s_waitcnt lgkmcnt(0)
	v_pk_add_f32 v[42:43], v[40:41], v[42:43]
	ds_bpermute_b32 v44, v208, v42
	ds_bpermute_b32 v45, v208, v43
	v_lshl_add_u64 v[40:41], s[16:17], 0, v[102:103]
	global_store_dwordx4 v[40:41], v[56:59], off
	s_and_saveexec_b64 s[56:57], s[12:13]
	s_cbranch_execz .LBB0_1719
	s_waitcnt lgkmcnt(0)
	v_pk_add_f32 v[42:43], v[42:43], v[44:45]
	v_add_co_u32_e32 v44, vcc, 0x12000, v186
	s_nop 1
	v_addc_co_u32_e32 v45, vcc, 0, v187, vcc
	global_store_dwordx2 v[44:45], v[42:43], off
.LBB0_1719:
	s_or_b64 exec, exec, s[56:57]
	ds_read_b64 v[42:43], v201 offset:1160
	s_waitcnt lgkmcnt(1)
	v_lshlrev_b32_e32 v45, 16, v88
	v_and_b32_e32 v46, 0xffff0000, v88
	v_cndmask_b32_e64 v37, v37, v50, s[6:7]
	v_cndmask_b32_e64 v36, v36, v48, s[6:7]
	s_waitcnt lgkmcnt(0)
	v_mul_f32_e32 v44, 0x3fb504f3, v43
	v_sub_f32_e32 v47, v46, v42
	v_sub_f32_e32 v46, v45, v42
	v_pk_mul_f32 v[46:47], v[46:47], v[44:45] op_sel_hi:[1,0]
	v_cndmask_b32_e64 v39, v39, v51, s[6:7]
	v_cndmask_b32_e64 v38, v38, v49, s[6:7]
	v_cndmask_b32_e64 v32, v32, v52, s[6:7]
	v_cndmask_b32_e64 v34, v34, v53, s[6:7]
	v_lshlrev_b32_e32 v48, 16, v89
	v_and_b32_e32 v49, 0xffff0000, v89
	v_lshlrev_b32_e32 v50, 16, v90
	v_and_b32_e32 v51, 0xffff0000, v90
	v_lshlrev_b32_e32 v52, 16, v91
	v_and_b32_e32 v53, 0xffff0000, v91
	v_pk_fma_f32 v[46:47], v[76:77], v[46:47], v[184:185]
	v_sub_f32_e32 v49, v49, v42
	v_sub_f32_e32 v48, v48, v42
	v_pk_add_f32 v[36:37], v[36:37], v[46:47]
	v_sub_f32_e32 v47, v51, v42
	v_sub_f32_e32 v46, v50, v42
	v_sub_f32_e32 v43, v53, v42
	v_sub_f32_e32 v42, v52, v42
	v_pk_mul_f32 v[48:49], v[48:49], v[44:45] op_sel_hi:[1,0]
	v_pk_mul_f32 v[42:43], v[42:43], v[44:45] op_sel_hi:[1,0]
	v_pk_mul_f32 v[44:45], v[46:47], v[44:45] op_sel_hi:[1,0]
	v_cndmask_b32_e64 v33, v33, v54, s[6:7]
	v_cndmask_b32_e64 v35, v35, v55, s[6:7]
	v_pk_fma_f32 v[48:49], v[78:79], v[48:49], v[182:183]
	v_pk_fma_f32 v[44:45], v[72:73], v[44:45], v[180:181]
	v_pk_fma_f32 v[42:43], v[74:75], v[42:43], v[178:179]
	v_pk_add_f32 v[38:39], v[38:39], v[48:49]
	v_pk_add_f32 v[34:35], v[34:35], v[42:43]
	v_pk_add_f32 v[32:33], v[32:33], v[44:45]
	v_cvt_pk_bf16_f32 v36, v36, v37
	v_cvt_pk_bf16_f32 v37, v38, v39
	s_nop 0
	v_cvt_pk_bf16_f32 v38, v32, v33
	v_cvt_pk_bf16_f32 v39, v34, v35
	v_lshlrev_b32_e32 v32, 16, v36
	v_and_b32_e32 v34, 0xffff0000, v36
	v_lshlrev_b32_e32 v42, 16, v37
	v_and_b32_e32 v44, 0xffff0000, v37
	v_lshlrev_b32_e32 v46, 16, v38
	v_and_b32_e32 v48, 0xffff0000, v38
	v_lshlrev_b32_e32 v50, 16, v39
	v_and_b32_e32 v52, 0xffff0000, v39
	v_mul_f32_e32 v33, v32, v32
	v_mul_f32_e32 v35, v34, v34
	v_mul_f32_e32 v43, v42, v42
	v_mul_f32_e32 v45, v44, v44
	v_mul_f32_e32 v47, v46, v46
	v_mul_f32_e32 v49, v48, v48
	v_mul_f32_e32 v51, v50, v50
	v_mul_f32_e32 v53, v52, v52
	v_pk_add_f32 v[32:33], v[32:33], v[34:35]
	v_pk_add_f32 v[34:35], v[42:43], v[44:45]
	v_pk_add_f32 v[42:43], v[50:51], v[52:53]
	v_pk_add_f32 v[32:33], v[32:33], v[34:35]
	v_pk_add_f32 v[34:35], v[46:47], v[48:49]
	global_store_dwordx4 v[40:41], v[36:39], off offset:128
	v_pk_add_f32 v[34:35], v[34:35], v[42:43]
	s_nop 0
	v_pk_add_f32 v[32:33], v[32:33], v[34:35]
	v_mov_b32_e32 v34, v165
	v_mov_b32_e32 v35, v165
	s_nop 0
	v_mov_b32_dpp v34, v32 quad_perm:[1,0,3,2] row_mask:0xf bank_mask:0xf
	v_mov_b32_dpp v35, v33 quad_perm:[1,0,3,2] row_mask:0xf bank_mask:0xf
	v_pk_add_f32 v[32:33], v[32:33], v[34:35]
	ds_bpermute_b32 v34, v207, v32
	ds_bpermute_b32 v35, v207, v33
	s_waitcnt lgkmcnt(0)
	v_pk_add_f32 v[32:33], v[32:33], v[34:35]
	ds_bpermute_b32 v34, v208, v32
	ds_bpermute_b32 v35, v208, v33
	s_and_saveexec_b64 s[56:57], s[12:13]
	s_cbranch_execz .LBB0_1721
	s_waitcnt lgkmcnt(0)
	v_pk_add_f32 v[32:33], v[32:33], v[34:35]
	v_add_co_u32_e32 v34, vcc, 0x12000, v186
	s_nop 1
	v_addc_co_u32_e32 v35, vcc, 0, v187, vcc
	global_store_dwordx2 v[34:35], v[32:33], off offset:512
; __device__ __forceinline__ u32x4 pack8f(f32x4 a, f32x4 b) { u32x4 w; w.x = cvt_pk_bf16(a[0], a[1]); w.y = cvt_pk_bf16(a[2], a[3]); w.z = cvt_pk_bf16(b[0], b[1]); w.w = cvt_pk_bf16(b[2], b[3]); return w; }
;     __device__ __forceinline__ void operator()(const f32x4 (&acc)[2][2][4][2], const Unit& u, int wr, int wc, int fr, int fq, const EpiCtx& X) const {
;     ...
;             for (int m = 0; m < 4; ++m) {
;                 const int rl = ai * HALF + m * 16; const unsigned off = lo + (unsigned)(rl * 64) * 2u;
;                 const f32x4 o0a = acc[ai][0][m][0], o0b = acc[ai][0][m][1], o1a = acc[ai][1][m][0], o1b = acc[ai][1][m][1];
;                 const f32x4 ra_ = dpp_swap1(odd ? o0a : o1a), rb_ = dpp_swap1(odd ? o0b : o1b);
;                 const f32x4 pa[2] = {odd ? ra_ : o0a, odd ? o1a : ra_}, pb[2] = {odd ? rb_ : o0b, odd ? o1b : rb_};
; #pragma unroll
;                 for (int q = 0; q < 2; ++q) {
;                     const u32x4 w0 = raw[2 * m + q];
;                     const f32x4 r0 = (f32x4){bf_lo(w0.x), bf_hi(w0.x), bf_lo(w0.y), bf_hi(w0.y)}, r1 = (f32x4){bf_lo(w0.z), bf_hi(w0.z), bf_lo(w0.w), bf_hi(w0.w)};
;                     f32x4 y0, y1;
;                     if (RESN) { const f32x2 t = tbl[rl + q]; const float mu = t.x, ra = t.y * ALPHA; y0 = (r0 - mu) * ra * g0 + b0 + pa[q]; y1 = (r1 - mu) * ra * g1 + b1 + pb[q]; }
;                     else { y0 = r0 * ALPHA + pa[q]; y1 = r1 * ALPHA + pb[q]; }
;                     { const u32x4 w = pack8f(y0, y1); *(u32x4*)(xb + off + q * 128) = w;
;                         y0 = (f32x4){bf_lo(w.x), bf_hi(w.x), bf_lo(w.y), bf_hi(w.y)}; y1 = (f32x4){bf_lo(w.z), bf_hi(w.z), bf_lo(w.w), bf_hi(w.w)}; }
;                     float sa = ((y0[0] + y0[1]) + (y0[2] + y0[3])) + ((y1[0] + y1[1]) + (y1[2] + y1[3]));
;                     float sb = ((y0[0] * y0[0] + y0[1] * y0[1]) + (y0[2] * y0[2] + y0[3] * y0[3])) + ((y1[0] * y1[0] + y1[1] * y1[1]) + (y1[2] * y1[2] + y1[3] * y1[3]));
;                     sa += dpp_x1(sa);
;                     sb += dpp_x1(sb);
;                     sa += __shfl_xor(sa, 16); sa += __shfl_xor(sa, 32); sb += __shfl_xor(sb, 16); sb += __shfl_xor(sb, 32);
;                     if (fq == 0 && !odd) ps[(size_t)(rl + q) * 64] = (f32x2){sa, sb};
;                 }
.LBB0_1721:
	s_or_b64 exec, exec, s[56:57]
	s_waitcnt lgkmcnt(1)
	v_cndmask_b32_e64 v34, v28, v20, s[6:7]
	v_mov_b32_e32 v32, 0
	v_cndmask_b32_e64 v33, v29, v21, s[6:7]
	s_waitcnt lgkmcnt(0)
	v_cndmask_b32_e64 v35, v30, v22, s[6:7]
	v_mov_b32_dpp v32, v34 quad_perm:[1,0,3,2] row_mask:0xf bank_mask:0xf
	v_mov_b32_e32 v34, 0
	v_cndmask_b32_e64 v36, v31, v23, s[6:7]
	v_cndmask_b32_e64 v38, v24, v16, s[6:7]
	v_mov_b32_dpp v34, v33 quad_perm:[1,0,3,2] row_mask:0xf bank_mask:0xf
	v_mov_b32_e32 v33, 0
	v_cndmask_b32_e64 v37, v25, v17, s[6:7]
	v_cndmask_b32_e64 v39, v26, v18, s[6:7]
	v_mov_b32_dpp v33, v35 quad_perm:[1,0,3,2] row_mask:0xf bank_mask:0xf
	v_mov_b32_e32 v35, 0
	v_cndmask_b32_e64 v40, v27, v19, s[6:7]
	s_waitcnt vmcnt(11)
	v_lshlrev_b32_e32 v43, 16, v84
	v_mov_b32_dpp v35, v36 quad_perm:[1,0,3,2] row_mask:0xf bank_mask:0xf
	v_mov_b32_e32 v36, 0
	v_and_b32_e32 v44, 0xffff0000, v84
	v_cndmask_b32_e64 v29, v34, v29, s[6:7]
	v_mov_b32_dpp v36, v38 quad_perm:[1,0,3,2] row_mask:0xf bank_mask:0xf
	v_mov_b32_e32 v38, 0
	v_cndmask_b32_e64 v28, v32, v28, s[6:7]
	v_lshlrev_b32_e32 v46, 16, v85
	v_mov_b32_dpp v38, v37 quad_perm:[1,0,3,2] row_mask:0xf bank_mask:0xf
	v_mov_b32_e32 v37, 0
	v_and_b32_e32 v47, 0xffff0000, v85
	v_lshlrev_b32_e32 v48, 16, v86
	v_mov_b32_dpp v37, v39 quad_perm:[1,0,3,2] row_mask:0xf bank_mask:0xf
	v_mov_b32_e32 v39, 0
	v_and_b32_e32 v49, 0xffff0000, v86
	v_lshlrev_b32_e32 v50, 16, v87
	v_mov_b32_dpp v39, v40 quad_perm:[1,0,3,2] row_mask:0xf bank_mask:0xf
	ds_read_b64 v[40:41], v201 offset:1280
	v_and_b32_e32 v51, 0xffff0000, v87
	v_cndmask_b32_e64 v31, v35, v31, s[6:7]
	v_cndmask_b32_e64 v30, v33, v30, s[6:7]
	v_cndmask_b32_e64 v25, v38, v25, s[6:7]
	s_waitcnt lgkmcnt(0)
	v_mul_f32_e32 v42, 0x3fb504f3, v41
	v_sub_f32_e32 v45, v44, v40
	v_sub_f32_e32 v44, v43, v40
	v_pk_mul_f32 v[44:45], v[44:45], v[42:43] op_sel_hi:[1,0]
	v_sub_f32_e32 v47, v47, v40
	v_pk_fma_f32 v[44:45], v[76:77], v[44:45], v[184:185]
	v_sub_f32_e32 v46, v46, v40
	v_pk_add_f32 v[28:29], v[28:29], v[44:45]
	v_sub_f32_e32 v45, v49, v40
	v_sub_f32_e32 v44, v48, v40
	v_sub_f32_e32 v41, v51, v40
	v_sub_f32_e32 v40, v50, v40
	v_pk_mul_f32 v[46:47], v[46:47], v[42:43] op_sel_hi:[1,0]
	v_pk_mul_f32 v[40:41], v[40:41], v[42:43] op_sel_hi:[1,0]
	v_pk_mul_f32 v[42:43], v[44:45], v[42:43] op_sel_hi:[1,0]
	v_cndmask_b32_e64 v24, v36, v24, s[6:7]
	v_cndmask_b32_e64 v27, v39, v27, s[6:7]
	v_cndmask_b32_e64 v26, v37, v26, s[6:7]
	v_pk_fma_f32 v[46:47], v[78:79], v[46:47], v[182:183]
	v_pk_fma_f32 v[42:43], v[72:73], v[42:43], v[180:181]
	v_pk_fma_f32 v[40:41], v[74:75], v[40:41], v[178:179]
	v_pk_add_f32 v[30:31], v[30:31], v[46:47]
	v_pk_add_f32 v[26:27], v[26:27], v[40:41]
	v_pk_add_f32 v[24:25], v[24:25], v[42:43]
	v_cvt_pk_bf16_f32 v40, v28, v29
	v_cvt_pk_bf16_f32 v41, v30, v31
	v_mov_b32_e32 v101, v165
	v_cvt_pk_bf16_f32 v42, v24, v25
	v_cvt_pk_bf16_f32 v43, v26, v27
	v_lshlrev_b32_e32 v24, 16, v40
	v_and_b32_e32 v26, 0xffff0000, v40
	v_lshlrev_b32_e32 v28, 16, v41
	v_and_b32_e32 v30, 0xffff0000, v41
	v_lshlrev_b32_e32 v44, 16, v42
	v_and_b32_e32 v46, 0xffff0000, v42
	v_lshlrev_b32_e32 v48, 16, v43
	v_and_b32_e32 v50, 0xffff0000, v43
	v_mul_f32_e32 v25, v24, v24
	v_mul_f32_e32 v27, v26, v26
	v_mul_f32_e32 v29, v28, v28
	v_mul_f32_e32 v31, v30, v30
	v_mul_f32_e32 v45, v44, v44
	v_mul_f32_e32 v47, v46, v46
	v_mul_f32_e32 v49, v48, v48
	v_mul_f32_e32 v51, v50, v50
	v_pk_add_f32 v[24:25], v[24:25], v[26:27]
	v_pk_add_f32 v[26:27], v[28:29], v[30:31]
	v_pk_add_f32 v[28:29], v[48:49], v[50:51]
	v_pk_add_f32 v[24:25], v[24:25], v[26:27]
	v_pk_add_f32 v[26:27], v[44:45], v[46:47]
	s_nop 0
	v_pk_add_f32 v[26:27], v[26:27], v[28:29]
	s_nop 0
	v_pk_add_f32 v[24:25], v[24:25], v[26:27]
	v_mov_b32_e32 v26, v165
	v_mov_b32_e32 v27, v165
	s_nop 0
	v_mov_b32_dpp v26, v24 quad_perm:[1,0,3,2] row_mask:0xf bank_mask:0xf
	v_mov_b32_dpp v27, v25 quad_perm:[1,0,3,2] row_mask:0xf bank_mask:0xf
	v_pk_add_f32 v[24:25], v[24:25], v[26:27]
	ds_bpermute_b32 v26, v207, v24
	ds_bpermute_b32 v27, v207, v25
	s_waitcnt lgkmcnt(0)
	v_pk_add_f32 v[26:27], v[24:25], v[26:27]
	ds_bpermute_b32 v28, v208, v26
	ds_bpermute_b32 v29, v208, v27
	v_lshl_add_u64 v[24:25], s[16:17], 0, v[100:101]
	global_store_dwordx4 v[24:25], v[40:43], off
	s_and_saveexec_b64 s[56:57], s[12:13]
	s_cbranch_execz .LBB0_1723
	s_waitcnt lgkmcnt(0)
	v_pk_add_f32 v[26:27], v[26:27], v[28:29]
	v_add_co_u32_e32 v28, vcc, 0x14000, v186
	s_nop 1
	v_addc_co_u32_e32 v29, vcc, 0, v187, vcc
	global_store_dwordx2 v[28:29], v[26:27], off
; __device__ __forceinline__ u32x4 pack8f(f32x4 a, f32x4 b) { u32x4 w; w.x = cvt_pk_bf16(a[0], a[1]); w.y = cvt_pk_bf16(a[2], a[3]); w.z = cvt_pk_bf16(b[0], b[1]); w.w = cvt_pk_bf16(b[2], b[3]); return w; }
;     __device__ __forceinline__ void operator()(const f32x4 (&acc)[2][2][4][2], const Unit& u, int wr, int wc, int fr, int fq, const EpiCtx& X) const {
;     ...
;             for (int m = 0; m < 4; ++m) {
;                 const int rl = ai * HALF + m * 16; const unsigned off = lo + (unsigned)(rl * 64) * 2u;
;                 const f32x4 o0a = acc[ai][0][m][0], o0b = acc[ai][0][m][1], o1a = acc[ai][1][m][0], o1b = acc[ai][1][m][1];
;                 const f32x4 ra_ = dpp_swap1(odd ? o0a : o1a), rb_ = dpp_swap1(odd ? o0b : o1b);
;                 const f32x4 pa[2] = {odd ? ra_ : o0a, odd ? o1a : ra_}, pb[2] = {odd ? rb_ : o0b, odd ? o1b : rb_};
; #pragma unroll
;                 for (int q = 0; q < 2; ++q) {
;                     const u32x4 w0 = raw[2 * m + q];
;                     const f32x4 r0 = (f32x4){bf_lo(w0.x), bf_hi(w0.x), bf_lo(w0.y), bf_hi(w0.y)}, r1 = (f32x4){bf_lo(w0.z), bf_hi(w0.z), bf_lo(w0.w), bf_hi(w0.w)};
;                     f32x4 y0, y1;
;                     if (RESN) { const f32x2 t = tbl[rl + q]; const float mu = t.x, ra = t.y * ALPHA; y0 = (r0 - mu) * ra * g0 + b0 + pa[q]; y1 = (r1 - mu) * ra * g1 + b1 + pb[q]; }
;                     else { y0 = r0 * ALPHA + pa[q]; y1 = r1 * ALPHA + pb[q]; }
;                     { const u32x4 w = pack8f(y0, y1); *(u32x4*)(xb + off + q * 128) = w;
;                         y0 = (f32x4){bf_lo(w.x), bf_hi(w.x), bf_lo(w.y), bf_hi(w.y)}; y1 = (f32x4){bf_lo(w.z), bf_hi(w.z), bf_lo(w.w), bf_hi(w.w)}; }
;                     float sa = ((y0[0] + y0[1]) + (y0[2] + y0[3])) + ((y1[0] + y1[1]) + (y1[2] + y1[3]));
;                     float sb = ((y0[0] * y0[0] + y0[1] * y0[1]) + (y0[2] * y0[2] + y0[3] * y0[3])) + ((y1[0] * y1[0] + y1[1] * y1[1]) + (y1[2] * y1[2] + y1[3] * y1[3]));
;                     sa += dpp_x1(sa);
;                     sb += dpp_x1(sb);
;                     sa += __shfl_xor(sa, 16); sa += __shfl_xor(sa, 32); sb += __shfl_xor(sb, 16); sb += __shfl_xor(sb, 32);
;                     if (fq == 0 && !odd) ps[(size_t)(rl + q) * 64] = (f32x2){sa, sb};
;                 }
.LBB0_1723:
	s_or_b64 exec, exec, s[56:57]
	ds_read_b64 v[26:27], v201 offset:1288
	s_waitcnt vmcnt(12) lgkmcnt(1)
	v_lshlrev_b32_e32 v29, 16, v80
	v_and_b32_e32 v30, 0xffff0000, v80
	v_cndmask_b32_e64 v21, v21, v34, s[6:7]
	v_cndmask_b32_e64 v20, v20, v32, s[6:7]
	s_waitcnt lgkmcnt(0)
	v_mul_f32_e32 v28, 0x3fb504f3, v27
	v_sub_f32_e32 v31, v30, v26
	v_sub_f32_e32 v30, v29, v26
	v_pk_mul_f32 v[30:31], v[30:31], v[28:29] op_sel_hi:[1,0]
	v_cndmask_b32_e64 v23, v23, v35, s[6:7]
	v_cndmask_b32_e64 v22, v22, v33, s[6:7]
	v_cndmask_b32_e64 v16, v16, v36, s[6:7]
	v_cndmask_b32_e64 v18, v18, v37, s[6:7]
	v_lshlrev_b32_e32 v32, 16, v81
	v_and_b32_e32 v33, 0xffff0000, v81
	v_lshlrev_b32_e32 v34, 16, v82
	v_and_b32_e32 v35, 0xffff0000, v82
	v_lshlrev_b32_e32 v36, 16, v83
	v_and_b32_e32 v37, 0xffff0000, v83
	v_pk_fma_f32 v[30:31], v[76:77], v[30:31], v[184:185]
	v_sub_f32_e32 v33, v33, v26
	v_sub_f32_e32 v32, v32, v26
	v_pk_add_f32 v[20:21], v[20:21], v[30:31]
	v_sub_f32_e32 v31, v35, v26
	v_sub_f32_e32 v30, v34, v26
	v_sub_f32_e32 v27, v37, v26
	v_sub_f32_e32 v26, v36, v26
	v_pk_mul_f32 v[32:33], v[32:33], v[28:29] op_sel_hi:[1,0]
	v_pk_mul_f32 v[26:27], v[26:27], v[28:29] op_sel_hi:[1,0]
	v_pk_mul_f32 v[28:29], v[30:31], v[28:29] op_sel_hi:[1,0]
	v_cndmask_b32_e64 v17, v17, v38, s[6:7]
	v_cndmask_b32_e64 v19, v19, v39, s[6:7]
	v_pk_fma_f32 v[32:33], v[78:79], v[32:33], v[182:183]
	v_pk_fma_f32 v[28:29], v[72:73], v[28:29], v[180:181]
	v_pk_fma_f32 v[26:27], v[74:75], v[26:27], v[178:179]
	v_pk_add_f32 v[22:23], v[22:23], v[32:33]
	v_pk_add_f32 v[18:19], v[18:19], v[26:27]
	v_pk_add_f32 v[16:17], v[16:17], v[28:29]
	v_cvt_pk_bf16_f32 v20, v20, v21
	v_cvt_pk_bf16_f32 v21, v22, v23
	s_nop 0
	v_cvt_pk_bf16_f32 v22, v16, v17
	v_cvt_pk_bf16_f32 v23, v18, v19
	v_lshlrev_b32_e32 v16, 16, v20
	v_and_b32_e32 v18, 0xffff0000, v20
	v_lshlrev_b32_e32 v26, 16, v21
	v_and_b32_e32 v28, 0xffff0000, v21
	v_lshlrev_b32_e32 v30, 16, v22
	v_and_b32_e32 v32, 0xffff0000, v22
	v_lshlrev_b32_e32 v34, 16, v23
	v_and_b32_e32 v36, 0xffff0000, v23
	v_mul_f32_e32 v17, v16, v16
	v_mul_f32_e32 v19, v18, v18
	v_mul_f32_e32 v27, v26, v26
	v_mul_f32_e32 v29, v28, v28
	v_mul_f32_e32 v31, v30, v30
	v_mul_f32_e32 v33, v32, v32
	v_mul_f32_e32 v35, v34, v34
	v_mul_f32_e32 v37, v36, v36
	v_pk_add_f32 v[16:17], v[16:17], v[18:19]
	v_pk_add_f32 v[18:19], v[26:27], v[28:29]
	v_pk_add_f32 v[26:27], v[34:35], v[36:37]
	v_pk_add_f32 v[16:17], v[16:17], v[18:19]
	v_pk_add_f32 v[18:19], v[30:31], v[32:33]
	global_store_dwordx4 v[24:25], v[20:23], off offset:128
	v_pk_add_f32 v[18:19], v[18:19], v[26:27]
	s_nop 0
	v_pk_add_f32 v[16:17], v[16:17], v[18:19]
	v_mov_b32_e32 v18, v165
	v_mov_b32_e32 v19, v165
	s_nop 0
	v_mov_b32_dpp v18, v16 quad_perm:[1,0,3,2] row_mask:0xf bank_mask:0xf
	v_mov_b32_dpp v19, v17 quad_perm:[1,0,3,2] row_mask:0xf bank_mask:0xf
	v_pk_add_f32 v[16:17], v[16:17], v[18:19]
	ds_bpermute_b32 v18, v207, v16
	ds_bpermute_b32 v19, v207, v17
	s_waitcnt lgkmcnt(0)
	v_pk_add_f32 v[16:17], v[16:17], v[18:19]
	ds_bpermute_b32 v18, v208, v16
	ds_bpermute_b32 v19, v208, v17
	s_and_saveexec_b64 s[56:57], s[12:13]
	s_cbranch_execz .LBB0_1725
	s_waitcnt lgkmcnt(0)
	v_pk_add_f32 v[16:17], v[16:17], v[18:19]
	v_add_co_u32_e32 v18, vcc, 0x14000, v186
	s_nop 1
	v_addc_co_u32_e32 v19, vcc, 0, v187, vcc
	global_store_dwordx2 v[18:19], v[16:17], off offset:512
.LBB0_1725:
	s_or_b64 exec, exec, s[56:57]
	s_waitcnt lgkmcnt(1)
	v_cndmask_b32_e64 v18, v12, v4, s[6:7]
	v_mov_b32_e32 v16, 0
	v_cndmask_b32_e64 v17, v13, v5, s[6:7]
	s_waitcnt lgkmcnt(0)
	v_cndmask_b32_e64 v19, v14, v6, s[6:7]
	v_mov_b32_dpp v16, v18 quad_perm:[1,0,3,2] row_mask:0xf bank_mask:0xf
	v_mov_b32_e32 v18, 0
	v_cndmask_b32_e64 v20, v15, v7, s[6:7]
	v_cndmask_b32_e64 v22, v8, v0, s[6:7]
	v_mov_b32_dpp v18, v17 quad_perm:[1,0,3,2] row_mask:0xf bank_mask:0xf
	v_mov_b32_e32 v17, 0
	v_cndmask_b32_e64 v21, v9, v1, s[6:7]
	v_cndmask_b32_e64 v23, v10, v2, s[6:7]
	v_mov_b32_dpp v17, v19 quad_perm:[1,0,3,2] row_mask:0xf bank_mask:0xf
	v_mov_b32_e32 v19, 0
	v_cndmask_b32_e64 v24, v11, v3, s[6:7]
	s_waitcnt vmcnt(13)
	v_lshlrev_b32_e32 v27, 16, v68
	v_mov_b32_dpp v19, v20 quad_perm:[1,0,3,2] row_mask:0xf bank_mask:0xf
	v_mov_b32_e32 v20, 0
	v_and_b32_e32 v28, 0xffff0000, v68
	v_cndmask_b32_e64 v13, v18, v13, s[6:7]
	v_mov_b32_dpp v20, v22 quad_perm:[1,0,3,2] row_mask:0xf bank_mask:0xf
	v_mov_b32_e32 v22, 0
	v_cndmask_b32_e64 v12, v16, v12, s[6:7]
	v_lshlrev_b32_e32 v30, 16, v69
	v_mov_b32_dpp v22, v21 quad_perm:[1,0,3,2] row_mask:0xf bank_mask:0xf
	v_mov_b32_e32 v21, 0
	v_and_b32_e32 v31, 0xffff0000, v69
	v_lshlrev_b32_e32 v32, 16, v70
	v_mov_b32_dpp v21, v23 quad_perm:[1,0,3,2] row_mask:0xf bank_mask:0xf
	v_mov_b32_e32 v23, 0
	v_and_b32_e32 v33, 0xffff0000, v70
	v_lshlrev_b32_e32 v34, 16, v71
	v_mov_b32_dpp v23, v24 quad_perm:[1,0,3,2] row_mask:0xf bank_mask:0xf
	ds_read_b64 v[24:25], v201 offset:1408
	v_and_b32_e32 v35, 0xffff0000, v71
	v_cndmask_b32_e64 v15, v19, v15, s[6:7]
	v_cndmask_b32_e64 v14, v17, v14, s[6:7]
	v_cndmask_b32_e64 v9, v22, v9, s[6:7]
	s_waitcnt lgkmcnt(0)
; __device__ __forceinline__ u32x4 pack8f(f32x4 a, f32x4 b) { u32x4 w; w.x = cvt_pk_bf16(a[0], a[1]); w.y = cvt_pk_bf16(a[2], a[3]); w.z = cvt_pk_bf16(b[0], b[1]); w.w = cvt_pk_bf16(b[2], b[3]); return w; }
;     __device__ __forceinline__ void operator()(const f32x4 (&acc)[2][2][4][2], const Unit& u, int wr, int wc, int fr, int fq, const EpiCtx& X) const {
;     ...
;             for (int m = 0; m < 4; ++m) {
;                 const int rl = ai * HALF + m * 16; const unsigned off = lo + (unsigned)(rl * 64) * 2u;
;                 const f32x4 o0a = acc[ai][0][m][0], o0b = acc[ai][0][m][1], o1a = acc[ai][1][m][0], o1b = acc[ai][1][m][1];
;                 const f32x4 ra_ = dpp_swap1(odd ? o0a : o1a), rb_ = dpp_swap1(odd ? o0b : o1b);
;                 const f32x4 pa[2] = {odd ? ra_ : o0a, odd ? o1a : ra_}, pb[2] = {odd ? rb_ : o0b, odd ? o1b : rb_};
; #pragma unroll
;                 for (int q = 0; q < 2; ++q) {
;                     const u32x4 w0 = raw[2 * m + q];
;                     const f32x4 r0 = (f32x4){bf_lo(w0.x), bf_hi(w0.x), bf_lo(w0.y), bf_hi(w0.y)}, r1 = (f32x4){bf_lo(w0.z), bf_hi(w0.z), bf_lo(w0.w), bf_hi(w0.w)};
;                     f32x4 y0, y1;
;                     if (RESN) { const f32x2 t = tbl[rl + q]; const float mu = t.x, ra = t.y * ALPHA; y0 = (r0 - mu) * ra * g0 + b0 + pa[q]; y1 = (r1 - mu) * ra * g1 + b1 + pb[q]; }
;                     else { y0 = r0 * ALPHA + pa[q]; y1 = r1 * ALPHA + pb[q]; }
;                     { const u32x4 w = pack8f(y0, y1); *(u32x4*)(xb + off + q * 128) = w;
;                         y0 = (f32x4){bf_lo(w.x), bf_hi(w.x), bf_lo(w.y), bf_hi(w.y)}; y1 = (f32x4){bf_lo(w.z), bf_hi(w.z), bf_lo(w.w), bf_hi(w.w)}; }
;                     float sa = ((y0[0] + y0[1]) + (y0[2] + y0[3])) + ((y1[0] + y1[1]) + (y1[2] + y1[3]));
;                     float sb = ((y0[0] * y0[0] + y0[1] * y0[1]) + (y0[2] * y0[2] + y0[3] * y0[3])) + ((y1[0] * y1[0] + y1[1] * y1[1]) + (y1[2] * y1[2] + y1[3] * y1[3]));
;                     sa += dpp_x1(sa);
;                     sb += dpp_x1(sb);
;                     sa += __shfl_xor(sa, 16); sa += __shfl_xor(sa, 32); sb += __shfl_xor(sb, 16); sb += __shfl_xor(sb, 32);
;                     if (fq == 0 && !odd) ps[(size_t)(rl + q) * 64] = (f32x2){sa, sb};
;                 }
	v_mul_f32_e32 v26, 0x3fb504f3, v25
	v_sub_f32_e32 v29, v28, v24
	v_sub_f32_e32 v28, v27, v24
	v_pk_mul_f32 v[28:29], v[28:29], v[26:27] op_sel_hi:[1,0]
	v_sub_f32_e32 v31, v31, v24
	v_pk_fma_f32 v[28:29], v[76:77], v[28:29], v[184:185]
	v_sub_f32_e32 v30, v30, v24
	v_pk_add_f32 v[12:13], v[12:13], v[28:29]
	v_sub_f32_e32 v29, v33, v24
	v_sub_f32_e32 v28, v32, v24
	v_sub_f32_e32 v25, v35, v24
	v_sub_f32_e32 v24, v34, v24
	v_pk_mul_f32 v[30:31], v[30:31], v[26:27] op_sel_hi:[1,0]
	v_pk_mul_f32 v[24:25], v[24:25], v[26:27] op_sel_hi:[1,0]
	v_pk_mul_f32 v[26:27], v[28:29], v[26:27] op_sel_hi:[1,0]
	v_cndmask_b32_e64 v8, v20, v8, s[6:7]
	v_cndmask_b32_e64 v11, v23, v11, s[6:7]
	v_cndmask_b32_e64 v10, v21, v10, s[6:7]
	v_pk_fma_f32 v[30:31], v[78:79], v[30:31], v[182:183]
	v_pk_fma_f32 v[26:27], v[72:73], v[26:27], v[180:181]
	v_pk_fma_f32 v[24:25], v[74:75], v[24:25], v[178:179]
	v_pk_add_f32 v[14:15], v[14:15], v[30:31]
	v_pk_add_f32 v[10:11], v[10:11], v[24:25]
	v_pk_add_f32 v[8:9], v[8:9], v[26:27]
	v_cvt_pk_bf16_f32 v24, v12, v13
	v_cvt_pk_bf16_f32 v25, v14, v15
	s_nop 0
	v_cvt_pk_bf16_f32 v26, v8, v9
	v_cvt_pk_bf16_f32 v27, v10, v11
	v_lshlrev_b32_e32 v8, 16, v24
	v_and_b32_e32 v10, 0xffff0000, v24
	v_lshlrev_b32_e32 v12, 16, v25
	v_and_b32_e32 v14, 0xffff0000, v25
	v_lshlrev_b32_e32 v28, 16, v26
	v_and_b32_e32 v30, 0xffff0000, v26
	v_lshlrev_b32_e32 v32, 16, v27
	v_and_b32_e32 v34, 0xffff0000, v27
	v_mul_f32_e32 v9, v8, v8
	v_mul_f32_e32 v11, v10, v10
	v_mul_f32_e32 v13, v12, v12
	v_mul_f32_e32 v15, v14, v14
	v_mul_f32_e32 v29, v28, v28
	v_mul_f32_e32 v31, v30, v30
	v_mul_f32_e32 v33, v32, v32
	v_mul_f32_e32 v35, v34, v34
	v_pk_add_f32 v[8:9], v[8:9], v[10:11]
	v_pk_add_f32 v[10:11], v[12:13], v[14:15]
	v_pk_add_f32 v[12:13], v[32:33], v[34:35]
	v_pk_add_f32 v[8:9], v[8:9], v[10:11]
	v_pk_add_f32 v[10:11], v[28:29], v[30:31]
	s_nop 0
	v_pk_add_f32 v[10:11], v[10:11], v[12:13]
	s_nop 0
	v_pk_add_f32 v[8:9], v[8:9], v[10:11]
	v_mov_b32_e32 v10, v165
	v_mov_b32_e32 v11, v165
	s_nop 0
	v_mov_b32_dpp v10, v8 quad_perm:[1,0,3,2] row_mask:0xf bank_mask:0xf
	v_mov_b32_dpp v11, v9 quad_perm:[1,0,3,2] row_mask:0xf bank_mask:0xf
	v_pk_add_f32 v[8:9], v[8:9], v[10:11]
	ds_bpermute_b32 v10, v207, v8
	ds_bpermute_b32 v11, v207, v9
	s_waitcnt lgkmcnt(0)
	v_pk_add_f32 v[10:11], v[8:9], v[10:11]
	ds_bpermute_b32 v12, v208, v10
	ds_bpermute_b32 v13, v208, v11
	v_lshl_add_u64 v[8:9], s[16:17], 0, v[164:165]
	global_store_dwordx4 v[8:9], v[24:27], off
	s_and_saveexec_b64 s[16:17], s[12:13]
	s_cbranch_execz .LBB0_1727
	s_waitcnt lgkmcnt(0)
	v_pk_add_f32 v[10:11], v[10:11], v[12:13]
	v_add_co_u32_e32 v12, vcc, 0x16000, v186
	s_nop 1
	v_addc_co_u32_e32 v13, vcc, 0, v187, vcc
	global_store_dwordx2 v[12:13], v[10:11], off
.LBB0_1727:
	s_or_b64 exec, exec, s[16:17]
	ds_read_b64 v[10:11], v201 offset:1416
	s_waitcnt vmcnt(14) lgkmcnt(1)
	v_lshlrev_b32_e32 v13, 16, v64
	v_and_b32_e32 v14, 0xffff0000, v64
	v_cndmask_b32_e64 v5, v5, v18, s[6:7]
	v_cndmask_b32_e64 v4, v4, v16, s[6:7]
	s_waitcnt lgkmcnt(0)
	v_mul_f32_e32 v12, 0x3fb504f3, v11
	v_sub_f32_e32 v15, v14, v10
	v_sub_f32_e32 v14, v13, v10
	v_pk_mul_f32 v[14:15], v[14:15], v[12:13] op_sel_hi:[1,0]
	v_cndmask_b32_e64 v7, v7, v19, s[6:7]
	v_cndmask_b32_e64 v6, v6, v17, s[6:7]
	v_cndmask_b32_e64 v0, v0, v20, s[6:7]
	v_cndmask_b32_e64 v2, v2, v21, s[6:7]
	v_lshlrev_b32_e32 v16, 16, v65
	v_and_b32_e32 v17, 0xffff0000, v65
	v_lshlrev_b32_e32 v18, 16, v66
	v_and_b32_e32 v19, 0xffff0000, v66
	v_lshlrev_b32_e32 v20, 16, v67
	v_and_b32_e32 v21, 0xffff0000, v67
	v_pk_fma_f32 v[14:15], v[76:77], v[14:15], v[184:185]
	v_sub_f32_e32 v17, v17, v10
	v_sub_f32_e32 v16, v16, v10
	v_pk_add_f32 v[4:5], v[4:5], v[14:15]
	v_sub_f32_e32 v15, v19, v10
	v_sub_f32_e32 v14, v18, v10
	v_sub_f32_e32 v11, v21, v10
	v_sub_f32_e32 v10, v20, v10
	v_pk_mul_f32 v[16:17], v[16:17], v[12:13] op_sel_hi:[1,0]
	v_pk_mul_f32 v[10:11], v[10:11], v[12:13] op_sel_hi:[1,0]
	v_pk_mul_f32 v[12:13], v[14:15], v[12:13] op_sel_hi:[1,0]
	v_cndmask_b32_e64 v1, v1, v22, s[6:7]
	v_cndmask_b32_e64 v3, v3, v23, s[6:7]
	v_pk_fma_f32 v[16:17], v[78:79], v[16:17], v[182:183]
	v_pk_fma_f32 v[12:13], v[72:73], v[12:13], v[180:181]
	v_pk_fma_f32 v[10:11], v[74:75], v[10:11], v[178:179]
	v_pk_add_f32 v[6:7], v[6:7], v[16:17]
	v_pk_add_f32 v[2:3], v[2:3], v[10:11]
	v_pk_add_f32 v[0:1], v[0:1], v[12:13]
	v_cvt_pk_bf16_f32 v4, v4, v5
	v_cvt_pk_bf16_f32 v5, v6, v7
	s_nop 0
	v_cvt_pk_bf16_f32 v6, v0, v1
	v_cvt_pk_bf16_f32 v7, v2, v3
	v_lshlrev_b32_e32 v0, 16, v4
	v_and_b32_e32 v2, 0xffff0000, v4
	v_lshlrev_b32_e32 v10, 16, v5
	v_and_b32_e32 v12, 0xffff0000, v5
	v_lshlrev_b32_e32 v14, 16, v6
	v_and_b32_e32 v16, 0xffff0000, v6
	v_lshlrev_b32_e32 v18, 16, v7
	v_and_b32_e32 v20, 0xffff0000, v7
	v_mul_f32_e32 v1, v0, v0
	v_mul_f32_e32 v3, v2, v2
	v_mul_f32_e32 v11, v10, v10
	v_mul_f32_e32 v13, v12, v12
	v_mul_f32_e32 v15, v14, v14
	v_mul_f32_e32 v17, v16, v16
	v_mul_f32_e32 v19, v18, v18
	v_mul_f32_e32 v21, v20, v20
	v_pk_add_f32 v[0:1], v[0:1], v[2:3]
	v_pk_add_f32 v[2:3], v[10:11], v[12:13]
	v_pk_add_f32 v[10:11], v[18:19], v[20:21]
	v_pk_add_f32 v[0:1], v[0:1], v[2:3]
	v_pk_add_f32 v[2:3], v[14:15], v[16:17]
	global_store_dwordx4 v[8:9], v[4:7], off offset:128
	v_pk_add_f32 v[2:3], v[2:3], v[10:11]
	s_nop 0
	v_pk_add_f32 v[0:1], v[0:1], v[2:3]
	v_mov_b32_e32 v2, v165
	v_mov_b32_e32 v3, v165
	s_nop 0
	v_mov_b32_dpp v2, v0 quad_perm:[1,0,3,2] row_mask:0xf bank_mask:0xf
	v_mov_b32_dpp v3, v1 quad_perm:[1,0,3,2] row_mask:0xf bank_mask:0xf
	v_pk_add_f32 v[0:1], v[0:1], v[2:3]
	ds_bpermute_b32 v2, v207, v0
	ds_bpermute_b32 v3, v207, v1
	s_waitcnt lgkmcnt(0)
	v_pk_add_f32 v[0:1], v[0:1], v[2:3]
	ds_bpermute_b32 v2, v208, v0
	ds_bpermute_b32 v3, v208, v1
	s_and_saveexec_b64 s[16:17], s[12:13]
	s_cbranch_execz .LBB0_1729
	s_waitcnt lgkmcnt(0)
	v_pk_add_f32 v[0:1], v[0:1], v[2:3]
	v_add_co_u32_e32 v2, vcc, 0x16000, v186
	s_nop 1
	v_addc_co_u32_e32 v3, vcc, 0, v187, vcc
	global_store_dwordx2 v[2:3], v[0:1], off offset:512
